# v47 + GEMM k-loops: scalar-base LDS-DMA form where the offset is provably 32-bit (40 VALU adds removed), load segments issue ds_reads before the DMA group (SL1(1) all loops, SL1(0) three loops)
# baseline (speedup 1.0000x reference)
.LBB0_269:
	ds_read_b128 v[146:149], v152
	ds_read_b128 v[156:159], v152 offset:1024
	ds_read_b128 v[160:163], v152 offset:2048
	ds_read_b128 v[164:167], v152 offset:3072
	s_add_u32 s24, s22, 0xfff80080
	s_addc_u32 s25, s23, -1
	s_cmp_eq_u32 s61, 28
	s_cselect_b32 s27, s9, s25
	s_cselect_b32 s26, s53, s24
	s_cselect_b32 s25, s7, s60
	s_cselect_b32 s24, s58, s59
	s_add_i32 m0, s21, 0xc000
	ds_read_b128 v[168:171], v153
	ds_read_b128 v[172:175], v153 offset:1024
	ds_read_b128 v[176:179], v153 offset:2048
	ds_read_b128 v[180:183], v153 offset:3072
	ds_read_b128 v[186:189], v153 offset:4096
	ds_read_b128 v[190:193], v153 offset:5120
	ds_read_b128 v[194:197], v153 offset:6144
	ds_read_b128 v[198:201], v153 offset:7168
	ds_read_b128 v[202:205], v154
	ds_read_b128 v[206:209], v154 offset:1024
	ds_read_b128 v[210:213], v154 offset:2048
	ds_read_b128 v[214:217], v154 offset:3072
	global_load_lds_dwordx4 v138, s[22:23]
	s_add_i32 m0, s21, 0xe000
	s_nop 0
	global_load_lds_dwordx4 v140, s[22:23]
	s_waitcnt vmcnt(8)
	s_waitcnt lgkmcnt(0)
	s_barrier
	s_setprio 1
	v_mfma_f32_16x16x32_bf16 v[126:129], v[146:149], v[168:171], v[126:129]
	v_mfma_f32_16x16x32_bf16 v[122:125], v[160:163], v[168:171], v[122:125]
	v_mfma_f32_16x16x32_bf16 v[118:121], v[146:149], v[176:179], v[118:121]
	v_mfma_f32_16x16x32_bf16 v[110:113], v[160:163], v[176:179], v[110:113]
	v_mfma_f32_16x16x32_bf16 v[102:105], v[146:149], v[186:189], v[102:105]
	v_mfma_f32_16x16x32_bf16 v[94:97], v[160:163], v[186:189], v[94:97]
	v_mfma_f32_16x16x32_bf16 v[86:89], v[146:149], v[194:197], v[86:89]
	v_mfma_f32_16x16x32_bf16 v[78:81], v[160:163], v[194:197], v[78:81]
	v_mfma_f32_16x16x32_bf16 v[126:129], v[156:159], v[172:175], v[126:129]
	v_mfma_f32_16x16x32_bf16 v[122:125], v[164:167], v[172:175], v[122:125]
	v_mfma_f32_16x16x32_bf16 v[118:121], v[156:159], v[180:183], v[118:121]
	v_mfma_f32_16x16x32_bf16 v[110:113], v[164:167], v[180:183], v[110:113]
	v_mfma_f32_16x16x32_bf16 v[102:105], v[156:159], v[190:193], v[102:105]
	v_mfma_f32_16x16x32_bf16 v[94:97], v[164:167], v[190:193], v[94:97]
	v_mfma_f32_16x16x32_bf16 v[86:89], v[156:159], v[198:201], v[86:89]
	v_mfma_f32_16x16x32_bf16 v[78:81], v[164:167], v[198:201], v[78:81]
	v_mfma_f32_16x16x32_bf16 v[114:117], v[202:205], v[168:171], v[114:117]
	v_mfma_f32_16x16x32_bf16 v[106:109], v[210:213], v[168:171], v[106:109]
	v_mfma_f32_16x16x32_bf16 v[98:101], v[202:205], v[176:179], v[98:101]
	v_mfma_f32_16x16x32_bf16 v[90:93], v[210:213], v[176:179], v[90:93]
	v_mfma_f32_16x16x32_bf16 v[82:85], v[202:205], v[186:189], v[82:85]
	v_mfma_f32_16x16x32_bf16 v[74:77], v[210:213], v[186:189], v[74:77]
	v_mfma_f32_16x16x32_bf16 v[70:73], v[202:205], v[194:197], v[70:73]
	v_mfma_f32_16x16x32_bf16 v[66:69], v[210:213], v[194:197], v[66:69]
	v_mfma_f32_16x16x32_bf16 v[114:117], v[206:209], v[172:175], v[114:117]
	v_mfma_f32_16x16x32_bf16 v[106:109], v[214:217], v[172:175], v[106:109]
	v_mfma_f32_16x16x32_bf16 v[98:101], v[206:209], v[180:183], v[98:101]
	v_mfma_f32_16x16x32_bf16 v[90:93], v[214:217], v[180:183], v[90:93]
	v_mfma_f32_16x16x32_bf16 v[82:85], v[206:209], v[190:193], v[82:85]
	v_mfma_f32_16x16x32_bf16 v[74:77], v[214:217], v[190:193], v[74:77]
	v_mfma_f32_16x16x32_bf16 v[70:73], v[206:209], v[198:201], v[70:73]
	v_mfma_f32_16x16x32_bf16 v[66:69], v[214:217], v[198:201], v[66:69]
	s_setprio 0
	s_barrier
	s_add_i32 s68, s45, s29
	v_lshl_add_u64 v[218:219], s[24:25], 0, v[134:135]
	s_mov_b32 m0, s68
	global_load_lds_dwordx4 v134, s[24:25]
	v_lshl_add_u64 v[220:221], s[24:25], 0, v[130:131]
	s_add_i32 m0, s68, 0x2000
	s_nop 0
	global_load_lds_dwordx4 v130, s[24:25]
	s_mov_b32 m0, s21
	v_lshl_add_u64 v[222:223], s[26:27], 0, v[136:137]
	ds_read_b128 v[168:171], v153 offset:16384
	ds_read_b128 v[172:175], v153 offset:17408
	ds_read_b128 v[176:179], v153 offset:18432
	ds_read_b128 v[180:183], v153 offset:19456
	ds_read_b128 v[186:189], v153 offset:20480
	ds_read_b128 v[190:193], v153 offset:21504
	ds_read_b128 v[194:197], v153 offset:22528
	ds_read_b128 v[198:201], v153 offset:23552
	global_load_lds_dwordx4 v136, s[26:27]
	v_lshl_add_u64 v[224:225], s[26:27], 0, v[132:133]
	s_mov_b32 m0, s34
	s_nop 0
	global_load_lds_dwordx4 v132, s[26:27]
	s_waitcnt vmcnt(6)
	s_waitcnt lgkmcnt(0)
	s_barrier
	s_setprio 1
	v_mfma_f32_16x16x32_bf16 v[62:65], v[146:149], v[168:171], v[62:65]
	v_mfma_f32_16x16x32_bf16 v[58:61], v[160:163], v[168:171], v[58:61]
	v_mfma_f32_16x16x32_bf16 v[54:57], v[146:149], v[176:179], v[54:57]
	v_mfma_f32_16x16x32_bf16 v[46:49], v[160:163], v[176:179], v[46:49]
	v_mfma_f32_16x16x32_bf16 v[38:41], v[146:149], v[186:189], v[38:41]
	v_mfma_f32_16x16x32_bf16 v[30:33], v[160:163], v[186:189], v[30:33]
	v_mfma_f32_16x16x32_bf16 v[22:25], v[146:149], v[194:197], v[22:25]
	v_mfma_f32_16x16x32_bf16 v[14:17], v[160:163], v[194:197], v[14:17]
	v_mfma_f32_16x16x32_bf16 v[62:65], v[156:159], v[172:175], v[62:65]
	v_mfma_f32_16x16x32_bf16 v[58:61], v[164:167], v[172:175], v[58:61]
	v_mfma_f32_16x16x32_bf16 v[54:57], v[156:159], v[180:183], v[54:57]
	v_mfma_f32_16x16x32_bf16 v[46:49], v[164:167], v[180:183], v[46:49]
	v_mfma_f32_16x16x32_bf16 v[38:41], v[156:159], v[190:193], v[38:41]
	v_mfma_f32_16x16x32_bf16 v[30:33], v[164:167], v[190:193], v[30:33]
	v_mfma_f32_16x16x32_bf16 v[22:25], v[156:159], v[198:201], v[22:25]
	v_mfma_f32_16x16x32_bf16 v[14:17], v[164:167], v[198:201], v[14:17]
	v_mfma_f32_16x16x32_bf16 v[50:53], v[202:205], v[168:171], v[50:53]
	v_mfma_f32_16x16x32_bf16 v[42:45], v[210:213], v[168:171], v[42:45]
	v_mfma_f32_16x16x32_bf16 v[34:37], v[202:205], v[176:179], v[34:37]
	v_mfma_f32_16x16x32_bf16 v[26:29], v[210:213], v[176:179], v[26:29]
	v_mfma_f32_16x16x32_bf16 v[18:21], v[202:205], v[186:189], v[18:21]
	v_mfma_f32_16x16x32_bf16 v[10:13], v[210:213], v[186:189], v[10:13]
	v_mfma_f32_16x16x32_bf16 v[6:9], v[202:205], v[194:197], v[6:9]
	v_mfma_f32_16x16x32_bf16 v[2:5], v[210:213], v[194:197], v[2:5]
	v_mfma_f32_16x16x32_bf16 v[50:53], v[206:209], v[172:175], v[50:53]
	v_mfma_f32_16x16x32_bf16 v[42:45], v[214:217], v[172:175], v[42:45]
	v_mfma_f32_16x16x32_bf16 v[34:37], v[206:209], v[180:183], v[34:37]
	v_mfma_f32_16x16x32_bf16 v[26:29], v[214:217], v[180:183], v[26:29]
	v_mfma_f32_16x16x32_bf16 v[18:21], v[206:209], v[190:193], v[18:21]
	v_mfma_f32_16x16x32_bf16 v[10:13], v[214:217], v[190:193], v[10:13]
	v_mfma_f32_16x16x32_bf16 v[6:9], v[206:209], v[198:201], v[6:9]
	v_mfma_f32_16x16x32_bf16 v[2:5], v[214:217], v[198:201], v[2:5]
	s_setprio 0
	s_barrier
	s_add_u32 s68, s24, 0x80000
	s_addc_u32 s69, s25, 0
	s_add_i32 s70, s46, s29
	s_mov_b32 m0, s70
	s_nop 0
	global_load_lds_dwordx4 v134, s[68:69]
	s_add_i32 m0, s70, 0x2000
	s_nop 0
	global_load_lds_dwordx4 v130, s[68:69]
	s_add_i32 s68, 0, 0x18000
	v_add_u32_e32 v155, s68, v150
	ds_read_b128 v[146:149], v155
	ds_read_b128 v[156:159], v155 offset:1024
	ds_read_b128 v[160:163], v155 offset:2048
	ds_read_b128 v[164:167], v155 offset:3072
	s_add_u32 s26, s26, 0x80000
	s_addc_u32 s27, s27, 0
	s_mov_b32 m0, s35
	ds_read_b128 v[168:171], v153 offset:32768
	ds_read_b128 v[172:175], v153 offset:33792
	ds_read_b128 v[176:179], v153 offset:34816
	ds_read_b128 v[180:183], v153 offset:35840
	ds_read_b128 v[186:189], v153 offset:36864
	ds_read_b128 v[190:193], v153 offset:37888
	ds_read_b128 v[194:197], v153 offset:38912
	ds_read_b128 v[198:201], v153 offset:39936
	v_add_u32_e32 v214, 0x1c000, v150
	ds_read_b128 v[202:205], v214
	ds_read_b128 v[206:209], v214 offset:1024
	ds_read_b128 v[210:213], v214 offset:2048
	ds_read_b128 v[214:217], v214 offset:3072
	global_load_lds_dwordx4 v136, s[26:27]
	s_mov_b32 m0, s36
	s_nop 0
	global_load_lds_dwordx4 v132, s[26:27]
	s_waitcnt vmcnt(8)
	s_waitcnt lgkmcnt(0)
	s_barrier
	s_setprio 1
	v_mfma_f32_16x16x32_bf16 v[126:129], v[146:149], v[168:171], v[126:129]
	v_mfma_f32_16x16x32_bf16 v[122:125], v[160:163], v[168:171], v[122:125]
	v_mfma_f32_16x16x32_bf16 v[118:121], v[146:149], v[176:179], v[118:121]
	v_mfma_f32_16x16x32_bf16 v[110:113], v[160:163], v[176:179], v[110:113]
	v_mfma_f32_16x16x32_bf16 v[102:105], v[146:149], v[186:189], v[102:105]
	v_mfma_f32_16x16x32_bf16 v[94:97], v[160:163], v[186:189], v[94:97]
	v_mfma_f32_16x16x32_bf16 v[86:89], v[146:149], v[194:197], v[86:89]
	v_mfma_f32_16x16x32_bf16 v[78:81], v[160:163], v[194:197], v[78:81]
	v_mfma_f32_16x16x32_bf16 v[126:129], v[156:159], v[172:175], v[126:129]
	v_mfma_f32_16x16x32_bf16 v[122:125], v[164:167], v[172:175], v[122:125]
	v_mfma_f32_16x16x32_bf16 v[118:121], v[156:159], v[180:183], v[118:121]
	v_mfma_f32_16x16x32_bf16 v[110:113], v[164:167], v[180:183], v[110:113]
	v_mfma_f32_16x16x32_bf16 v[102:105], v[156:159], v[190:193], v[102:105]
	v_mfma_f32_16x16x32_bf16 v[94:97], v[164:167], v[190:193], v[94:97]
	v_mfma_f32_16x16x32_bf16 v[86:89], v[156:159], v[198:201], v[86:89]
	v_mfma_f32_16x16x32_bf16 v[78:81], v[164:167], v[198:201], v[78:81]
	v_mfma_f32_16x16x32_bf16 v[114:117], v[202:205], v[168:171], v[114:117]
	v_mfma_f32_16x16x32_bf16 v[106:109], v[210:213], v[168:171], v[106:109]
	v_mfma_f32_16x16x32_bf16 v[98:101], v[202:205], v[176:179], v[98:101]
	v_mfma_f32_16x16x32_bf16 v[90:93], v[210:213], v[176:179], v[90:93]
	v_mfma_f32_16x16x32_bf16 v[82:85], v[202:205], v[186:189], v[82:85]
	v_mfma_f32_16x16x32_bf16 v[74:77], v[210:213], v[186:189], v[74:77]
	v_mfma_f32_16x16x32_bf16 v[70:73], v[202:205], v[194:197], v[70:73]
	v_mfma_f32_16x16x32_bf16 v[66:69], v[210:213], v[194:197], v[66:69]
	v_mfma_f32_16x16x32_bf16 v[114:117], v[206:209], v[172:175], v[114:117]
	v_mfma_f32_16x16x32_bf16 v[106:109], v[214:217], v[172:175], v[106:109]
	v_mfma_f32_16x16x32_bf16 v[98:101], v[206:209], v[180:183], v[98:101]
	v_mfma_f32_16x16x32_bf16 v[90:93], v[214:217], v[180:183], v[90:93]
	v_mfma_f32_16x16x32_bf16 v[82:85], v[206:209], v[190:193], v[82:85]
	v_mfma_f32_16x16x32_bf16 v[74:77], v[214:217], v[190:193], v[74:77]
	v_mfma_f32_16x16x32_bf16 v[70:73], v[206:209], v[198:201], v[70:73]
	v_mfma_f32_16x16x32_bf16 v[66:69], v[214:217], v[198:201], v[66:69]
	s_setprio 0
	s_barrier
	s_add_i32 s26, 0, 0x1c000
	s_add_i32 s27, s68, s29
	v_lshl_add_u64 v[218:219], v[218:219], 0, s[4:5]
	s_mov_b32 m0, s27
	global_load_lds_dwordx4 v[218:219], off
	v_lshl_add_u64 v[218:219], v[220:221], 0, s[4:5]
	s_add_i32 m0, s27, 0x2000
	s_nop 0
	global_load_lds_dwordx4 v[218:219], off
	s_mov_b32 m0, s41
	v_lshl_add_u64 v[218:219], v[222:223], 0, s[4:5]
	ds_read_b128 v[168:171], v153 offset:49152
	ds_read_b128 v[172:175], v153 offset:50176
	ds_read_b128 v[176:179], v153 offset:51200
	ds_read_b128 v[180:183], v153 offset:52224
	ds_read_b128 v[186:189], v153 offset:53248
	ds_read_b128 v[190:193], v153 offset:54272
	ds_read_b128 v[194:197], v153 offset:55296
	ds_read_b128 v[198:201], v153 offset:56320
	global_load_lds_dwordx4 v[218:219], off
	v_lshl_add_u64 v[218:219], v[224:225], 0, s[4:5]
	s_mov_b32 m0, s42
	s_nop 0
	global_load_lds_dwordx4 v[218:219], off
	s_add_u32 s24, s24, 0x80080
	s_addc_u32 s25, s25, 0
	s_add_i32 s26, s26, s29
	s_mov_b32 m0, s26
	s_nop 0
	global_load_lds_dwordx4 v134, s[24:25]
	s_add_i32 m0, s26, 0x2000
	s_nop 0
	global_load_lds_dwordx4 v130, s[24:25]
	s_waitcnt vmcnt(8)
	s_waitcnt lgkmcnt(0)
	s_barrier
	s_setprio 1
	v_mfma_f32_16x16x32_bf16 v[62:65], v[146:149], v[168:171], v[62:65]
	v_mfma_f32_16x16x32_bf16 v[58:61], v[160:163], v[168:171], v[58:61]
	v_mfma_f32_16x16x32_bf16 v[54:57], v[146:149], v[176:179], v[54:57]
	v_mfma_f32_16x16x32_bf16 v[46:49], v[160:163], v[176:179], v[46:49]
	v_mfma_f32_16x16x32_bf16 v[38:41], v[146:149], v[186:189], v[38:41]
	v_mfma_f32_16x16x32_bf16 v[30:33], v[160:163], v[186:189], v[30:33]
	v_mfma_f32_16x16x32_bf16 v[22:25], v[146:149], v[194:197], v[22:25]
	v_mfma_f32_16x16x32_bf16 v[14:17], v[160:163], v[194:197], v[14:17]
	v_mfma_f32_16x16x32_bf16 v[62:65], v[156:159], v[172:175], v[62:65]
	v_mfma_f32_16x16x32_bf16 v[58:61], v[164:167], v[172:175], v[58:61]
	v_mfma_f32_16x16x32_bf16 v[54:57], v[156:159], v[180:183], v[54:57]
	v_mfma_f32_16x16x32_bf16 v[46:49], v[164:167], v[180:183], v[46:49]
	v_mfma_f32_16x16x32_bf16 v[38:41], v[156:159], v[190:193], v[38:41]
	v_mfma_f32_16x16x32_bf16 v[30:33], v[164:167], v[190:193], v[30:33]
	v_mfma_f32_16x16x32_bf16 v[22:25], v[156:159], v[198:201], v[22:25]
	v_mfma_f32_16x16x32_bf16 v[14:17], v[164:167], v[198:201], v[14:17]
	v_mfma_f32_16x16x32_bf16 v[50:53], v[202:205], v[168:171], v[50:53]
	v_mfma_f32_16x16x32_bf16 v[42:45], v[210:213], v[168:171], v[42:45]
	v_mfma_f32_16x16x32_bf16 v[34:37], v[202:205], v[176:179], v[34:37]
	v_mfma_f32_16x16x32_bf16 v[26:29], v[210:213], v[176:179], v[26:29]
	v_mfma_f32_16x16x32_bf16 v[18:21], v[202:205], v[186:189], v[18:21]
	v_mfma_f32_16x16x32_bf16 v[10:13], v[210:213], v[186:189], v[10:13]
	v_mfma_f32_16x16x32_bf16 v[6:9], v[202:205], v[194:197], v[6:9]
	v_mfma_f32_16x16x32_bf16 v[2:5], v[210:213], v[194:197], v[2:5]
	v_mfma_f32_16x16x32_bf16 v[50:53], v[206:209], v[172:175], v[50:53]
	v_mfma_f32_16x16x32_bf16 v[42:45], v[214:217], v[172:175], v[42:45]
	v_mfma_f32_16x16x32_bf16 v[34:37], v[206:209], v[180:183], v[34:37]
	v_mfma_f32_16x16x32_bf16 v[26:29], v[214:217], v[180:183], v[26:29]
	v_mfma_f32_16x16x32_bf16 v[18:21], v[206:209], v[190:193], v[18:21]
	v_mfma_f32_16x16x32_bf16 v[10:13], v[214:217], v[190:193], v[10:13]
	v_mfma_f32_16x16x32_bf16 v[6:9], v[206:209], v[198:201], v[6:9]
	v_mfma_f32_16x16x32_bf16 v[2:5], v[214:217], v[198:201], v[2:5]
	s_setprio 0
	s_add_i32 s61, s61, 2
	s_add_u32 s22, s22, 0x100
	s_addc_u32 s23, s23, 0
	s_add_u32 s59, s59, 0x100
	s_addc_u32 s60, s60, 0
	s_cmp_gt_u32 s61, 29
	s_barrier
	s_cbranch_scc0 .LBB0_269
	v_lshl_or_b32 v148, s52, 8, v151
	v_lshl_add_u32 v155, s20, 8, v1
	v_ashrrev_i32_e32 v149, 31, v148
	v_mov_b64_e32 v[146:147], s[54:55]
	v_mad_i64_i32 v[156:157], s[22:23], v155, s47, v[146:147]
	v_lshlrev_b64 v[148:149], 1, v[148:149]
	v_lshl_add_u64 v[156:157], v[156:157], 0, v[148:149]
	v_cvt_pk_bf16_f32 v126, v126, v127
	v_cvt_pk_bf16_f32 v127, v128, v129
	v_cvt_pk_bf16_f32 v128, v122, v123
	v_cvt_pk_bf16_f32 v129, v124, v125
	global_store_dwordx4 v[156:157], v[126:129], off
	v_cvt_pk_bf16_f32 v114, v114, v115
	v_cvt_pk_bf16_f32 v115, v116, v117
	v_cvt_pk_bf16_f32 v116, v106, v107
	v_or_b32_e32 v106, 16, v155
	v_mad_i64_i32 v[106:107], s[22:23], v106, s47, v[146:147]
	v_cvt_pk_bf16_f32 v117, v108, v109
	global_store_dwordx4 v[156:157], v[114:117], off offset:256
	s_and_b64 vcc, exec, s[2:3]
	s_mov_b32 s52, s6
	v_lshl_add_u64 v[114:115], v[106:107], 0, v[148:149]
	v_cvt_pk_bf16_f32 v106, v118, v119
	v_cvt_pk_bf16_f32 v107, v120, v121
	v_cvt_pk_bf16_f32 v108, v110, v111
	v_cvt_pk_bf16_f32 v109, v112, v113
	global_store_dwordx4 v[114:115], v[106:109], off
	v_cvt_pk_bf16_f32 v98, v98, v99
	v_cvt_pk_bf16_f32 v99, v100, v101
	v_cvt_pk_bf16_f32 v100, v90, v91
	v_or_b32_e32 v90, 32, v155
	v_mad_i64_i32 v[90:91], s[22:23], v90, s47, v[146:147]
	v_cvt_pk_bf16_f32 v101, v92, v93
	global_store_dwordx4 v[114:115], v[98:101], off offset:256
	s_mov_b32 s20, s8
	s_mov_b64 s[24:25], s[18:19]
	v_lshl_add_u64 v[98:99], v[90:91], 0, v[148:149]
	v_cvt_pk_bf16_f32 v90, v102, v103
	v_cvt_pk_bf16_f32 v91, v104, v105
	v_cvt_pk_bf16_f32 v92, v94, v95
	v_cvt_pk_bf16_f32 v93, v96, v97
	global_store_dwordx4 v[98:99], v[90:93], off
	v_cvt_pk_bf16_f32 v82, v82, v83
	v_cvt_pk_bf16_f32 v83, v84, v85
	v_cvt_pk_bf16_f32 v84, v74, v75
	v_or_b32_e32 v74, 48, v155
	v_mad_i64_i32 v[74:75], s[22:23], v74, s47, v[146:147]
	v_cvt_pk_bf16_f32 v85, v76, v77
	global_store_dwordx4 v[98:99], v[82:85], off offset:256
	s_nop 1
	v_lshl_add_u64 v[82:83], v[74:75], 0, v[148:149]
	v_cvt_pk_bf16_f32 v74, v86, v87
	v_cvt_pk_bf16_f32 v75, v88, v89
	v_cvt_pk_bf16_f32 v76, v78, v79
	v_cvt_pk_bf16_f32 v77, v80, v81
	global_store_dwordx4 v[82:83], v[74:77], off
	v_cvt_pk_bf16_f32 v70, v70, v71
	v_cvt_pk_bf16_f32 v71, v72, v73
	v_cvt_pk_bf16_f32 v72, v66, v67
	v_add_u32_e32 v66, 0x80, v155
	v_mad_i64_i32 v[66:67], s[22:23], v66, s47, v[146:147]
	v_lshl_add_u64 v[66:67], v[66:67], 0, v[148:149]
	v_cvt_pk_bf16_f32 v73, v68, v69
	global_store_dwordx4 v[82:83], v[70:73], off offset:256
	v_cvt_pk_bf16_f32 v62, v62, v63
	v_cvt_pk_bf16_f32 v63, v64, v65
	v_cvt_pk_bf16_f32 v64, v58, v59
	v_cvt_pk_bf16_f32 v65, v60, v61
	global_store_dwordx4 v[66:67], v[62:65], off
	v_cvt_pk_bf16_f32 v50, v50, v51
	v_cvt_pk_bf16_f32 v51, v52, v53
	v_cvt_pk_bf16_f32 v52, v42, v43
	v_add_u32_e32 v42, 0x90, v155
	v_mad_i64_i32 v[42:43], s[22:23], v42, s47, v[146:147]
	v_cvt_pk_bf16_f32 v53, v44, v45
	global_store_dwordx4 v[66:67], v[50:53], off offset:256
	s_nop 1
	v_lshl_add_u64 v[50:51], v[42:43], 0, v[148:149]
	v_cvt_pk_bf16_f32 v42, v54, v55
	v_cvt_pk_bf16_f32 v43, v56, v57
	v_cvt_pk_bf16_f32 v44, v46, v47
	v_cvt_pk_bf16_f32 v45, v48, v49
	global_store_dwordx4 v[50:51], v[42:45], off
	v_cvt_pk_bf16_f32 v34, v34, v35
	v_cvt_pk_bf16_f32 v35, v36, v37
	v_cvt_pk_bf16_f32 v36, v26, v27
	v_add_u32_e32 v26, 0xa0, v155
	v_mad_i64_i32 v[26:27], s[22:23], v26, s47, v[146:147]
	v_cvt_pk_bf16_f32 v37, v28, v29
	global_store_dwordx4 v[50:51], v[34:37], off offset:256
	s_nop 1
	v_lshl_add_u64 v[34:35], v[26:27], 0, v[148:149]
	v_cvt_pk_bf16_f32 v26, v38, v39
	v_cvt_pk_bf16_f32 v27, v40, v41
	v_cvt_pk_bf16_f32 v28, v30, v31
	v_cvt_pk_bf16_f32 v29, v32, v33
	global_store_dwordx4 v[34:35], v[26:29], off
	v_cvt_pk_bf16_f32 v18, v18, v19
	v_cvt_pk_bf16_f32 v19, v20, v21
	v_cvt_pk_bf16_f32 v20, v10, v11
	v_add_u32_e32 v10, 0xb0, v155
	v_mad_i64_i32 v[10:11], s[22:23], v10, s47, v[146:147]
	v_cvt_pk_bf16_f32 v21, v12, v13
	global_store_dwordx4 v[34:35], v[18:21], off offset:256
	s_mov_b64 s[22:23], s[16:17]
	s_nop 0
	v_lshl_add_u64 v[18:19], v[10:11], 0, v[148:149]
	v_cvt_pk_bf16_f32 v10, v22, v23
	v_cvt_pk_bf16_f32 v11, v24, v25
	v_cvt_pk_bf16_f32 v12, v14, v15
	v_cvt_pk_bf16_f32 v13, v16, v17
	global_store_dwordx4 v[18:19], v[10:13], off
	v_cvt_pk_bf16_f32 v6, v6, v7
	v_cvt_pk_bf16_f32 v7, v8, v9
	v_cvt_pk_bf16_f32 v8, v2, v3
	v_cvt_pk_bf16_f32 v9, v4, v5
	global_store_dwordx4 v[18:19], v[6:9], off offset:256
	s_cbranch_vccz .LBB0_266
	s_waitcnt vmcnt(0)
	s_cmpk_gt_u32 s28, 0xff
	s_cbranch_scc1 .LBB0_273
	s_barrier

.LBB0_457:
	ds_read_b128 v[154:157], v150
	ds_read_b128 v[158:161], v150 offset:1024
	ds_read_b128 v[162:165], v150 offset:2048
	ds_read_b128 v[166:169], v150 offset:3072
	s_add_u32 s4, s28, 0x100
	s_addc_u32 s5, s29, 0
	s_cmp_eq_u32 s81, 4
	s_cselect_b32 s35, s25, s5
	s_cselect_b32 s34, s24, s4
	s_cselect_b32 s31, s23, s80
	s_cselect_b32 s30, s78, s79
	v_lshl_add_u64 v[146:147], s[28:29], 0, v[138:139]
	s_add_i32 m0, s46, 0xc000
	ds_read_b128 v[170:173], v151
	ds_read_b128 v[174:177], v151 offset:1024
	ds_read_b128 v[178:181], v151 offset:2048
	ds_read_b128 v[186:189], v151 offset:3072
	ds_read_b128 v[190:193], v151 offset:4096
	ds_read_b128 v[194:197], v151 offset:5120
	ds_read_b128 v[198:201], v151 offset:6144
	ds_read_b128 v[202:205], v151 offset:7168
	global_load_lds_dwordx4 v[146:147], off
	v_lshl_add_u64 v[146:147], s[28:29], 0, v[140:141]
	s_add_i32 m0, s46, 0xe000
	s_nop 0
	global_load_lds_dwordx4 v[146:147], off
	ds_read_b128 v[206:209], v152
	ds_read_b128 v[210:213], v152 offset:1024
	ds_read_b128 v[214:217], v152 offset:2048
	ds_read_b128 v[218:221], v152 offset:3072
	s_waitcnt vmcnt(8)
	s_waitcnt lgkmcnt(0)
	s_barrier
	s_setprio 1
	v_mfma_f32_16x16x32_bf16 v[126:129], v[154:157], v[170:173], v[126:129]
	v_mfma_f32_16x16x32_bf16 v[122:125], v[162:165], v[170:173], v[122:125]
	v_mfma_f32_16x16x32_bf16 v[114:117], v[154:157], v[178:181], v[114:117]
	v_mfma_f32_16x16x32_bf16 v[106:109], v[162:165], v[178:181], v[106:109]
	v_mfma_f32_16x16x32_bf16 v[98:101], v[154:157], v[190:193], v[98:101]
	v_mfma_f32_16x16x32_bf16 v[90:93], v[162:165], v[190:193], v[90:93]
	v_mfma_f32_16x16x32_bf16 v[82:85], v[154:157], v[198:201], v[82:85]
	v_mfma_f32_16x16x32_bf16 v[74:77], v[162:165], v[198:201], v[74:77]
	v_mfma_f32_16x16x32_bf16 v[126:129], v[158:161], v[174:177], v[126:129]
	v_mfma_f32_16x16x32_bf16 v[122:125], v[166:169], v[174:177], v[122:125]
	v_mfma_f32_16x16x32_bf16 v[114:117], v[158:161], v[186:189], v[114:117]
	v_mfma_f32_16x16x32_bf16 v[106:109], v[166:169], v[186:189], v[106:109]
	v_mfma_f32_16x16x32_bf16 v[98:101], v[158:161], v[194:197], v[98:101]
	v_mfma_f32_16x16x32_bf16 v[90:93], v[166:169], v[194:197], v[90:93]
	v_mfma_f32_16x16x32_bf16 v[82:85], v[158:161], v[202:205], v[82:85]
	v_mfma_f32_16x16x32_bf16 v[74:77], v[166:169], v[202:205], v[74:77]
	v_mfma_f32_16x16x32_bf16 v[118:121], v[206:209], v[170:173], v[118:121]
	v_mfma_f32_16x16x32_bf16 v[110:113], v[214:217], v[170:173], v[110:113]
	v_mfma_f32_16x16x32_bf16 v[102:105], v[206:209], v[178:181], v[102:105]
	v_mfma_f32_16x16x32_bf16 v[94:97], v[214:217], v[178:181], v[94:97]
	v_mfma_f32_16x16x32_bf16 v[86:89], v[206:209], v[190:193], v[86:89]
	v_mfma_f32_16x16x32_bf16 v[78:81], v[214:217], v[190:193], v[78:81]
	v_mfma_f32_16x16x32_bf16 v[70:73], v[206:209], v[198:201], v[70:73]
	v_mfma_f32_16x16x32_bf16 v[66:69], v[214:217], v[198:201], v[66:69]
	v_mfma_f32_16x16x32_bf16 v[118:121], v[210:213], v[174:177], v[118:121]
	v_mfma_f32_16x16x32_bf16 v[110:113], v[218:221], v[174:177], v[110:113]
	v_mfma_f32_16x16x32_bf16 v[102:105], v[210:213], v[186:189], v[102:105]
	v_mfma_f32_16x16x32_bf16 v[94:97], v[218:221], v[186:189], v[94:97]
	v_mfma_f32_16x16x32_bf16 v[86:89], v[210:213], v[194:197], v[86:89]
	v_mfma_f32_16x16x32_bf16 v[78:81], v[218:221], v[194:197], v[78:81]
	v_mfma_f32_16x16x32_bf16 v[70:73], v[210:213], v[202:205], v[70:73]
	v_mfma_f32_16x16x32_bf16 v[66:69], v[218:221], v[202:205], v[66:69]
	s_setprio 0
	s_barrier
	s_add_i32 s28, s61, s45
	v_lshl_add_u64 v[146:147], s[30:31], 0, v[132:133]
	s_mov_b32 m0, s28
	global_load_lds_dwordx4 v132, s[30:31]
	v_lshl_add_u64 v[182:183], s[30:31], 0, v[136:137]
	s_add_i32 m0, s28, 0x2000
	s_nop 0
	global_load_lds_dwordx4 v136, s[30:31]
	s_mov_b32 m0, s46
	v_lshl_add_u64 v[222:223], s[34:35], 0, v[130:131]
	ds_read_b128 v[170:173], v151 offset:16384
	ds_read_b128 v[174:177], v151 offset:17408
	ds_read_b128 v[178:181], v151 offset:18432
	ds_read_b128 v[186:189], v151 offset:19456
	ds_read_b128 v[190:193], v151 offset:20480
	ds_read_b128 v[194:197], v151 offset:21504
	ds_read_b128 v[198:201], v151 offset:22528
	ds_read_b128 v[202:205], v151 offset:23552
	global_load_lds_dwordx4 v130, s[34:35]
	v_lshl_add_u64 v[224:225], s[34:35], 0, v[134:135]
	s_mov_b32 m0, s47
	s_nop 0
	global_load_lds_dwordx4 v134, s[34:35]
	s_waitcnt vmcnt(6)
	s_waitcnt lgkmcnt(0)
	s_barrier
	s_setprio 1
	v_mfma_f32_16x16x32_bf16 v[62:65], v[154:157], v[170:173], v[62:65]
	v_mfma_f32_16x16x32_bf16 v[58:61], v[162:165], v[170:173], v[58:61]
	v_mfma_f32_16x16x32_bf16 v[54:57], v[154:157], v[178:181], v[54:57]
	v_mfma_f32_16x16x32_bf16 v[46:49], v[162:165], v[178:181], v[46:49]
	v_mfma_f32_16x16x32_bf16 v[38:41], v[154:157], v[190:193], v[38:41]
	v_mfma_f32_16x16x32_bf16 v[30:33], v[162:165], v[190:193], v[30:33]
	v_mfma_f32_16x16x32_bf16 v[22:25], v[154:157], v[198:201], v[22:25]
	v_mfma_f32_16x16x32_bf16 v[14:17], v[162:165], v[198:201], v[14:17]
	v_mfma_f32_16x16x32_bf16 v[62:65], v[158:161], v[174:177], v[62:65]
	v_mfma_f32_16x16x32_bf16 v[58:61], v[166:169], v[174:177], v[58:61]
	v_mfma_f32_16x16x32_bf16 v[54:57], v[158:161], v[186:189], v[54:57]
	v_mfma_f32_16x16x32_bf16 v[46:49], v[166:169], v[186:189], v[46:49]
	v_mfma_f32_16x16x32_bf16 v[38:41], v[158:161], v[194:197], v[38:41]
	v_mfma_f32_16x16x32_bf16 v[30:33], v[166:169], v[194:197], v[30:33]
	v_mfma_f32_16x16x32_bf16 v[22:25], v[158:161], v[202:205], v[22:25]
	v_mfma_f32_16x16x32_bf16 v[14:17], v[166:169], v[202:205], v[14:17]
	v_mfma_f32_16x16x32_bf16 v[50:53], v[206:209], v[170:173], v[50:53]
	v_mfma_f32_16x16x32_bf16 v[42:45], v[214:217], v[170:173], v[42:45]
	v_mfma_f32_16x16x32_bf16 v[34:37], v[206:209], v[178:181], v[34:37]
	v_mfma_f32_16x16x32_bf16 v[26:29], v[214:217], v[178:181], v[26:29]
	v_mfma_f32_16x16x32_bf16 v[18:21], v[206:209], v[190:193], v[18:21]
	v_mfma_f32_16x16x32_bf16 v[10:13], v[214:217], v[190:193], v[10:13]
	v_mfma_f32_16x16x32_bf16 v[6:9], v[206:209], v[198:201], v[6:9]
	v_mfma_f32_16x16x32_bf16 v[2:5], v[214:217], v[198:201], v[2:5]
	v_mfma_f32_16x16x32_bf16 v[50:53], v[210:213], v[174:177], v[50:53]
	v_mfma_f32_16x16x32_bf16 v[42:45], v[218:221], v[174:177], v[42:45]
	v_mfma_f32_16x16x32_bf16 v[34:37], v[210:213], v[186:189], v[34:37]
	v_mfma_f32_16x16x32_bf16 v[26:29], v[218:221], v[186:189], v[26:29]
	v_mfma_f32_16x16x32_bf16 v[18:21], v[210:213], v[194:197], v[18:21]
	v_mfma_f32_16x16x32_bf16 v[10:13], v[218:221], v[194:197], v[10:13]
	v_mfma_f32_16x16x32_bf16 v[6:9], v[210:213], v[202:205], v[6:9]
	v_mfma_f32_16x16x32_bf16 v[2:5], v[218:221], v[202:205], v[2:5]
	s_setprio 0
	s_barrier
	s_add_u32 s28, s30, 0x20000
	s_addc_u32 s29, s31, 0
	s_add_i32 s82, s71, s45
	s_mov_b32 m0, s82
	s_nop 0
	global_load_lds_dwordx4 v132, s[28:29]
	s_add_i32 m0, s82, 0x2000
	s_nop 0
	global_load_lds_dwordx4 v136, s[28:29]
	s_add_i32 s82, 0, 0x18000
	v_add_u32_e32 v153, s82, v148
	ds_read_b128 v[154:157], v153
	ds_read_b128 v[158:161], v153 offset:1024
	ds_read_b128 v[162:165], v153 offset:2048
	ds_read_b128 v[166:169], v153 offset:3072
	s_add_u32 s28, s34, 0xf0000
	s_addc_u32 s29, s35, 0
	s_mov_b32 m0, s50
	ds_read_b128 v[170:173], v151 offset:32768
	ds_read_b128 v[174:177], v151 offset:33792
	ds_read_b128 v[178:181], v151 offset:34816
	ds_read_b128 v[186:189], v151 offset:35840
	ds_read_b128 v[190:193], v151 offset:36864
	ds_read_b128 v[194:197], v151 offset:37888
	ds_read_b128 v[198:201], v151 offset:38912
	ds_read_b128 v[202:205], v151 offset:39936
	v_add_u32_e32 v218, 0x1c000, v148
	ds_read_b128 v[206:209], v218
	ds_read_b128 v[210:213], v218 offset:1024
	ds_read_b128 v[214:217], v218 offset:2048
	ds_read_b128 v[218:221], v218 offset:3072
	global_load_lds_dwordx4 v130, s[28:29]
	s_mov_b32 m0, s51
	s_nop 0
	global_load_lds_dwordx4 v134, s[28:29]
	s_waitcnt vmcnt(8)
	s_waitcnt lgkmcnt(0)
	s_barrier
	s_setprio 1
	v_mfma_f32_16x16x32_bf16 v[126:129], v[154:157], v[170:173], v[126:129]
	v_mfma_f32_16x16x32_bf16 v[122:125], v[162:165], v[170:173], v[122:125]
	v_mfma_f32_16x16x32_bf16 v[114:117], v[154:157], v[178:181], v[114:117]
	v_mfma_f32_16x16x32_bf16 v[106:109], v[162:165], v[178:181], v[106:109]
	v_mfma_f32_16x16x32_bf16 v[98:101], v[154:157], v[190:193], v[98:101]
	v_mfma_f32_16x16x32_bf16 v[90:93], v[162:165], v[190:193], v[90:93]
	v_mfma_f32_16x16x32_bf16 v[82:85], v[154:157], v[198:201], v[82:85]
	v_mfma_f32_16x16x32_bf16 v[74:77], v[162:165], v[198:201], v[74:77]
	v_mfma_f32_16x16x32_bf16 v[126:129], v[158:161], v[174:177], v[126:129]
	v_mfma_f32_16x16x32_bf16 v[122:125], v[166:169], v[174:177], v[122:125]
	v_mfma_f32_16x16x32_bf16 v[114:117], v[158:161], v[186:189], v[114:117]
	v_mfma_f32_16x16x32_bf16 v[106:109], v[166:169], v[186:189], v[106:109]
	v_mfma_f32_16x16x32_bf16 v[98:101], v[158:161], v[194:197], v[98:101]
	v_mfma_f32_16x16x32_bf16 v[90:93], v[166:169], v[194:197], v[90:93]
	v_mfma_f32_16x16x32_bf16 v[82:85], v[158:161], v[202:205], v[82:85]
	v_mfma_f32_16x16x32_bf16 v[74:77], v[166:169], v[202:205], v[74:77]
	v_mfma_f32_16x16x32_bf16 v[118:121], v[206:209], v[170:173], v[118:121]
	v_mfma_f32_16x16x32_bf16 v[110:113], v[214:217], v[170:173], v[110:113]
	v_mfma_f32_16x16x32_bf16 v[102:105], v[206:209], v[178:181], v[102:105]
	v_mfma_f32_16x16x32_bf16 v[94:97], v[214:217], v[178:181], v[94:97]
	v_mfma_f32_16x16x32_bf16 v[86:89], v[206:209], v[190:193], v[86:89]
	v_mfma_f32_16x16x32_bf16 v[78:81], v[214:217], v[190:193], v[78:81]
	v_mfma_f32_16x16x32_bf16 v[70:73], v[206:209], v[198:201], v[70:73]
	v_mfma_f32_16x16x32_bf16 v[66:69], v[214:217], v[198:201], v[66:69]
	v_mfma_f32_16x16x32_bf16 v[118:121], v[210:213], v[174:177], v[118:121]
	v_mfma_f32_16x16x32_bf16 v[110:113], v[218:221], v[174:177], v[110:113]
	v_mfma_f32_16x16x32_bf16 v[102:105], v[210:213], v[186:189], v[102:105]
	v_mfma_f32_16x16x32_bf16 v[94:97], v[218:221], v[186:189], v[94:97]
	v_mfma_f32_16x16x32_bf16 v[86:89], v[210:213], v[194:197], v[86:89]
	v_mfma_f32_16x16x32_bf16 v[78:81], v[218:221], v[194:197], v[78:81]
	v_mfma_f32_16x16x32_bf16 v[70:73], v[210:213], v[202:205], v[70:73]
	v_mfma_f32_16x16x32_bf16 v[66:69], v[218:221], v[202:205], v[66:69]
	s_setprio 0
	s_barrier
	s_add_i32 s34, 0, 0x1c000
	s_add_i32 s28, s82, s45
	v_lshl_add_u64 v[146:147], v[146:147], 0, s[6:7]
	s_mov_b32 m0, s28
	global_load_lds_dwordx4 v[146:147], off
	v_lshl_add_u64 v[146:147], v[182:183], 0, s[6:7]
	s_add_i32 m0, s28, 0x2000
	s_nop 0
	global_load_lds_dwordx4 v[146:147], off
	s_mov_b32 m0, s53
	v_lshl_add_u64 v[146:147], v[222:223], 0, s[6:7]
	ds_read_b128 v[170:173], v151 offset:49152
	ds_read_b128 v[174:177], v151 offset:50176
	ds_read_b128 v[178:181], v151 offset:51200
	ds_read_b128 v[186:189], v151 offset:52224
	ds_read_b128 v[190:193], v151 offset:53248
	ds_read_b128 v[194:197], v151 offset:54272
	ds_read_b128 v[198:201], v151 offset:55296
	ds_read_b128 v[202:205], v151 offset:56320
	global_load_lds_dwordx4 v[146:147], off
	v_lshl_add_u64 v[146:147], v[224:225], 0, s[6:7]
	s_mov_b32 m0, s58
	s_nop 0
	global_load_lds_dwordx4 v[146:147], off
	s_add_u32 s28, s30, 0x20080
	s_addc_u32 s29, s31, 0
	s_add_i32 s30, s34, s45
	s_mov_b32 m0, s30
	s_nop 0
	global_load_lds_dwordx4 v132, s[28:29]
	s_add_i32 m0, s30, 0x2000
	s_nop 0
	global_load_lds_dwordx4 v136, s[28:29]
	s_waitcnt vmcnt(8)
	s_waitcnt lgkmcnt(0)
	s_barrier
	s_setprio 1
	v_mfma_f32_16x16x32_bf16 v[62:65], v[154:157], v[170:173], v[62:65]
	v_mfma_f32_16x16x32_bf16 v[58:61], v[162:165], v[170:173], v[58:61]
	v_mfma_f32_16x16x32_bf16 v[54:57], v[154:157], v[178:181], v[54:57]
	v_mfma_f32_16x16x32_bf16 v[46:49], v[162:165], v[178:181], v[46:49]
	v_mfma_f32_16x16x32_bf16 v[38:41], v[154:157], v[190:193], v[38:41]
	v_mfma_f32_16x16x32_bf16 v[30:33], v[162:165], v[190:193], v[30:33]
	v_mfma_f32_16x16x32_bf16 v[22:25], v[154:157], v[198:201], v[22:25]
	v_mfma_f32_16x16x32_bf16 v[14:17], v[162:165], v[198:201], v[14:17]
	v_mfma_f32_16x16x32_bf16 v[62:65], v[158:161], v[174:177], v[62:65]
	v_mfma_f32_16x16x32_bf16 v[58:61], v[166:169], v[174:177], v[58:61]
	v_mfma_f32_16x16x32_bf16 v[54:57], v[158:161], v[186:189], v[54:57]
	v_mfma_f32_16x16x32_bf16 v[46:49], v[166:169], v[186:189], v[46:49]
	v_mfma_f32_16x16x32_bf16 v[38:41], v[158:161], v[194:197], v[38:41]
	v_mfma_f32_16x16x32_bf16 v[30:33], v[166:169], v[194:197], v[30:33]
	v_mfma_f32_16x16x32_bf16 v[22:25], v[158:161], v[202:205], v[22:25]
	v_mfma_f32_16x16x32_bf16 v[14:17], v[166:169], v[202:205], v[14:17]
	v_mfma_f32_16x16x32_bf16 v[50:53], v[206:209], v[170:173], v[50:53]
	v_mfma_f32_16x16x32_bf16 v[42:45], v[214:217], v[170:173], v[42:45]
	v_mfma_f32_16x16x32_bf16 v[34:37], v[206:209], v[178:181], v[34:37]
	v_mfma_f32_16x16x32_bf16 v[26:29], v[214:217], v[178:181], v[26:29]
	v_mfma_f32_16x16x32_bf16 v[18:21], v[206:209], v[190:193], v[18:21]
	v_mfma_f32_16x16x32_bf16 v[10:13], v[214:217], v[190:193], v[10:13]
	v_mfma_f32_16x16x32_bf16 v[6:9], v[206:209], v[198:201], v[6:9]
	v_mfma_f32_16x16x32_bf16 v[2:5], v[214:217], v[198:201], v[2:5]
	v_mfma_f32_16x16x32_bf16 v[50:53], v[210:213], v[174:177], v[50:53]
	v_mfma_f32_16x16x32_bf16 v[42:45], v[218:221], v[174:177], v[42:45]
	v_mfma_f32_16x16x32_bf16 v[34:37], v[210:213], v[186:189], v[34:37]
	v_mfma_f32_16x16x32_bf16 v[26:29], v[218:221], v[186:189], v[26:29]
	v_mfma_f32_16x16x32_bf16 v[18:21], v[210:213], v[194:197], v[18:21]
	v_mfma_f32_16x16x32_bf16 v[10:13], v[218:221], v[194:197], v[10:13]
	v_mfma_f32_16x16x32_bf16 v[6:9], v[210:213], v[202:205], v[6:9]
	v_mfma_f32_16x16x32_bf16 v[2:5], v[218:221], v[202:205], v[2:5]
	s_setprio 0
	s_add_i32 s81, s81, 2
	s_add_u32 s79, s79, 0x100
	s_addc_u32 s80, s80, 0
	s_cmp_gt_u32 s81, 5
	s_mov_b64 s[28:29], s[4:5]
	s_barrier
	s_cbranch_scc0 .LBB0_457
	v_lshl_add_u32 v154, s69, 8, v1
	v_lshl_or_b32 v146, s70, 8, v149
	v_ashrrev_i32_e32 v155, 31, v154
	v_ashrrev_i32_e32 v147, 31, v146
	v_lshlrev_b64 v[156:157], 12, v[154:155]
	v_lshl_add_u64 v[156:157], s[88:89], 0, v[156:157]
	v_lshlrev_b64 v[158:159], 1, v[146:147]
	v_lshl_add_u64 v[146:147], v[156:157], 0, v[158:159]
	v_cvt_pk_bf16_f32 v126, v126, v127
	v_cvt_pk_bf16_f32 v127, v128, v129
	v_cvt_pk_bf16_f32 v128, v122, v123
	v_cvt_pk_bf16_f32 v129, v124, v125
	global_store_dwordx4 v[146:147], v[126:129], off
	v_cvt_pk_bf16_f32 v118, v118, v119
	v_cvt_pk_bf16_f32 v119, v120, v121
	v_cvt_pk_bf16_f32 v120, v110, v111
	v_or_b32_e32 v110, 16, v154
	v_ashrrev_i32_e32 v111, 31, v110
	v_lshlrev_b64 v[110:111], 12, v[110:111]
	v_lshl_add_u64 v[110:111], s[88:89], 0, v[110:111]
	v_cvt_pk_bf16_f32 v121, v112, v113
	global_store_dwordx4 v[146:147], v[118:121], off offset:256
	s_mov_b32 s70, s22
	s_mov_b32 s69, s68
	v_lshl_add_u64 v[118:119], v[110:111], 0, v[158:159]
	v_cvt_pk_bf16_f32 v110, v114, v115
	v_cvt_pk_bf16_f32 v111, v116, v117
	v_cvt_pk_bf16_f32 v112, v106, v107
	v_cvt_pk_bf16_f32 v113, v108, v109
	global_store_dwordx4 v[118:119], v[110:113], off
	v_cvt_pk_bf16_f32 v102, v102, v103
	v_cvt_pk_bf16_f32 v103, v104, v105
	v_cvt_pk_bf16_f32 v104, v94, v95
	v_or_b32_e32 v94, 32, v154
	v_ashrrev_i32_e32 v95, 31, v94
	v_lshlrev_b64 v[94:95], 12, v[94:95]
	v_lshl_add_u64 v[94:95], s[88:89], 0, v[94:95]
	v_cvt_pk_bf16_f32 v105, v96, v97
	global_store_dwordx4 v[118:119], v[102:105], off offset:256
	s_mov_b64 s[30:31], s[26:27]
	s_mov_b64 s[28:29], s[24:25]
	v_lshl_add_u64 v[102:103], v[94:95], 0, v[158:159]
	v_cvt_pk_bf16_f32 v94, v98, v99
	v_cvt_pk_bf16_f32 v95, v100, v101
	v_cvt_pk_bf16_f32 v96, v90, v91
	v_cvt_pk_bf16_f32 v97, v92, v93
	global_store_dwordx4 v[102:103], v[94:97], off
	v_cvt_pk_bf16_f32 v86, v86, v87
	v_cvt_pk_bf16_f32 v87, v88, v89
	v_cvt_pk_bf16_f32 v88, v78, v79
	v_or_b32_e32 v78, 48, v154
	v_ashrrev_i32_e32 v79, 31, v78
	v_lshlrev_b64 v[78:79], 12, v[78:79]
	v_lshl_add_u64 v[78:79], s[88:89], 0, v[78:79]
	v_cvt_pk_bf16_f32 v89, v80, v81
	global_store_dwordx4 v[102:103], v[86:89], off offset:256
	s_nop 1
	v_lshl_add_u64 v[86:87], v[78:79], 0, v[158:159]
	v_cvt_pk_bf16_f32 v78, v82, v83
	v_cvt_pk_bf16_f32 v79, v84, v85
	v_cvt_pk_bf16_f32 v80, v74, v75
	v_cvt_pk_bf16_f32 v81, v76, v77
	global_store_dwordx4 v[86:87], v[78:81], off
	v_cvt_pk_bf16_f32 v70, v70, v71
	v_cvt_pk_bf16_f32 v71, v72, v73
	v_cvt_pk_bf16_f32 v72, v66, v67
	v_cvt_pk_bf16_f32 v73, v68, v69
	global_store_dwordx4 v[86:87], v[70:73], off offset:256
	v_cvt_pk_bf16_f32 v62, v62, v63
	v_cvt_pk_bf16_f32 v63, v64, v65
	v_cvt_pk_bf16_f32 v64, v58, v59
	v_add_co_u32_e32 v58, vcc, s74, v146
	v_lshl_add_u64 v[66:67], v[146:147], 0, s[8:9]
	s_nop 0
	v_addc_co_u32_e32 v59, vcc, 0, v147, vcc
	v_cvt_pk_bf16_f32 v65, v60, v61
	global_store_dwordx4 v[58:59], v[62:65], off
	v_cvt_pk_bf16_f32 v50, v50, v51
	v_cvt_pk_bf16_f32 v51, v52, v53
	v_cvt_pk_bf16_f32 v52, v42, v43
	v_cvt_pk_bf16_f32 v53, v44, v45
	global_store_dwordx4 v[66:67], v[50:53], off offset:256
	v_cvt_pk_bf16_f32 v42, v54, v55
	v_cvt_pk_bf16_f32 v43, v56, v57
	v_cvt_pk_bf16_f32 v44, v46, v47
	v_add_co_u32_e32 v46, vcc, s75, v146
	s_nop 0
	v_lshl_add_u64 v[50:51], v[146:147], 0, s[16:17]
	v_addc_co_u32_e32 v47, vcc, 0, v147, vcc
	v_cvt_pk_bf16_f32 v45, v48, v49
	global_store_dwordx4 v[46:47], v[42:45], off
	v_cvt_pk_bf16_f32 v34, v34, v35
	v_cvt_pk_bf16_f32 v35, v36, v37
	v_cvt_pk_bf16_f32 v36, v26, v27
	v_cvt_pk_bf16_f32 v37, v28, v29
	global_store_dwordx4 v[50:51], v[34:37], off offset:256
	v_cvt_pk_bf16_f32 v26, v38, v39
	v_cvt_pk_bf16_f32 v27, v40, v41
	v_cvt_pk_bf16_f32 v28, v30, v31
	v_add_co_u32_e32 v30, vcc, s76, v146
	s_nop 0
	v_lshl_add_u64 v[34:35], v[146:147], 0, s[18:19]
	v_addc_co_u32_e32 v31, vcc, 0, v147, vcc
	v_cvt_pk_bf16_f32 v29, v32, v33
	global_store_dwordx4 v[30:31], v[26:29], off
	v_cvt_pk_bf16_f32 v18, v18, v19
	v_cvt_pk_bf16_f32 v19, v20, v21
	v_cvt_pk_bf16_f32 v20, v10, v11
	v_cvt_pk_bf16_f32 v21, v12, v13
	global_store_dwordx4 v[34:35], v[18:21], off offset:256
	v_cvt_pk_bf16_f32 v10, v22, v23
	v_cvt_pk_bf16_f32 v11, v24, v25
	v_cvt_pk_bf16_f32 v12, v14, v15
	v_add_co_u32_e32 v14, vcc, s77, v146
	s_nop 0
	v_lshl_add_u64 v[18:19], v[146:147], 0, s[20:21]
	v_addc_co_u32_e32 v15, vcc, 0, v147, vcc
	s_and_b64 vcc, exec, s[2:3]
	v_cvt_pk_bf16_f32 v13, v16, v17
	global_store_dwordx4 v[14:15], v[10:13], off
	v_cvt_pk_bf16_f32 v6, v6, v7
	v_cvt_pk_bf16_f32 v7, v8, v9
	v_cvt_pk_bf16_f32 v8, v2, v3
	v_cvt_pk_bf16_f32 v9, v4, v5
	global_store_dwordx4 v[18:19], v[6:9], off offset:256
	s_cbranch_vccz .LBB0_448
	s_waitcnt vmcnt(0)
	s_cmpk_gt_u32 s36, 0xff
	s_cbranch_scc1 .LBB0_461
	s_barrier

.LBB0_696:
	ds_read_b128 v[82:85], v208
	ds_read_b128 v[86:89], v208 offset:1024
	ds_read_b128 v[94:97], v208 offset:2048
	ds_read_b128 v[102:105], v208 offset:3072
	s_add_u32 s8, s2, 0x100
	s_addc_u32 s9, s3, 0
	s_cmp_eq_u32 s68, 28
	s_cselect_b32 s31, s25, s9
	s_cselect_b32 s30, s24, s8
	s_cselect_b32 s29, s1, s63
	s_cselect_b32 s28, s23, s53
	v_lshl_add_u64 v[182:183], s[2:3], 0, v[170:171]
	s_add_i32 m0, s41, 0xc000
	ds_read_b128 v[146:149], v209
	ds_read_b128 v[150:153], v209 offset:1024
	ds_read_b128 v[154:157], v209 offset:2048
	ds_read_b128 v[158:161], v209 offset:3072
	ds_read_b128 v[178:181], v209 offset:4096
	ds_read_b128 v[186:189], v209 offset:5120
	ds_read_b128 v[190:193], v209 offset:6144
	ds_read_b128 v[194:197], v209 offset:7168
	global_load_lds_dwordx4 v[182:183], off
	v_lshl_add_u64 v[182:183], s[2:3], 0, v[172:173]
	s_add_i32 m0, s41, 0xe000
	s_nop 0
	global_load_lds_dwordx4 v[182:183], off
	ds_read_b128 v[198:201], v210
	ds_read_b128 v[202:205], v210 offset:1024
	ds_read_b128 v[212:215], v210 offset:2048
	ds_read_b128 v[216:219], v210 offset:3072
	s_waitcnt vmcnt(8)
	s_waitcnt lgkmcnt(0)
	s_barrier
	s_setprio 1
	v_mfma_f32_16x16x32_bf16 v[142:145], v[82:85], v[146:149], v[142:145]
	v_mfma_f32_16x16x32_bf16 v[138:141], v[94:97], v[146:149], v[138:141]
	v_mfma_f32_16x16x32_bf16 v[126:129], v[82:85], v[154:157], v[126:129]
	v_mfma_f32_16x16x32_bf16 v[122:125], v[94:97], v[154:157], v[122:125]
	v_mfma_f32_16x16x32_bf16 v[110:113], v[82:85], v[178:181], v[110:113]
	v_mfma_f32_16x16x32_bf16 v[106:109], v[94:97], v[178:181], v[106:109]
	v_mfma_f32_16x16x32_bf16 v[78:81], v[82:85], v[190:193], v[78:81]
	v_mfma_f32_16x16x32_bf16 v[74:77], v[94:97], v[190:193], v[74:77]
	v_mfma_f32_16x16x32_bf16 v[142:145], v[86:89], v[150:153], v[142:145]
	v_mfma_f32_16x16x32_bf16 v[138:141], v[102:105], v[150:153], v[138:141]
	v_mfma_f32_16x16x32_bf16 v[126:129], v[86:89], v[158:161], v[126:129]
	v_mfma_f32_16x16x32_bf16 v[122:125], v[102:105], v[158:161], v[122:125]
	v_mfma_f32_16x16x32_bf16 v[110:113], v[86:89], v[186:189], v[110:113]
	v_mfma_f32_16x16x32_bf16 v[106:109], v[102:105], v[186:189], v[106:109]
	v_mfma_f32_16x16x32_bf16 v[78:81], v[86:89], v[194:197], v[78:81]
	v_mfma_f32_16x16x32_bf16 v[74:77], v[102:105], v[194:197], v[74:77]
	v_mfma_f32_16x16x32_bf16 v[134:137], v[198:201], v[146:149], v[134:137]
	v_mfma_f32_16x16x32_bf16 v[130:133], v[212:215], v[146:149], v[130:133]
	v_mfma_f32_16x16x32_bf16 v[118:121], v[198:201], v[154:157], v[118:121]
	v_mfma_f32_16x16x32_bf16 v[114:117], v[212:215], v[154:157], v[114:117]
	v_mfma_f32_16x16x32_bf16 v[98:101], v[198:201], v[178:181], v[98:101]
	v_mfma_f32_16x16x32_bf16 v[90:93], v[212:215], v[178:181], v[90:93]
	v_mfma_f32_16x16x32_bf16 v[70:73], v[198:201], v[190:193], v[70:73]
	v_mfma_f32_16x16x32_bf16 v[66:69], v[212:215], v[190:193], v[66:69]
	v_mfma_f32_16x16x32_bf16 v[134:137], v[202:205], v[150:153], v[134:137]
	v_mfma_f32_16x16x32_bf16 v[130:133], v[216:219], v[150:153], v[130:133]
	v_mfma_f32_16x16x32_bf16 v[118:121], v[202:205], v[158:161], v[118:121]
	v_mfma_f32_16x16x32_bf16 v[114:117], v[216:219], v[158:161], v[114:117]
	v_mfma_f32_16x16x32_bf16 v[98:101], v[202:205], v[186:189], v[98:101]
	v_mfma_f32_16x16x32_bf16 v[90:93], v[216:219], v[186:189], v[90:93]
	v_mfma_f32_16x16x32_bf16 v[70:73], v[202:205], v[194:197], v[70:73]
	v_mfma_f32_16x16x32_bf16 v[66:69], v[216:219], v[194:197], v[66:69]
	s_setprio 0
	s_barrier
	s_add_i32 s2, s59, s37
	v_lshl_add_u64 v[182:183], s[28:29], 0, v[164:165]
	s_mov_b32 m0, s2
	global_load_lds_dwordx4 v164, s[28:29]
	v_lshl_add_u64 v[220:221], s[28:29], 0, v[168:169]
	s_add_i32 m0, s2, 0x2000
	s_nop 0
	global_load_lds_dwordx4 v168, s[28:29]
	s_mov_b32 m0, s41
	v_lshl_add_u64 v[222:223], s[30:31], 0, v[162:163]
	ds_read_b128 v[146:149], v209 offset:16384
	ds_read_b128 v[150:153], v209 offset:17408
	ds_read_b128 v[154:157], v209 offset:18432
	ds_read_b128 v[158:161], v209 offset:19456
	ds_read_b128 v[178:181], v209 offset:20480
	ds_read_b128 v[186:189], v209 offset:21504
	ds_read_b128 v[190:193], v209 offset:22528
	ds_read_b128 v[194:197], v209 offset:23552
	global_load_lds_dwordx4 v162, s[30:31]
	v_lshl_add_u64 v[224:225], s[30:31], 0, v[166:167]
	s_mov_b32 m0, s42
	s_nop 0
	global_load_lds_dwordx4 v166, s[30:31]
	s_waitcnt vmcnt(6)
	s_waitcnt lgkmcnt(0)
	s_barrier
	s_setprio 1
	v_mfma_f32_16x16x32_bf16 v[62:65], v[82:85], v[146:149], v[62:65]
	v_mfma_f32_16x16x32_bf16 v[58:61], v[94:97], v[146:149], v[58:61]
	v_mfma_f32_16x16x32_bf16 v[46:49], v[82:85], v[154:157], v[46:49]
	v_mfma_f32_16x16x32_bf16 v[42:45], v[94:97], v[154:157], v[42:45]
	v_mfma_f32_16x16x32_bf16 v[30:33], v[82:85], v[178:181], v[30:33]
	v_mfma_f32_16x16x32_bf16 v[26:29], v[94:97], v[178:181], v[26:29]
	v_mfma_f32_16x16x32_bf16 v[14:17], v[82:85], v[190:193], v[14:17]
	v_mfma_f32_16x16x32_bf16 v[10:13], v[94:97], v[190:193], v[10:13]
	v_mfma_f32_16x16x32_bf16 v[62:65], v[86:89], v[150:153], v[62:65]
	v_mfma_f32_16x16x32_bf16 v[58:61], v[102:105], v[150:153], v[58:61]
	v_mfma_f32_16x16x32_bf16 v[46:49], v[86:89], v[158:161], v[46:49]
	v_mfma_f32_16x16x32_bf16 v[42:45], v[102:105], v[158:161], v[42:45]
	v_mfma_f32_16x16x32_bf16 v[30:33], v[86:89], v[186:189], v[30:33]
	v_mfma_f32_16x16x32_bf16 v[26:29], v[102:105], v[186:189], v[26:29]
	v_mfma_f32_16x16x32_bf16 v[14:17], v[86:89], v[194:197], v[14:17]
	v_mfma_f32_16x16x32_bf16 v[10:13], v[102:105], v[194:197], v[10:13]
	v_mfma_f32_16x16x32_bf16 v[54:57], v[198:201], v[146:149], v[54:57]
	v_mfma_f32_16x16x32_bf16 v[50:53], v[212:215], v[146:149], v[50:53]
	v_mfma_f32_16x16x32_bf16 v[38:41], v[198:201], v[154:157], v[38:41]
	v_mfma_f32_16x16x32_bf16 v[34:37], v[212:215], v[154:157], v[34:37]
	v_mfma_f32_16x16x32_bf16 v[22:25], v[198:201], v[178:181], v[22:25]
	v_mfma_f32_16x16x32_bf16 v[18:21], v[212:215], v[178:181], v[18:21]
	v_mfma_f32_16x16x32_bf16 v[6:9], v[198:201], v[190:193], v[6:9]
	v_mfma_f32_16x16x32_bf16 v[2:5], v[212:215], v[190:193], v[2:5]
	v_mfma_f32_16x16x32_bf16 v[54:57], v[202:205], v[150:153], v[54:57]
	v_mfma_f32_16x16x32_bf16 v[50:53], v[216:219], v[150:153], v[50:53]
	v_mfma_f32_16x16x32_bf16 v[38:41], v[202:205], v[158:161], v[38:41]
	v_mfma_f32_16x16x32_bf16 v[34:37], v[216:219], v[158:161], v[34:37]
	v_mfma_f32_16x16x32_bf16 v[22:25], v[202:205], v[186:189], v[22:25]
	v_mfma_f32_16x16x32_bf16 v[18:21], v[216:219], v[186:189], v[18:21]
	v_mfma_f32_16x16x32_bf16 v[6:9], v[202:205], v[194:197], v[6:9]
	v_mfma_f32_16x16x32_bf16 v[2:5], v[216:219], v[194:197], v[2:5]
	s_setprio 0
	s_barrier
	s_add_u32 s2, s28, 0x80000
	s_addc_u32 s3, s29, 0
	s_add_i32 s69, s60, s37
	s_mov_b32 m0, s69
	s_nop 0
	global_load_lds_dwordx4 v164, s[2:3]
	s_add_i32 m0, s69, 0x2000
	s_nop 0
	global_load_lds_dwordx4 v168, s[2:3]
	s_add_i32 s69, 0, 0x18000
	v_add_u32_e32 v102, s69, v206
	ds_read_b128 v[82:85], v102
	ds_read_b128 v[86:89], v102 offset:1024
	ds_read_b128 v[94:97], v102 offset:2048
	ds_read_b128 v[102:105], v102 offset:3072
	s_add_u32 s2, s30, 0xf0000
	s_addc_u32 s3, s31, 0
	s_mov_b32 m0, s43
	ds_read_b128 v[146:149], v209 offset:32768
	ds_read_b128 v[150:153], v209 offset:33792
	ds_read_b128 v[154:157], v209 offset:34816
	ds_read_b128 v[158:161], v209 offset:35840
	ds_read_b128 v[178:181], v209 offset:36864
	ds_read_b128 v[186:189], v209 offset:37888
	ds_read_b128 v[190:193], v209 offset:38912
	ds_read_b128 v[194:197], v209 offset:39936
	v_add_u32_e32 v216, 0x1c000, v206
	ds_read_b128 v[198:201], v216
	ds_read_b128 v[202:205], v216 offset:1024
	ds_read_b128 v[212:215], v216 offset:2048
	ds_read_b128 v[216:219], v216 offset:3072
	global_load_lds_dwordx4 v162, s[2:3]
	s_mov_b32 m0, s44
	s_nop 0
	global_load_lds_dwordx4 v166, s[2:3]
	s_waitcnt vmcnt(8)
	s_waitcnt lgkmcnt(0)
	s_barrier
	s_setprio 1
	v_mfma_f32_16x16x32_bf16 v[142:145], v[82:85], v[146:149], v[142:145]
	v_mfma_f32_16x16x32_bf16 v[138:141], v[94:97], v[146:149], v[138:141]
	v_mfma_f32_16x16x32_bf16 v[126:129], v[82:85], v[154:157], v[126:129]
	v_mfma_f32_16x16x32_bf16 v[122:125], v[94:97], v[154:157], v[122:125]
	v_mfma_f32_16x16x32_bf16 v[110:113], v[82:85], v[178:181], v[110:113]
	v_mfma_f32_16x16x32_bf16 v[106:109], v[94:97], v[178:181], v[106:109]
	v_mfma_f32_16x16x32_bf16 v[78:81], v[82:85], v[190:193], v[78:81]
	v_mfma_f32_16x16x32_bf16 v[74:77], v[94:97], v[190:193], v[74:77]
	v_mfma_f32_16x16x32_bf16 v[142:145], v[86:89], v[150:153], v[142:145]
	v_mfma_f32_16x16x32_bf16 v[138:141], v[102:105], v[150:153], v[138:141]
	v_mfma_f32_16x16x32_bf16 v[126:129], v[86:89], v[158:161], v[126:129]
	v_mfma_f32_16x16x32_bf16 v[122:125], v[102:105], v[158:161], v[122:125]
	v_mfma_f32_16x16x32_bf16 v[110:113], v[86:89], v[186:189], v[110:113]
	v_mfma_f32_16x16x32_bf16 v[106:109], v[102:105], v[186:189], v[106:109]
	v_mfma_f32_16x16x32_bf16 v[78:81], v[86:89], v[194:197], v[78:81]
	v_mfma_f32_16x16x32_bf16 v[74:77], v[102:105], v[194:197], v[74:77]
	v_mfma_f32_16x16x32_bf16 v[134:137], v[198:201], v[146:149], v[134:137]
	v_mfma_f32_16x16x32_bf16 v[130:133], v[212:215], v[146:149], v[130:133]
	v_mfma_f32_16x16x32_bf16 v[118:121], v[198:201], v[154:157], v[118:121]
	v_mfma_f32_16x16x32_bf16 v[114:117], v[212:215], v[154:157], v[114:117]
	v_mfma_f32_16x16x32_bf16 v[98:101], v[198:201], v[178:181], v[98:101]
	v_mfma_f32_16x16x32_bf16 v[90:93], v[212:215], v[178:181], v[90:93]
	v_mfma_f32_16x16x32_bf16 v[70:73], v[198:201], v[190:193], v[70:73]
	v_mfma_f32_16x16x32_bf16 v[66:69], v[212:215], v[190:193], v[66:69]
	v_mfma_f32_16x16x32_bf16 v[134:137], v[202:205], v[150:153], v[134:137]
	v_mfma_f32_16x16x32_bf16 v[130:133], v[216:219], v[150:153], v[130:133]
	v_mfma_f32_16x16x32_bf16 v[118:121], v[202:205], v[158:161], v[118:121]
	v_mfma_f32_16x16x32_bf16 v[114:117], v[216:219], v[158:161], v[114:117]
	v_mfma_f32_16x16x32_bf16 v[98:101], v[202:205], v[186:189], v[98:101]
	v_mfma_f32_16x16x32_bf16 v[90:93], v[216:219], v[186:189], v[90:93]
	v_mfma_f32_16x16x32_bf16 v[70:73], v[202:205], v[194:197], v[70:73]
	v_mfma_f32_16x16x32_bf16 v[66:69], v[216:219], v[194:197], v[66:69]
	s_setprio 0
	s_barrier
	s_add_i32 s30, 0, 0x1c000
	s_add_i32 s2, s69, s37
	v_lshl_add_u64 v[182:183], v[182:183], 0, s[20:21]
	s_mov_b32 m0, s2
	global_load_lds_dwordx4 v[182:183], off
	v_lshl_add_u64 v[182:183], v[220:221], 0, s[20:21]
	s_add_i32 m0, s2, 0x2000
	s_nop 0
	global_load_lds_dwordx4 v[182:183], off
	s_mov_b32 m0, s47
	v_lshl_add_u64 v[182:183], v[222:223], 0, s[20:21]
	ds_read_b128 v[146:149], v209 offset:49152
	ds_read_b128 v[150:153], v209 offset:50176
	ds_read_b128 v[154:157], v209 offset:51200
	ds_read_b128 v[158:161], v209 offset:52224
	ds_read_b128 v[178:181], v209 offset:53248
	ds_read_b128 v[186:189], v209 offset:54272
	ds_read_b128 v[190:193], v209 offset:55296
	ds_read_b128 v[194:197], v209 offset:56320
	global_load_lds_dwordx4 v[182:183], off
	v_lshl_add_u64 v[182:183], v[224:225], 0, s[20:21]
	s_mov_b32 m0, s48
	s_nop 0
	global_load_lds_dwordx4 v[182:183], off
	s_add_u32 s2, s28, 0x80080
	s_addc_u32 s3, s29, 0
	s_add_i32 s28, s30, s37
	s_mov_b32 m0, s28
	s_nop 0
	global_load_lds_dwordx4 v164, s[2:3]
	s_add_i32 m0, s28, 0x2000
	s_nop 0
	global_load_lds_dwordx4 v168, s[2:3]
	s_waitcnt vmcnt(8)
	s_waitcnt lgkmcnt(0)
	s_barrier
	s_setprio 1
	v_mfma_f32_16x16x32_bf16 v[62:65], v[82:85], v[146:149], v[62:65]
	v_mfma_f32_16x16x32_bf16 v[58:61], v[94:97], v[146:149], v[58:61]
	v_mfma_f32_16x16x32_bf16 v[46:49], v[82:85], v[154:157], v[46:49]
	v_mfma_f32_16x16x32_bf16 v[42:45], v[94:97], v[154:157], v[42:45]
	v_mfma_f32_16x16x32_bf16 v[30:33], v[82:85], v[178:181], v[30:33]
	v_mfma_f32_16x16x32_bf16 v[26:29], v[94:97], v[178:181], v[26:29]
	v_mfma_f32_16x16x32_bf16 v[14:17], v[82:85], v[190:193], v[14:17]
	v_mfma_f32_16x16x32_bf16 v[10:13], v[94:97], v[190:193], v[10:13]
	v_mfma_f32_16x16x32_bf16 v[62:65], v[86:89], v[150:153], v[62:65]
	v_mfma_f32_16x16x32_bf16 v[58:61], v[102:105], v[150:153], v[58:61]
	v_mfma_f32_16x16x32_bf16 v[46:49], v[86:89], v[158:161], v[46:49]
	v_mfma_f32_16x16x32_bf16 v[42:45], v[102:105], v[158:161], v[42:45]
	v_mfma_f32_16x16x32_bf16 v[30:33], v[86:89], v[186:189], v[30:33]
	v_mfma_f32_16x16x32_bf16 v[26:29], v[102:105], v[186:189], v[26:29]
	v_mfma_f32_16x16x32_bf16 v[14:17], v[86:89], v[194:197], v[14:17]
	v_mfma_f32_16x16x32_bf16 v[10:13], v[102:105], v[194:197], v[10:13]
	v_mfma_f32_16x16x32_bf16 v[54:57], v[198:201], v[146:149], v[54:57]
	v_mfma_f32_16x16x32_bf16 v[50:53], v[212:215], v[146:149], v[50:53]
	v_mfma_f32_16x16x32_bf16 v[38:41], v[198:201], v[154:157], v[38:41]
	v_mfma_f32_16x16x32_bf16 v[34:37], v[212:215], v[154:157], v[34:37]
	v_mfma_f32_16x16x32_bf16 v[22:25], v[198:201], v[178:181], v[22:25]
	v_mfma_f32_16x16x32_bf16 v[18:21], v[212:215], v[178:181], v[18:21]
	v_mfma_f32_16x16x32_bf16 v[6:9], v[198:201], v[190:193], v[6:9]
	v_mfma_f32_16x16x32_bf16 v[2:5], v[212:215], v[190:193], v[2:5]
	v_mfma_f32_16x16x32_bf16 v[54:57], v[202:205], v[150:153], v[54:57]
	v_mfma_f32_16x16x32_bf16 v[50:53], v[216:219], v[150:153], v[50:53]
	v_mfma_f32_16x16x32_bf16 v[38:41], v[202:205], v[158:161], v[38:41]
	v_mfma_f32_16x16x32_bf16 v[34:37], v[216:219], v[158:161], v[34:37]
	v_mfma_f32_16x16x32_bf16 v[22:25], v[202:205], v[186:189], v[22:25]
	v_mfma_f32_16x16x32_bf16 v[18:21], v[216:219], v[186:189], v[18:21]
	v_mfma_f32_16x16x32_bf16 v[6:9], v[202:205], v[194:197], v[6:9]
	v_mfma_f32_16x16x32_bf16 v[2:5], v[216:219], v[194:197], v[2:5]
	s_setprio 0
	s_add_i32 s68, s68, 2
	s_add_u32 s53, s53, 0x100
	s_addc_u32 s63, s63, 0
	s_cmp_gt_u32 s68, 29
	s_mov_b64 s[2:3], s[8:9]
	s_barrier
	s_cbranch_scc0 .LBB0_696
	s_min_i32 s1, s52, 64
	s_ashr_i32 s1, s1, 3
	v_lshl_or_b32 v178, s0, 8, v207
	s_mul_hi_i32 s2, s1, 0xc000
	s_mul_i32 s1, s1, 0xc000
	s_add_u32 s0, s10, s1
	v_ashrrev_i32_e32 v179, 31, v178
	s_addc_u32 s1, s11, s2
	v_lshlrev_b64 v[198:199], 2, v[178:179]
	v_lshl_add_u32 v200, s52, 8, v1
	v_lshl_add_u64 v[82:83], s[0:1], 0, v[198:199]
	v_add_u32_e32 v94, 0xffffc000, v200
	v_ashrrev_i32_e32 v201, 31, v200
	v_cmp_gt_i32_e64 s[0:1], s46, v200
	v_add_co_u32_e32 v84, vcc, s46, v82
	s_nop 0
	v_cndmask_b32_e64 v95, 0, v201, s[0:1]
	v_cndmask_b32_e64 v94, v94, v200, s[0:1]
	v_mov_b32_e32 v152, s15
	v_mov_b32_e32 v153, s13
	v_mov_b32_e32 v154, s14
	v_mov_b32_e32 v155, s12
	v_addc_co_u32_e32 v85, vcc, 0, v83, vcc
	v_cndmask_b32_e64 v97, v152, v153, s[0:1]
	v_cndmask_b32_e64 v96, v154, v155, s[0:1]
	v_lshlrev_b64 v[94:95], 13, v[94:95]
	v_add_co_u32_e32 v82, vcc, s49, v82
	v_lshl_add_u64 v[94:95], v[96:97], 0, v[94:95]
	v_lshl_add_u64 v[146:147], v[94:95], 0, v[198:199]
	v_addc_co_u32_e32 v83, vcc, 0, v83, vcc
	global_load_dwordx4 v[86:89], v[84:85], off
	global_load_dwordx4 v[180:183], v[146:147], off
	global_load_dwordx4 v[186:189], v[82:83], off
	global_load_dwordx4 v[190:193], v[82:83], off offset:64
	global_load_dwordx4 v[194:197], v[82:83], off offset:512
	global_load_dwordx4 v[212:215], v[82:83], off offset:576
	v_lshl_add_u64 v[82:83], s[56:57], 0, v[198:199]
	global_load_dwordx4 v[216:219], v[82:83], off
	global_load_dwordx4 v[220:223], v[82:83], off offset:64
	global_load_dwordx4 v[224:227], v[82:83], off offset:512
	global_load_dwordx4 v[228:231], v[82:83], off offset:576
	global_load_dwordx4 v[232:235], v[146:147], off offset:64
	global_load_dwordx4 v[102:105], v[84:85], off offset:64
	global_load_dwordx4 v[94:97], v[84:85], off offset:512
	global_load_dwordx4 v[236:239], v[146:147], off offset:512
	global_load_dwordx4 v[240:243], v[146:147], off offset:576
	s_nop 0
	global_load_dwordx4 v[82:85], v[84:85], off offset:576
	v_or_b32_e32 v202, 16, v200
	v_add_u32_e32 v150, 0xffffc010, v200
	v_ashrrev_i32_e32 v203, 31, v202
	v_cmp_gt_i32_e32 vcc, s46, v202
	v_lshlrev_b64 v[146:147], 13, v[200:201]
	v_lshl_add_u64 v[146:147], s[66:67], 0, v[146:147]
	v_cndmask_b32_e32 v151, 0, v203, vcc
	v_cndmask_b32_e32 v150, v150, v202, vcc
	v_cndmask_b32_e32 v153, v152, v153, vcc
	v_cndmask_b32_e32 v152, v154, v155, vcc
	v_lshlrev_b64 v[150:151], 13, v[150:151]
	v_lshlrev_b64 v[148:149], 12, v[200:201]
	v_lshl_add_u64 v[204:205], v[146:147], 0, v[198:199]
	v_lshl_add_u64 v[146:147], v[152:153], 0, v[150:151]
	v_lshl_add_u64 v[148:149], s[88:89], 0, v[148:149]
	v_lshl_add_u64 v[146:147], v[146:147], 0, v[198:199]
	v_lshl_add_u64 v[244:245], v[178:179], 1, v[148:149]
	global_load_dwordx4 v[158:161], v[146:147], off
	global_load_dwordx4 v[154:157], v[146:147], off offset:64
	global_load_dwordx4 v[150:153], v[146:147], off offset:512
	s_nop 0
	global_load_dwordx4 v[146:149], v[146:147], off offset:576
	s_waitcnt vmcnt(0)
	v_pk_fma_f32 v[138:139], v[138:139], v[102:103], v[232:233]
	v_pk_fma_f32 v[144:145], v[144:145], v[88:89], v[182:183]
	v_pk_fma_f32 v[142:143], v[142:143], v[86:87], v[180:181]
	v_pk_add_f32 v[180:181], v[188:189], 1.0 op_sel_hi:[1,0]
	v_pk_add_f32 v[182:183], v[186:187], 1.0 op_sel_hi:[1,0]
	v_pk_add_f32 v[212:213], v[212:213], 1.0 op_sel_hi:[1,0]
	v_pk_add_f32 v[246:247], v[196:197], 1.0 op_sel_hi:[1,0]
	v_pk_add_f32 v[248:249], v[194:195], 1.0 op_sel_hi:[1,0]
	v_pk_mul_f32 v[194:195], v[218:219], v[180:181]
	v_pk_mul_f32 v[196:197], v[216:217], v[182:183]
	v_pk_mul_f32 v[180:181], v[228:229], v[212:213]
	v_mul_f32_e32 v212, v143, v143
	global_store_dwordx4 v[204:205], v[142:145], off
	v_fmac_f32_e32 v212, v142, v142
	v_pk_add_f32 v[188:189], v[190:191], 1.0 op_sel_hi:[1,0]
	v_pk_mul_f32 v[142:143], v[196:197], v[142:143]
	v_fmac_f32_e32 v212, v144, v144
	v_cvt_pk_bf16_f32 v142, v142, v143
	v_pk_add_f32 v[186:187], v[192:193], 1.0 op_sel_hi:[1,0]
	v_pk_mul_f32 v[192:193], v[220:221], v[188:189]
	v_fmac_f32_e32 v212, v145, v145
	v_pk_mul_f32 v[144:145], v[194:195], v[144:145]
	v_pk_fma_f32 v[140:141], v[140:141], v[104:105], v[234:235]
	v_cvt_pk_bf16_f32 v143, v144, v145
	global_store_dwordx2 v[244:245], v[142:143], off
	v_mul_f32_e32 v142, v139, v139
	global_store_dwordx4 v[204:205], v[138:141], off offset:64
	v_fmac_f32_e32 v142, v138, v138
	v_pk_mul_f32 v[190:191], v[222:223], v[186:187]
	v_pk_mul_f32 v[138:139], v[192:193], v[138:139]
	v_fmac_f32_e32 v142, v140, v140
	v_cvt_pk_bf16_f32 v138, v138, v139
	v_pk_fma_f32 v[134:135], v[134:135], v[94:95], v[236:237]
	v_fmac_f32_e32 v142, v141, v141
	v_pk_mul_f32 v[140:141], v[190:191], v[140:141]
	v_pk_fma_f32 v[136:137], v[136:137], v[96:97], v[238:239]
	v_cvt_pk_bf16_f32 v139, v140, v141
	global_store_dwordx2 v[244:245], v[138:139], off offset:32
	v_mul_f32_e32 v138, v135, v135
	v_fmac_f32_e32 v138, v134, v134
	v_pk_mul_f32 v[188:189], v[224:225], v[248:249]
	v_fmac_f32_e32 v138, v136, v136
	v_add_f32_e32 v142, v212, v142
	global_store_dwordx4 v[204:205], v[134:137], off offset:512
	v_fmac_f32_e32 v138, v137, v137
	v_add_f32_e32 v139, v142, v138
	v_pk_mul_f32 v[134:135], v[188:189], v[134:135]
	v_pk_mul_f32 v[186:187], v[226:227], v[246:247]
	v_cvt_pk_bf16_f32 v138, v134, v135
	v_pk_fma_f32 v[134:135], v[132:133], v[84:85], v[242:243]
	v_pk_fma_f32 v[132:133], v[130:131], v[82:83], v[240:241]
	v_xor_b32_e32 v131, 16, v211
	v_mul_f32_e32 v130, v133, v133
	v_fmac_f32_e32 v130, v132, v132
	v_fmac_f32_e32 v130, v134, v134
	v_fmac_f32_e32 v130, v135, v135
	v_add_f32_e32 v130, v139, v130
	v_and_b32_e32 v139, 64, v211
	v_add_u32_e32 v140, 64, v139
	v_cmp_lt_i32_e32 vcc, v131, v140
	v_pk_add_f32 v[214:215], v[214:215], 1.0 op_sel_hi:[1,0]
	v_pk_mul_f32 v[136:137], v[186:187], v[136:137]
	v_cndmask_b32_e32 v131, v211, v131, vcc
	v_lshlrev_b32_e32 v212, 2, v131
	ds_bpermute_b32 v131, v212, v130
	v_cvt_pk_bf16_f32 v139, v136, v137
	v_pk_mul_f32 v[182:183], v[230:231], v[214:215]
	global_store_dwordx2 v[244:245], v[138:139], off offset:256
	global_store_dwordx4 v[204:205], v[132:135], off offset:576
	s_waitcnt lgkmcnt(0)
	v_add_f32_e32 v130, v130, v131
	v_xor_b32_e32 v131, 32, v211
	v_cmp_lt_i32_e32 vcc, v131, v140
	v_pk_mul_f32 v[132:133], v[180:181], v[132:133]
	v_pk_mul_f32 v[134:135], v[182:183], v[134:135]
	v_cndmask_b32_e32 v131, v211, v131, vcc
	v_lshlrev_b32_e32 v213, 2, v131
	ds_bpermute_b32 v131, v213, v130
	v_cvt_pk_bf16_f32 v132, v132, v133
	v_cvt_pk_bf16_f32 v133, v134, v135
	global_store_dwordx2 v[244:245], v[132:133], off offset:288
	s_and_saveexec_b64 s[0:1], s[4:5]
	s_cbranch_execz .LBB0_699
	v_lshl_add_u64 v[132:133], v[200:201], 2, s[18:19]
	s_waitcnt lgkmcnt(0)
	v_add_f32_e32 v130, v130, v131
	global_atomic_add_f32 v[132:133], v130, off

.LBB0_803:
	s_add_u32 s4, s12, 0xfff80080
	s_addc_u32 s20, s13, -1
	s_add_i32 s58, 0, 0x10000
	v_add_u32_e32 v140, s58, v161
	ds_read_b128 v[128:131], v140
	ds_read_b128 v[132:135], v140 offset:1024
	ds_read_b128 v[136:139], v140 offset:2048
	ds_read_b128 v[140:143], v140 offset:3072
	s_cmp_eq_u32 s57, 28
	s_cselect_b32 s25, s15, s20
	s_cselect_b32 s24, s45, s4
	s_cselect_b32 s21, s3, s56
	s_cselect_b32 s20, s52, s53
	v_lshl_add_u64 v[158:159], s[12:13], 0, v[150:151]
	s_add_i32 m0, s16, 0xc000
	ds_read_b128 v[154:157], v163
	ds_read_b128 v[164:167], v163 offset:1024
	ds_read_b128 v[168:171], v163 offset:2048
	ds_read_b128 v[172:175], v163 offset:3072
	ds_read_b128 v[176:179], v163 offset:4096
	ds_read_b128 v[180:183], v163 offset:5120
	ds_read_b128 v[196:199], v163 offset:6144
	ds_read_b128 v[200:203], v163 offset:7168
	v_add_u32_e32 v216, 0x14000, v161
	ds_read_b128 v[204:207], v216
	ds_read_b128 v[208:211], v216 offset:1024
	ds_read_b128 v[212:215], v216 offset:2048
	ds_read_b128 v[216:219], v216 offset:3072
	global_load_lds_dwordx4 v150, s[12:13]
	v_lshl_add_u64 v[158:159], s[12:13], 0, v[152:153]
	s_add_i32 m0, s16, 0xe000
	s_nop 0
	global_load_lds_dwordx4 v152, s[12:13]
	s_waitcnt vmcnt(8)
	s_waitcnt lgkmcnt(0)
	s_barrier
	s_setprio 1
	v_mfma_f32_16x16x32_bf16 v[124:127], v[128:131], v[154:157], v[124:127]
	v_mfma_f32_16x16x32_bf16 v[120:123], v[136:139], v[154:157], v[120:123]
	v_mfma_f32_16x16x32_bf16 v[108:111], v[128:131], v[168:171], v[108:111]
	v_mfma_f32_16x16x32_bf16 v[104:107], v[136:139], v[168:171], v[104:107]
	v_mfma_f32_16x16x32_bf16 v[92:95], v[128:131], v[176:179], v[92:95]
	v_mfma_f32_16x16x32_bf16 v[88:91], v[136:139], v[176:179], v[88:91]
	v_mfma_f32_16x16x32_bf16 v[76:79], v[128:131], v[196:199], v[76:79]
	v_mfma_f32_16x16x32_bf16 v[72:75], v[136:139], v[196:199], v[72:75]
	v_mfma_f32_16x16x32_bf16 v[124:127], v[132:135], v[164:167], v[124:127]
	v_mfma_f32_16x16x32_bf16 v[120:123], v[140:143], v[164:167], v[120:123]
	v_mfma_f32_16x16x32_bf16 v[108:111], v[132:135], v[172:175], v[108:111]
	v_mfma_f32_16x16x32_bf16 v[104:107], v[140:143], v[172:175], v[104:107]
	v_mfma_f32_16x16x32_bf16 v[92:95], v[132:135], v[180:183], v[92:95]
	v_mfma_f32_16x16x32_bf16 v[88:91], v[140:143], v[180:183], v[88:91]
	v_mfma_f32_16x16x32_bf16 v[76:79], v[132:135], v[200:203], v[76:79]
	v_mfma_f32_16x16x32_bf16 v[72:75], v[140:143], v[200:203], v[72:75]
	v_mfma_f32_16x16x32_bf16 v[116:119], v[204:207], v[154:157], v[116:119]
	v_mfma_f32_16x16x32_bf16 v[112:115], v[212:215], v[154:157], v[112:115]
	v_mfma_f32_16x16x32_bf16 v[100:103], v[204:207], v[168:171], v[100:103]
	v_mfma_f32_16x16x32_bf16 v[96:99], v[212:215], v[168:171], v[96:99]
	v_mfma_f32_16x16x32_bf16 v[84:87], v[204:207], v[176:179], v[84:87]
	v_mfma_f32_16x16x32_bf16 v[80:83], v[212:215], v[176:179], v[80:83]
	v_mfma_f32_16x16x32_bf16 v[68:71], v[204:207], v[196:199], v[68:71]
	v_mfma_f32_16x16x32_bf16 v[64:67], v[212:215], v[196:199], v[64:67]
	v_mfma_f32_16x16x32_bf16 v[116:119], v[208:211], v[164:167], v[116:119]
	v_mfma_f32_16x16x32_bf16 v[112:115], v[216:219], v[164:167], v[112:115]
	v_mfma_f32_16x16x32_bf16 v[100:103], v[208:211], v[172:175], v[100:103]
	v_mfma_f32_16x16x32_bf16 v[96:99], v[216:219], v[172:175], v[96:99]
	v_mfma_f32_16x16x32_bf16 v[84:87], v[208:211], v[180:183], v[84:87]
	v_mfma_f32_16x16x32_bf16 v[80:83], v[216:219], v[180:183], v[80:83]
	v_mfma_f32_16x16x32_bf16 v[68:71], v[208:211], v[200:203], v[68:71]
	v_mfma_f32_16x16x32_bf16 v[64:67], v[216:219], v[200:203], v[64:67]
	s_setprio 0
	s_barrier
	s_add_i32 s4, 0, 0x14000
	s_add_i32 s58, s58, s27
	v_lshl_add_u64 v[158:159], s[20:21], 0, v[186:187]
	s_mov_b32 m0, s58
	v_lshl_add_u64 v[220:221], s[20:21], 0, v[144:145]
	global_load_lds_dwordx4 v186, s[20:21]
	s_add_i32 m0, s58, 0x2000
	s_nop 0
	global_load_lds_dwordx4 v144, s[20:21]
	s_mov_b32 m0, s16
	v_lshl_add_u64 v[222:223], s[24:25], 0, v[148:149]
	ds_read_b128 v[154:157], v163 offset:16384
	ds_read_b128 v[164:167], v163 offset:17408
	ds_read_b128 v[168:171], v163 offset:18432
	ds_read_b128 v[172:175], v163 offset:19456
	ds_read_b128 v[176:179], v163 offset:20480
	ds_read_b128 v[180:183], v163 offset:21504
	ds_read_b128 v[196:199], v163 offset:22528
	ds_read_b128 v[200:203], v163 offset:23552
	global_load_lds_dwordx4 v148, s[24:25]
	v_lshl_add_u64 v[224:225], s[24:25], 0, v[146:147]
	s_mov_b32 m0, s17
	s_nop 0
	global_load_lds_dwordx4 v146, s[24:25]
	s_waitcnt vmcnt(6)
	s_waitcnt lgkmcnt(0)
	s_barrier
	s_setprio 1
	v_mfma_f32_16x16x32_bf16 v[60:63], v[128:131], v[154:157], v[60:63]
	v_mfma_f32_16x16x32_bf16 v[56:59], v[136:139], v[154:157], v[56:59]
	v_mfma_f32_16x16x32_bf16 v[44:47], v[128:131], v[168:171], v[44:47]
	v_mfma_f32_16x16x32_bf16 v[40:43], v[136:139], v[168:171], v[40:43]
	v_mfma_f32_16x16x32_bf16 v[28:31], v[128:131], v[176:179], v[28:31]
	v_mfma_f32_16x16x32_bf16 v[24:27], v[136:139], v[176:179], v[24:27]
	v_mfma_f32_16x16x32_bf16 v[12:15], v[128:131], v[196:199], v[12:15]
	v_mfma_f32_16x16x32_bf16 v[8:11], v[136:139], v[196:199], v[8:11]
	v_mfma_f32_16x16x32_bf16 v[60:63], v[132:135], v[164:167], v[60:63]
	v_mfma_f32_16x16x32_bf16 v[56:59], v[140:143], v[164:167], v[56:59]
	v_mfma_f32_16x16x32_bf16 v[44:47], v[132:135], v[172:175], v[44:47]
	v_mfma_f32_16x16x32_bf16 v[40:43], v[140:143], v[172:175], v[40:43]
	v_mfma_f32_16x16x32_bf16 v[28:31], v[132:135], v[180:183], v[28:31]
	v_mfma_f32_16x16x32_bf16 v[24:27], v[140:143], v[180:183], v[24:27]
	v_mfma_f32_16x16x32_bf16 v[12:15], v[132:135], v[200:203], v[12:15]
	v_mfma_f32_16x16x32_bf16 v[8:11], v[140:143], v[200:203], v[8:11]
	v_mfma_f32_16x16x32_bf16 v[52:55], v[204:207], v[154:157], v[52:55]
	v_mfma_f32_16x16x32_bf16 v[48:51], v[212:215], v[154:157], v[48:51]
	v_mfma_f32_16x16x32_bf16 v[36:39], v[204:207], v[168:171], v[36:39]
	v_mfma_f32_16x16x32_bf16 v[32:35], v[212:215], v[168:171], v[32:35]
	v_mfma_f32_16x16x32_bf16 v[20:23], v[204:207], v[176:179], v[20:23]
	v_mfma_f32_16x16x32_bf16 v[16:19], v[212:215], v[176:179], v[16:19]
	v_mfma_f32_16x16x32_bf16 v[4:7], v[204:207], v[196:199], v[4:7]
	v_mfma_f32_16x16x32_bf16 v[0:3], v[212:215], v[196:199], v[0:3]
	v_mfma_f32_16x16x32_bf16 v[52:55], v[208:211], v[164:167], v[52:55]
	v_mfma_f32_16x16x32_bf16 v[48:51], v[216:219], v[164:167], v[48:51]
	v_mfma_f32_16x16x32_bf16 v[36:39], v[208:211], v[172:175], v[36:39]
	v_mfma_f32_16x16x32_bf16 v[32:35], v[216:219], v[172:175], v[32:35]
	v_mfma_f32_16x16x32_bf16 v[20:23], v[208:211], v[180:183], v[20:23]
	v_mfma_f32_16x16x32_bf16 v[16:19], v[216:219], v[180:183], v[16:19]
	v_mfma_f32_16x16x32_bf16 v[4:7], v[208:211], v[200:203], v[4:7]
	v_mfma_f32_16x16x32_bf16 v[0:3], v[216:219], v[200:203], v[0:3]
	s_setprio 0
	s_barrier
	s_add_u32 s58, s20, 0x80000
	s_addc_u32 s59, s21, 0
	s_add_i32 s4, s4, s27
	s_mov_b32 m0, s4
	s_nop 0
	global_load_lds_dwordx4 v186, s[58:59]
	s_add_i32 m0, s4, 0x2000
	s_nop 0
	global_load_lds_dwordx4 v144, s[58:59]
	s_add_i32 s4, 0, 0x18000
	v_add_u32_e32 v140, s4, v161
	ds_read_b128 v[128:131], v140
	ds_read_b128 v[132:135], v140 offset:1024
	ds_read_b128 v[136:139], v140 offset:2048
	ds_read_b128 v[140:143], v140 offset:3072
	s_add_u32 s24, s24, 0x80000
	s_addc_u32 s25, s25, 0
	s_mov_b32 m0, s30
	ds_read_b128 v[154:157], v163 offset:32768
	ds_read_b128 v[164:167], v163 offset:33792
	ds_read_b128 v[168:171], v163 offset:34816
	ds_read_b128 v[172:175], v163 offset:35840
	ds_read_b128 v[176:179], v163 offset:36864
	ds_read_b128 v[180:183], v163 offset:37888
	ds_read_b128 v[196:199], v163 offset:38912
	ds_read_b128 v[200:203], v163 offset:39936
	v_add_u32_e32 v216, 0x1c000, v161
	ds_read_b128 v[204:207], v216
	ds_read_b128 v[208:211], v216 offset:1024
	ds_read_b128 v[212:215], v216 offset:2048
	ds_read_b128 v[216:219], v216 offset:3072
	global_load_lds_dwordx4 v148, s[24:25]
	s_mov_b32 m0, s31
	s_nop 0
	global_load_lds_dwordx4 v146, s[24:25]
	s_waitcnt vmcnt(8)
	s_waitcnt lgkmcnt(0)
	s_barrier
	s_setprio 1
	v_mfma_f32_16x16x32_bf16 v[124:127], v[128:131], v[154:157], v[124:127]
	v_mfma_f32_16x16x32_bf16 v[120:123], v[136:139], v[154:157], v[120:123]
	v_mfma_f32_16x16x32_bf16 v[108:111], v[128:131], v[168:171], v[108:111]
	v_mfma_f32_16x16x32_bf16 v[104:107], v[136:139], v[168:171], v[104:107]
	v_mfma_f32_16x16x32_bf16 v[92:95], v[128:131], v[176:179], v[92:95]
	v_mfma_f32_16x16x32_bf16 v[88:91], v[136:139], v[176:179], v[88:91]
	v_mfma_f32_16x16x32_bf16 v[76:79], v[128:131], v[196:199], v[76:79]
	v_mfma_f32_16x16x32_bf16 v[72:75], v[136:139], v[196:199], v[72:75]
	v_mfma_f32_16x16x32_bf16 v[124:127], v[132:135], v[164:167], v[124:127]
	v_mfma_f32_16x16x32_bf16 v[120:123], v[140:143], v[164:167], v[120:123]
	v_mfma_f32_16x16x32_bf16 v[108:111], v[132:135], v[172:175], v[108:111]
	v_mfma_f32_16x16x32_bf16 v[104:107], v[140:143], v[172:175], v[104:107]
	v_mfma_f32_16x16x32_bf16 v[92:95], v[132:135], v[180:183], v[92:95]
	v_mfma_f32_16x16x32_bf16 v[88:91], v[140:143], v[180:183], v[88:91]
	v_mfma_f32_16x16x32_bf16 v[76:79], v[132:135], v[200:203], v[76:79]
	v_mfma_f32_16x16x32_bf16 v[72:75], v[140:143], v[200:203], v[72:75]
	v_mfma_f32_16x16x32_bf16 v[116:119], v[204:207], v[154:157], v[116:119]
	v_mfma_f32_16x16x32_bf16 v[112:115], v[212:215], v[154:157], v[112:115]
	v_mfma_f32_16x16x32_bf16 v[100:103], v[204:207], v[168:171], v[100:103]
	v_mfma_f32_16x16x32_bf16 v[96:99], v[212:215], v[168:171], v[96:99]
	v_mfma_f32_16x16x32_bf16 v[84:87], v[204:207], v[176:179], v[84:87]
	v_mfma_f32_16x16x32_bf16 v[80:83], v[212:215], v[176:179], v[80:83]
	v_mfma_f32_16x16x32_bf16 v[68:71], v[204:207], v[196:199], v[68:71]
	v_mfma_f32_16x16x32_bf16 v[64:67], v[212:215], v[196:199], v[64:67]
	v_mfma_f32_16x16x32_bf16 v[116:119], v[208:211], v[164:167], v[116:119]
	v_mfma_f32_16x16x32_bf16 v[112:115], v[216:219], v[164:167], v[112:115]
	v_mfma_f32_16x16x32_bf16 v[100:103], v[208:211], v[172:175], v[100:103]
	v_mfma_f32_16x16x32_bf16 v[96:99], v[216:219], v[172:175], v[96:99]
	v_mfma_f32_16x16x32_bf16 v[84:87], v[208:211], v[180:183], v[84:87]
	v_mfma_f32_16x16x32_bf16 v[80:83], v[216:219], v[180:183], v[80:83]
	v_mfma_f32_16x16x32_bf16 v[68:71], v[208:211], v[200:203], v[68:71]
	v_mfma_f32_16x16x32_bf16 v[64:67], v[216:219], v[200:203], v[64:67]
	s_setprio 0
	s_barrier
	s_add_i32 s24, 0, 0x1c000
	s_add_i32 s4, s4, s27
	v_lshl_add_u64 v[158:159], v[158:159], 0, s[0:1]
	s_mov_b32 m0, s4
	global_load_lds_dwordx4 v[158:159], off
	v_lshl_add_u64 v[158:159], v[220:221], 0, s[0:1]
	s_add_i32 m0, s4, 0x2000
	s_nop 0
	global_load_lds_dwordx4 v[158:159], off
	s_mov_b32 m0, s38
	v_lshl_add_u64 v[158:159], v[222:223], 0, s[0:1]
	ds_read_b128 v[154:157], v163 offset:49152
	ds_read_b128 v[164:167], v163 offset:50176
	ds_read_b128 v[168:171], v163 offset:51200
	ds_read_b128 v[172:175], v163 offset:52224
	ds_read_b128 v[176:179], v163 offset:53248
	ds_read_b128 v[180:183], v163 offset:54272
	ds_read_b128 v[196:199], v163 offset:55296
	ds_read_b128 v[200:203], v163 offset:56320
	global_load_lds_dwordx4 v[158:159], off
	v_lshl_add_u64 v[158:159], v[224:225], 0, s[0:1]
	s_mov_b32 m0, s39
	s_nop 0
	global_load_lds_dwordx4 v[158:159], off
	s_add_u32 s20, s20, 0x80080
	s_addc_u32 s21, s21, 0
	s_add_i32 s4, s24, s27
	s_mov_b32 m0, s4
	s_nop 0
	global_load_lds_dwordx4 v186, s[20:21]
	s_add_i32 m0, s4, 0x2000
	s_nop 0
	global_load_lds_dwordx4 v144, s[20:21]
	s_waitcnt vmcnt(8)
	s_waitcnt lgkmcnt(0)
	s_barrier
	s_setprio 1
	v_mfma_f32_16x16x32_bf16 v[60:63], v[128:131], v[154:157], v[60:63]
	v_mfma_f32_16x16x32_bf16 v[56:59], v[136:139], v[154:157], v[56:59]
	v_mfma_f32_16x16x32_bf16 v[44:47], v[128:131], v[168:171], v[44:47]
	v_mfma_f32_16x16x32_bf16 v[40:43], v[136:139], v[168:171], v[40:43]
	v_mfma_f32_16x16x32_bf16 v[28:31], v[128:131], v[176:179], v[28:31]
	v_mfma_f32_16x16x32_bf16 v[24:27], v[136:139], v[176:179], v[24:27]
	v_mfma_f32_16x16x32_bf16 v[12:15], v[128:131], v[196:199], v[12:15]
	v_mfma_f32_16x16x32_bf16 v[8:11], v[136:139], v[196:199], v[8:11]
	v_mfma_f32_16x16x32_bf16 v[60:63], v[132:135], v[164:167], v[60:63]
	v_mfma_f32_16x16x32_bf16 v[56:59], v[140:143], v[164:167], v[56:59]
	v_mfma_f32_16x16x32_bf16 v[44:47], v[132:135], v[172:175], v[44:47]
	v_mfma_f32_16x16x32_bf16 v[40:43], v[140:143], v[172:175], v[40:43]
	v_mfma_f32_16x16x32_bf16 v[28:31], v[132:135], v[180:183], v[28:31]
	v_mfma_f32_16x16x32_bf16 v[24:27], v[140:143], v[180:183], v[24:27]
	v_mfma_f32_16x16x32_bf16 v[12:15], v[132:135], v[200:203], v[12:15]
	v_mfma_f32_16x16x32_bf16 v[8:11], v[140:143], v[200:203], v[8:11]
	v_mfma_f32_16x16x32_bf16 v[52:55], v[204:207], v[154:157], v[52:55]
	v_mfma_f32_16x16x32_bf16 v[48:51], v[212:215], v[154:157], v[48:51]
	v_mfma_f32_16x16x32_bf16 v[36:39], v[204:207], v[168:171], v[36:39]
	v_mfma_f32_16x16x32_bf16 v[32:35], v[212:215], v[168:171], v[32:35]
	v_mfma_f32_16x16x32_bf16 v[20:23], v[204:207], v[176:179], v[20:23]
	v_mfma_f32_16x16x32_bf16 v[16:19], v[212:215], v[176:179], v[16:19]
	v_mfma_f32_16x16x32_bf16 v[4:7], v[204:207], v[196:199], v[4:7]
	v_mfma_f32_16x16x32_bf16 v[0:3], v[212:215], v[196:199], v[0:3]
	v_mfma_f32_16x16x32_bf16 v[52:55], v[208:211], v[164:167], v[52:55]
	v_mfma_f32_16x16x32_bf16 v[48:51], v[216:219], v[164:167], v[48:51]
	v_mfma_f32_16x16x32_bf16 v[36:39], v[208:211], v[172:175], v[36:39]
	v_mfma_f32_16x16x32_bf16 v[32:35], v[216:219], v[172:175], v[32:35]
	v_mfma_f32_16x16x32_bf16 v[20:23], v[208:211], v[180:183], v[20:23]
	v_mfma_f32_16x16x32_bf16 v[16:19], v[216:219], v[180:183], v[16:19]
	v_mfma_f32_16x16x32_bf16 v[4:7], v[208:211], v[200:203], v[4:7]
	v_mfma_f32_16x16x32_bf16 v[0:3], v[216:219], v[200:203], v[0:3]
	s_setprio 0
	s_add_i32 s57, s57, 2
	s_add_u32 s12, s12, 0x100
	s_addc_u32 s13, s13, 0
	s_add_u32 s53, s53, 0x100
	s_addc_u32 s56, s56, 0
	s_cmp_gt_u32 s57, 29
	s_barrier
	s_cbranch_scc0 .LBB0_803
	s_lshl_b32 s3, s44, 8
	s_add_i32 s4, s3, s35
	v_add_u32_e32 v156, s3, v160
	s_min_i32 s3, s4, 0x4000
	v_add_u32_e32 v128, s35, v156
	s_ashr_i32 s12, s3, 11
	v_ashrrev_i32_e32 v129, 31, v128
	s_ashr_i32 s13, s12, 31
	v_lshl_add_u64 v[128:129], v[128:129], 2, s[48:49]
	s_lshl_b64 s[12:13], s[12:13], 15
	global_load_dword v167, v[128:129], off
	global_load_dword v170, v[128:129], off offset:64
	global_load_dword v171, v[128:129], off offset:128
	global_load_dword v172, v[128:129], off offset:192
	global_load_dword v173, v[128:129], off offset:512
	global_load_dword v166, v[128:129], off offset:576
	global_load_dword v165, v[128:129], off offset:640
	v_lshl_or_b32 v154, s41, 8, v162
	s_add_u32 s12, s37, s12
	s_addc_u32 s13, s6, s13
	v_ashrrev_i32_e32 v155, 31, v154
	global_load_dword v164, v[128:129], off offset:704
	v_lshl_add_u64 v[128:129], v[154:155], 2, s[12:13]
	global_load_dwordx4 v[140:143], v[128:129], off
	global_load_dwordx4 v[136:139], v[128:129], off offset:16
	global_load_dwordx4 v[132:135], v[128:129], off offset:512
	s_nop 0
	global_load_dwordx4 v[128:131], v[128:129], off offset:528
	v_ashrrev_i32_e32 v157, 31, v156
	v_lshlrev_b64 v[158:159], 1, v[154:155]
	v_lshlrev_b64 v[154:155], 14, v[156:157]
	v_lshl_add_u64 v[154:155], s[54:55], 0, v[154:155]
	v_lshl_add_u64 v[154:155], v[154:155], 0, v[158:159]
	v_or_b32_e32 v168, 16, v156
	v_ashrrev_i32_e32 v169, 31, v168
	s_mov_b32 s3, 0x200000
	s_mov_b64 s[12:13], 0x200000
	s_mov_b32 s41, s2
	s_mov_b32 s44, s14
	s_mov_b64 s[20:21], s[28:29]
	s_waitcnt vmcnt(0)
	s_nop 0
	v_fmamk_f32 v157, v167, 0x3a000000, v229
	v_mul_f32_e32 v167, 0x4b800000, v157
	v_cmp_gt_f32_e32 vcc, s5, v157
	s_nop 1
	v_cndmask_b32_e32 v157, v157, v167, vcc
	v_rsq_f32_e32 v157, v157
	v_fmamk_f32 v167, v170, 0x3a000000, v229
	v_mul_f32_e32 v170, 0x45800000, v157
	v_cndmask_b32_e32 v170, v157, v170, vcc
	v_pk_fma_f32 v[124:125], v[124:125], v[170:171], v[140:141] op_sel_hi:[1,0,1]
	v_pk_fma_f32 v[112:113], v[112:113], v[170:171], v[128:129] op_sel_hi:[1,0,1]
	v_pk_fma_f32 v[126:127], v[126:127], v[170:171], v[142:143] op_sel_hi:[1,0,1]
	v_pk_fma_f32 v[122:123], v[122:123], v[170:171], v[138:139] op_sel_hi:[1,0,1]
	v_pk_fma_f32 v[120:121], v[120:121], v[170:171], v[136:137] op_sel_hi:[1,0,1]
	v_pk_fma_f32 v[116:117], v[116:117], v[170:171], v[132:133] op_sel_hi:[1,0,1]
	v_pk_fma_f32 v[114:115], v[114:115], v[170:171], v[130:131] op_sel_hi:[1,0,1]
	v_max_f32_e32 v124, 0, v124
	v_max_f32_e32 v125, 0, v125
	v_max_f32_e32 v112, 0, v112
	v_pk_fma_f32 v[118:119], v[118:119], v[170:171], v[134:135] op_sel_hi:[1,0,1]
	v_max_f32_e32 v120, 0, v120
	v_max_f32_e32 v121, 0, v121
	v_max_f32_e32 v126, 0, v126
	v_max_f32_e32 v122, 0, v122
	v_max_f32_e32 v127, 0, v127
	v_max_f32_e32 v123, 0, v123
	v_max_f32_e32 v116, 0, v116
	v_max_f32_e32 v117, 0, v117
	v_max_f32_e32 v113, 0, v113
	v_max_f32_e32 v114, 0, v114
	v_max_f32_e32 v115, 0, v115
	v_mul_f32_e32 v124, v124, v124
	v_mul_f32_e32 v125, v125, v125
	v_mul_f32_e32 v157, v112, v112
	v_cvt_pk_bf16_f32 v112, v124, v125
	v_mul_f32_e32 v174, 0x4b800000, v167
	v_max_f32_e32 v118, 0, v118
	v_max_f32_e32 v119, 0, v119
	v_mul_f32_e32 v120, v120, v120
	v_mul_f32_e32 v121, v121, v121
	v_mul_f32_e32 v126, v126, v126
	v_mul_f32_e32 v122, v122, v122
	v_mul_f32_e32 v127, v127, v127
	v_mul_f32_e32 v123, v123, v123
	v_mul_f32_e32 v116, v116, v116
	v_mul_f32_e32 v117, v117, v117
	v_mul_f32_e32 v170, v113, v113
	v_mul_f32_e32 v175, v114, v114
	v_mul_f32_e32 v176, v115, v115
	v_cvt_pk_bf16_f32 v113, v126, v127
	v_cvt_pk_bf16_f32 v114, v120, v121
	v_cvt_pk_bf16_f32 v115, v122, v123
	global_store_dwordx4 v[154:155], v[112:115], off
	v_cmp_gt_f32_e32 vcc, s5, v167
	v_mul_f32_e32 v118, v118, v118
	v_cvt_pk_bf16_f32 v112, v116, v117
	v_mul_f32_e32 v119, v119, v119
	v_cvt_pk_bf16_f32 v113, v118, v119
	v_cvt_pk_bf16_f32 v114, v157, v170
	v_cvt_pk_bf16_f32 v115, v175, v176
	global_store_dwordx4 v[154:155], v[112:115], off offset:256
	s_nop 1
	v_cndmask_b32_e32 v112, v167, v174, vcc
	v_rsq_f32_e32 v114, v112
	v_lshlrev_b64 v[112:113], 14, v[168:169]
	v_lshl_add_u64 v[112:113], s[54:55], 0, v[112:113]
	v_lshl_add_u64 v[112:113], v[112:113], 0, v[158:159]
	v_mul_f32_e32 v115, 0x45800000, v114
	v_cndmask_b32_e32 v114, v114, v115, vcc
	v_pk_fma_f32 v[104:105], v[104:105], v[114:115], v[136:137] op_sel_hi:[1,0,1]
	v_pk_fma_f32 v[108:109], v[108:109], v[114:115], v[140:141] op_sel_hi:[1,0,1]
	v_pk_fma_f32 v[106:107], v[106:107], v[114:115], v[138:139] op_sel_hi:[1,0,1]
	v_max_f32_e32 v104, 0, v104
	v_pk_fma_f32 v[110:111], v[110:111], v[114:115], v[142:143] op_sel_hi:[1,0,1]
	v_mul_f32_e32 v115, v104, v104
	v_max_f32_e32 v104, 0, v109
	v_max_f32_e32 v105, 0, v105
	v_max_f32_e32 v106, 0, v106
	v_max_f32_e32 v108, 0, v108
	v_mul_f32_e32 v104, v104, v104
	v_mul_f32_e32 v109, v105, v105
	v_max_f32_e32 v105, 0, v110
	v_mul_f32_e32 v110, v106, v106
	v_max_f32_e32 v106, 0, v111
	v_max_f32_e32 v107, 0, v107
	v_pk_fma_f32 v[98:99], v[98:99], v[114:115], v[130:131] op_sel_hi:[1,0,1]
	v_pk_fma_f32 v[96:97], v[96:97], v[114:115], v[128:129] op_sel_hi:[1,0,1]
	v_mul_f32_e32 v108, v108, v108
	v_mul_f32_e32 v105, v105, v105
	v_mul_f32_e32 v106, v106, v106
	v_mul_f32_e32 v107, v107, v107
	v_cvt_pk_bf16_f32 v104, v108, v104
	v_pk_fma_f32 v[102:103], v[102:103], v[114:115], v[134:135] op_sel_hi:[1,0,1]
	v_pk_fma_f32 v[100:101], v[100:101], v[114:115], v[132:133] op_sel_hi:[1,0,1]
	v_max_f32_e32 v96, 0, v96
	v_max_f32_e32 v97, 0, v97
	v_max_f32_e32 v98, 0, v98
	v_cvt_pk_bf16_f32 v105, v105, v106
	v_cvt_pk_bf16_f32 v106, v115, v109
	v_cvt_pk_bf16_f32 v107, v110, v107
	global_store_dwordx4 v[112:113], v[104:107], off
	v_max_f32_e32 v100, 0, v100
	v_max_f32_e32 v99, 0, v99
	v_mul_f32_e32 v104, v96, v96
	v_max_f32_e32 v96, 0, v101
	v_mul_f32_e32 v101, v97, v97
	v_max_f32_e32 v97, 0, v102
	v_mul_f32_e32 v102, v98, v98
	v_max_f32_e32 v98, 0, v103
	v_mul_f32_e32 v96, v96, v96
	v_mul_f32_e32 v97, v97, v97
	v_mul_f32_e32 v98, v98, v98
	v_mul_f32_e32 v100, v100, v100
	v_mul_f32_e32 v99, v99, v99
	v_cvt_pk_bf16_f32 v96, v100, v96
	v_cvt_pk_bf16_f32 v97, v97, v98
	v_cvt_pk_bf16_f32 v98, v104, v101
	v_cvt_pk_bf16_f32 v99, v102, v99
	global_store_dwordx4 v[112:113], v[96:99], off offset:256
	s_nop 1
	v_fmamk_f32 v98, v171, 0x3a000000, v229
	v_mul_f32_e32 v99, 0x4b800000, v98
	v_cmp_gt_f32_e32 vcc, s5, v98
	v_or_b32_e32 v96, 32, v156
	v_ashrrev_i32_e32 v97, 31, v96
	v_cndmask_b32_e32 v98, v98, v99, vcc
	v_rsq_f32_e32 v98, v98
	v_lshlrev_b64 v[96:97], 14, v[96:97]
	v_lshl_add_u64 v[96:97], s[54:55], 0, v[96:97]
	v_lshl_add_u64 v[96:97], v[96:97], 0, v[158:159]
	v_mul_f32_e32 v99, 0x45800000, v98
	v_cndmask_b32_e32 v98, v98, v99, vcc
	v_pk_fma_f32 v[88:89], v[88:89], v[98:99], v[136:137] op_sel_hi:[1,0,1]
	v_pk_fma_f32 v[92:93], v[92:93], v[98:99], v[140:141] op_sel_hi:[1,0,1]
	v_pk_fma_f32 v[90:91], v[90:91], v[98:99], v[138:139] op_sel_hi:[1,0,1]
	v_max_f32_e32 v88, 0, v88
	v_pk_fma_f32 v[94:95], v[94:95], v[98:99], v[142:143] op_sel_hi:[1,0,1]
	v_mul_f32_e32 v99, v88, v88
	v_max_f32_e32 v88, 0, v93
	v_max_f32_e32 v89, 0, v89
	v_max_f32_e32 v90, 0, v90
	v_max_f32_e32 v92, 0, v92
	v_mul_f32_e32 v88, v88, v88
	v_mul_f32_e32 v93, v89, v89
	v_max_f32_e32 v89, 0, v94
	v_mul_f32_e32 v94, v90, v90
	v_max_f32_e32 v90, 0, v95
	v_max_f32_e32 v91, 0, v91
	v_pk_fma_f32 v[82:83], v[82:83], v[98:99], v[130:131] op_sel_hi:[1,0,1]
	v_pk_fma_f32 v[80:81], v[80:81], v[98:99], v[128:129] op_sel_hi:[1,0,1]
	v_mul_f32_e32 v92, v92, v92
	v_mul_f32_e32 v89, v89, v89
	v_mul_f32_e32 v90, v90, v90
	v_mul_f32_e32 v91, v91, v91
	v_cvt_pk_bf16_f32 v88, v92, v88
	v_pk_fma_f32 v[86:87], v[86:87], v[98:99], v[134:135] op_sel_hi:[1,0,1]
	v_pk_fma_f32 v[84:85], v[84:85], v[98:99], v[132:133] op_sel_hi:[1,0,1]
	v_max_f32_e32 v80, 0, v80
	v_max_f32_e32 v81, 0, v81
	v_max_f32_e32 v82, 0, v82
	v_cvt_pk_bf16_f32 v89, v89, v90
	v_cvt_pk_bf16_f32 v90, v99, v93
	v_cvt_pk_bf16_f32 v91, v94, v91
	global_store_dwordx4 v[96:97], v[88:91], off
	v_max_f32_e32 v84, 0, v84
	v_max_f32_e32 v83, 0, v83
	v_mul_f32_e32 v88, v80, v80
	v_max_f32_e32 v80, 0, v85
	v_mul_f32_e32 v85, v81, v81
	v_max_f32_e32 v81, 0, v86
	v_mul_f32_e32 v86, v82, v82
	v_max_f32_e32 v82, 0, v87
	v_mul_f32_e32 v80, v80, v80
	v_mul_f32_e32 v81, v81, v81
	v_mul_f32_e32 v82, v82, v82
	v_mul_f32_e32 v84, v84, v84
	v_mul_f32_e32 v83, v83, v83
	v_cvt_pk_bf16_f32 v80, v84, v80
	v_cvt_pk_bf16_f32 v81, v81, v82
	v_cvt_pk_bf16_f32 v82, v88, v85
	v_cvt_pk_bf16_f32 v83, v86, v83
	global_store_dwordx4 v[96:97], v[80:83], off offset:256
	s_nop 1
	v_fmamk_f32 v82, v172, 0x3a000000, v229
	v_mul_f32_e32 v83, 0x4b800000, v82
	v_cmp_gt_f32_e32 vcc, s5, v82
	v_or_b32_e32 v80, 48, v156
	v_ashrrev_i32_e32 v81, 31, v80
	v_cndmask_b32_e32 v82, v82, v83, vcc
	v_rsq_f32_e32 v82, v82
	v_lshlrev_b64 v[80:81], 14, v[80:81]
	v_lshl_add_u64 v[80:81], s[54:55], 0, v[80:81]
	v_lshl_add_u64 v[80:81], v[80:81], 0, v[158:159]
	v_mul_f32_e32 v83, 0x45800000, v82
	v_cndmask_b32_e32 v82, v82, v83, vcc
	v_pk_fma_f32 v[72:73], v[72:73], v[82:83], v[136:137] op_sel_hi:[1,0,1]
	v_pk_fma_f32 v[76:77], v[76:77], v[82:83], v[140:141] op_sel_hi:[1,0,1]
	v_pk_fma_f32 v[74:75], v[74:75], v[82:83], v[138:139] op_sel_hi:[1,0,1]
	v_max_f32_e32 v72, 0, v72
	v_pk_fma_f32 v[78:79], v[78:79], v[82:83], v[142:143] op_sel_hi:[1,0,1]
	v_mul_f32_e32 v83, v72, v72
	v_max_f32_e32 v72, 0, v77
	v_max_f32_e32 v73, 0, v73
	v_max_f32_e32 v74, 0, v74
	v_max_f32_e32 v76, 0, v76
	v_mul_f32_e32 v72, v72, v72
	v_mul_f32_e32 v77, v73, v73
	v_max_f32_e32 v73, 0, v78
	v_mul_f32_e32 v78, v74, v74
	v_max_f32_e32 v74, 0, v79
	v_max_f32_e32 v75, 0, v75
	v_pk_fma_f32 v[64:65], v[64:65], v[82:83], v[128:129] op_sel_hi:[1,0,1]
	v_mul_f32_e32 v76, v76, v76
	v_mul_f32_e32 v73, v73, v73
	v_mul_f32_e32 v74, v74, v74
	v_mul_f32_e32 v75, v75, v75
	v_cvt_pk_bf16_f32 v72, v76, v72
	v_pk_fma_f32 v[68:69], v[68:69], v[82:83], v[132:133] op_sel_hi:[1,0,1]
	v_pk_fma_f32 v[66:67], v[66:67], v[82:83], v[130:131] op_sel_hi:[1,0,1]
	v_max_f32_e32 v64, 0, v64
	v_cvt_pk_bf16_f32 v73, v73, v74
	v_cvt_pk_bf16_f32 v74, v83, v77
	v_cvt_pk_bf16_f32 v75, v78, v75
	global_store_dwordx4 v[80:81], v[72:75], off
	v_pk_fma_f32 v[70:71], v[70:71], v[82:83], v[134:135] op_sel_hi:[1,0,1]
	v_max_f32_e32 v68, 0, v68
	v_mul_f32_e32 v72, v64, v64
	v_max_f32_e32 v64, 0, v69
	v_max_f32_e32 v65, 0, v65
	v_max_f32_e32 v66, 0, v66
	v_mul_f32_e32 v68, v68, v68
	v_mul_f32_e32 v64, v64, v64
	v_mul_f32_e32 v69, v65, v65
	v_max_f32_e32 v65, 0, v70
	v_mul_f32_e32 v70, v66, v66
	v_max_f32_e32 v66, 0, v71
	v_mul_f32_e32 v65, v65, v65
	v_mul_f32_e32 v66, v66, v66
	v_cvt_pk_bf16_f32 v64, v68, v64
	v_fmamk_f32 v68, v173, 0x3a000000, v229
	v_cvt_pk_bf16_f32 v65, v65, v66
	v_cvt_pk_bf16_f32 v66, v72, v69
	v_mul_f32_e32 v69, 0x4b800000, v68
	v_cmp_gt_f32_e32 vcc, s5, v68
	v_max_f32_e32 v67, 0, v67
	v_mul_f32_e32 v67, v67, v67
	v_cndmask_b32_e32 v68, v68, v69, vcc
	v_rsq_f32_e32 v68, v68
	v_cvt_pk_bf16_f32 v67, v70, v67
	global_store_dwordx4 v[80:81], v[64:67], off offset:256
	s_nop 1
	v_mul_f32_e32 v66, 0x45800000, v68
	v_cndmask_b32_e32 v66, v68, v66, vcc
	v_pk_fma_f32 v[56:57], v[56:57], v[66:67], v[136:137] op_sel_hi:[1,0,1]
	v_pk_fma_f32 v[60:61], v[60:61], v[66:67], v[140:141] op_sel_hi:[1,0,1]
	v_pk_fma_f32 v[58:59], v[58:59], v[66:67], v[138:139] op_sel_hi:[1,0,1]
	v_max_f32_e32 v56, 0, v56
	v_pk_fma_f32 v[62:63], v[62:63], v[66:67], v[142:143] op_sel_hi:[1,0,1]
	v_max_f32_e32 v60, 0, v60
	v_mul_f32_e32 v67, v56, v56
	v_max_f32_e32 v56, 0, v61
	v_max_f32_e32 v57, 0, v57
	v_max_f32_e32 v58, 0, v58
	v_mul_f32_e32 v60, v60, v60
	v_mul_f32_e32 v56, v56, v56
	v_mul_f32_e32 v61, v57, v57
	v_max_f32_e32 v57, 0, v62
	v_mul_f32_e32 v62, v58, v58
	v_max_f32_e32 v58, 0, v63
	v_mul_f32_e32 v57, v57, v57
	v_max_f32_e32 v59, 0, v59
	v_mul_f32_e32 v58, v58, v58
	v_cvt_pk_bf16_f32 v56, v60, v56
	v_add_co_u32_e32 v60, vcc, s3, v154
	v_pk_fma_f32 v[48:49], v[48:49], v[66:67], v[128:129] op_sel_hi:[1,0,1]
	v_mul_f32_e32 v59, v59, v59
	v_cvt_pk_bf16_f32 v57, v57, v58
	v_cvt_pk_bf16_f32 v58, v67, v61
	v_addc_co_u32_e32 v61, vcc, 0, v155, vcc
	v_pk_fma_f32 v[52:53], v[52:53], v[66:67], v[132:133] op_sel_hi:[1,0,1]
	v_pk_fma_f32 v[50:51], v[50:51], v[66:67], v[130:131] op_sel_hi:[1,0,1]
	v_max_f32_e32 v48, 0, v48
	v_cvt_pk_bf16_f32 v59, v62, v59
	global_store_dwordx4 v[60:61], v[56:59], off
	v_pk_fma_f32 v[54:55], v[54:55], v[66:67], v[134:135] op_sel_hi:[1,0,1]
	v_max_f32_e32 v52, 0, v52
	v_mul_f32_e32 v56, v48, v48
	v_max_f32_e32 v48, 0, v53
	v_max_f32_e32 v49, 0, v49
	v_max_f32_e32 v50, 0, v50
	v_mul_f32_e32 v52, v52, v52
	v_mul_f32_e32 v48, v48, v48
	v_mul_f32_e32 v53, v49, v49
	v_max_f32_e32 v49, 0, v54
	v_mul_f32_e32 v54, v50, v50
	v_max_f32_e32 v50, 0, v55
	v_mul_f32_e32 v49, v49, v49
	v_mul_f32_e32 v50, v50, v50
	v_cvt_pk_bf16_f32 v48, v52, v48
	v_fmamk_f32 v52, v166, 0x3a000000, v229
	v_cvt_pk_bf16_f32 v49, v49, v50
	v_cvt_pk_bf16_f32 v50, v56, v53
	v_mul_f32_e32 v53, 0x4b800000, v52
	v_cmp_gt_f32_e32 vcc, s5, v52
	v_max_f32_e32 v51, 0, v51
	v_lshl_add_u64 v[64:65], v[154:155], 0, s[12:13]
	v_cndmask_b32_e32 v52, v52, v53, vcc
	v_rsq_f32_e32 v52, v52
	v_mul_f32_e32 v51, v51, v51
	v_cvt_pk_bf16_f32 v51, v54, v51
	global_store_dwordx4 v[64:65], v[48:51], off offset:256
	s_mov_b32 s3, 0x240000
	s_mov_b64 s[12:13], 0x240000
	v_mul_f32_e32 v50, 0x45800000, v52
	v_cndmask_b32_e32 v50, v52, v50, vcc
	v_pk_fma_f32 v[40:41], v[40:41], v[50:51], v[136:137] op_sel_hi:[1,0,1]
	v_pk_fma_f32 v[44:45], v[44:45], v[50:51], v[140:141] op_sel_hi:[1,0,1]
	v_pk_fma_f32 v[42:43], v[42:43], v[50:51], v[138:139] op_sel_hi:[1,0,1]
	v_max_f32_e32 v40, 0, v40
	v_pk_fma_f32 v[46:47], v[46:47], v[50:51], v[142:143] op_sel_hi:[1,0,1]
	v_max_f32_e32 v44, 0, v44
	v_mul_f32_e32 v51, v40, v40
	v_max_f32_e32 v40, 0, v45
	v_max_f32_e32 v41, 0, v41
	v_max_f32_e32 v42, 0, v42
	v_mul_f32_e32 v44, v44, v44
	v_mul_f32_e32 v40, v40, v40
	v_mul_f32_e32 v45, v41, v41
	v_max_f32_e32 v41, 0, v46
	v_mul_f32_e32 v46, v42, v42
	v_max_f32_e32 v42, 0, v47
	v_mul_f32_e32 v41, v41, v41
	v_max_f32_e32 v43, 0, v43
	v_mul_f32_e32 v42, v42, v42
	v_cvt_pk_bf16_f32 v40, v44, v40
	v_add_co_u32_e32 v44, vcc, s3, v154
	v_pk_fma_f32 v[32:33], v[32:33], v[50:51], v[128:129] op_sel_hi:[1,0,1]
	v_mul_f32_e32 v43, v43, v43
	v_cvt_pk_bf16_f32 v41, v41, v42
	v_cvt_pk_bf16_f32 v42, v51, v45
	v_addc_co_u32_e32 v45, vcc, 0, v155, vcc
	v_pk_fma_f32 v[36:37], v[36:37], v[50:51], v[132:133] op_sel_hi:[1,0,1]
	v_pk_fma_f32 v[34:35], v[34:35], v[50:51], v[130:131] op_sel_hi:[1,0,1]
	v_max_f32_e32 v32, 0, v32
	v_cvt_pk_bf16_f32 v43, v46, v43
	global_store_dwordx4 v[44:45], v[40:43], off
	v_pk_fma_f32 v[38:39], v[38:39], v[50:51], v[134:135] op_sel_hi:[1,0,1]
	v_max_f32_e32 v36, 0, v36
	v_mul_f32_e32 v40, v32, v32
	v_max_f32_e32 v32, 0, v37
	v_max_f32_e32 v33, 0, v33
	v_max_f32_e32 v34, 0, v34
	v_mul_f32_e32 v36, v36, v36
	v_mul_f32_e32 v32, v32, v32
	v_mul_f32_e32 v37, v33, v33
	v_max_f32_e32 v33, 0, v38
	v_mul_f32_e32 v38, v34, v34
	v_max_f32_e32 v34, 0, v39
	v_mul_f32_e32 v33, v33, v33
	v_mul_f32_e32 v34, v34, v34
	v_cvt_pk_bf16_f32 v32, v36, v32
	v_fmamk_f32 v36, v165, 0x3a000000, v229
	v_cvt_pk_bf16_f32 v33, v33, v34
	v_cvt_pk_bf16_f32 v34, v40, v37
	v_mul_f32_e32 v37, 0x4b800000, v36
	v_cmp_gt_f32_e32 vcc, s5, v36
	v_max_f32_e32 v35, 0, v35
	v_lshl_add_u64 v[48:49], v[154:155], 0, s[12:13]
	v_cndmask_b32_e32 v36, v36, v37, vcc
	v_rsq_f32_e32 v36, v36
	v_mul_f32_e32 v35, v35, v35
	v_cvt_pk_bf16_f32 v35, v38, v35
	global_store_dwordx4 v[48:49], v[32:35], off offset:256
	s_mov_b32 s3, 0x280000
	s_mov_b64 s[12:13], 0x280000
	v_mul_f32_e32 v34, 0x45800000, v36
	v_cndmask_b32_e32 v34, v36, v34, vcc
	v_pk_fma_f32 v[24:25], v[24:25], v[34:35], v[136:137] op_sel_hi:[1,0,1]
	v_pk_fma_f32 v[28:29], v[28:29], v[34:35], v[140:141] op_sel_hi:[1,0,1]
	v_pk_fma_f32 v[26:27], v[26:27], v[34:35], v[138:139] op_sel_hi:[1,0,1]
	v_max_f32_e32 v24, 0, v24
	v_pk_fma_f32 v[30:31], v[30:31], v[34:35], v[142:143] op_sel_hi:[1,0,1]
	v_max_f32_e32 v28, 0, v28
	v_mul_f32_e32 v35, v24, v24
	v_max_f32_e32 v24, 0, v29
	v_max_f32_e32 v25, 0, v25
	v_max_f32_e32 v26, 0, v26
	v_mul_f32_e32 v28, v28, v28
	v_mul_f32_e32 v24, v24, v24
	v_mul_f32_e32 v29, v25, v25
	v_max_f32_e32 v25, 0, v30
	v_mul_f32_e32 v30, v26, v26
	v_max_f32_e32 v26, 0, v31
	v_mul_f32_e32 v25, v25, v25
	v_max_f32_e32 v27, 0, v27
	v_mul_f32_e32 v26, v26, v26
	v_cvt_pk_bf16_f32 v24, v28, v24
	v_add_co_u32_e32 v28, vcc, s3, v154
	v_pk_fma_f32 v[16:17], v[16:17], v[34:35], v[128:129] op_sel_hi:[1,0,1]
	v_mul_f32_e32 v27, v27, v27
	v_cvt_pk_bf16_f32 v25, v25, v26
	v_cvt_pk_bf16_f32 v26, v35, v29
	v_addc_co_u32_e32 v29, vcc, 0, v155, vcc
	v_pk_fma_f32 v[20:21], v[20:21], v[34:35], v[132:133] op_sel_hi:[1,0,1]
	v_pk_fma_f32 v[18:19], v[18:19], v[34:35], v[130:131] op_sel_hi:[1,0,1]
	v_max_f32_e32 v16, 0, v16
	v_cvt_pk_bf16_f32 v27, v30, v27
	global_store_dwordx4 v[28:29], v[24:27], off
	v_pk_fma_f32 v[22:23], v[22:23], v[34:35], v[134:135] op_sel_hi:[1,0,1]
	v_max_f32_e32 v20, 0, v20
	v_mul_f32_e32 v24, v16, v16
	v_max_f32_e32 v16, 0, v21
	v_max_f32_e32 v17, 0, v17
	v_max_f32_e32 v18, 0, v18
	v_mul_f32_e32 v20, v20, v20
	v_mul_f32_e32 v16, v16, v16
	v_mul_f32_e32 v21, v17, v17
	v_max_f32_e32 v17, 0, v22
	v_mul_f32_e32 v22, v18, v18
	v_max_f32_e32 v18, 0, v23
	v_mul_f32_e32 v17, v17, v17
	v_mul_f32_e32 v18, v18, v18
	v_cvt_pk_bf16_f32 v16, v20, v16
	v_fmamk_f32 v20, v164, 0x3a000000, v229
	v_cvt_pk_bf16_f32 v17, v17, v18
	v_cvt_pk_bf16_f32 v18, v24, v21
	v_mul_f32_e32 v21, 0x4b800000, v20
	v_cmp_gt_f32_e32 vcc, s5, v20
	v_max_f32_e32 v19, 0, v19
	v_lshl_add_u64 v[32:33], v[154:155], 0, s[12:13]
	v_cndmask_b32_e32 v20, v20, v21, vcc
	v_rsq_f32_e32 v20, v20
	v_mul_f32_e32 v19, v19, v19
	v_cvt_pk_bf16_f32 v19, v22, v19
	global_store_dwordx4 v[32:33], v[16:19], off offset:256
	s_mov_b32 s3, 0x2c0000
	s_mov_b64 s[12:13], 0x2c0000
	v_mul_f32_e32 v18, 0x45800000, v20
	v_cndmask_b32_e32 v18, v20, v18, vcc
	v_pk_fma_f32 v[8:9], v[8:9], v[18:19], v[136:137] op_sel_hi:[1,0,1]
	v_pk_fma_f32 v[12:13], v[12:13], v[18:19], v[140:141] op_sel_hi:[1,0,1]
	v_pk_fma_f32 v[10:11], v[10:11], v[18:19], v[138:139] op_sel_hi:[1,0,1]
	v_max_f32_e32 v8, 0, v8
	v_pk_fma_f32 v[14:15], v[14:15], v[18:19], v[142:143] op_sel_hi:[1,0,1]
	v_max_f32_e32 v12, 0, v12
	v_mul_f32_e32 v19, v8, v8
	v_max_f32_e32 v8, 0, v13
	v_max_f32_e32 v9, 0, v9
	v_max_f32_e32 v10, 0, v10
	v_mul_f32_e32 v12, v12, v12
	v_mul_f32_e32 v8, v8, v8
	v_mul_f32_e32 v13, v9, v9
	v_max_f32_e32 v9, 0, v14
	v_mul_f32_e32 v14, v10, v10
	v_max_f32_e32 v10, 0, v15
	v_mul_f32_e32 v9, v9, v9
	v_max_f32_e32 v11, 0, v11
	v_mul_f32_e32 v10, v10, v10
	v_cvt_pk_bf16_f32 v8, v12, v8
	v_add_co_u32_e32 v12, vcc, s3, v154
	v_pk_fma_f32 v[2:3], v[2:3], v[18:19], v[130:131] op_sel_hi:[1,0,1]
	v_pk_fma_f32 v[0:1], v[0:1], v[18:19], v[128:129] op_sel_hi:[1,0,1]
	v_mul_f32_e32 v11, v11, v11
	v_cvt_pk_bf16_f32 v9, v9, v10
	v_cvt_pk_bf16_f32 v10, v19, v13
	v_addc_co_u32_e32 v13, vcc, 0, v155, vcc
	v_pk_fma_f32 v[6:7], v[6:7], v[18:19], v[134:135] op_sel_hi:[1,0,1]
	v_pk_fma_f32 v[4:5], v[4:5], v[18:19], v[132:133] op_sel_hi:[1,0,1]
	v_max_f32_e32 v0, 0, v0
	v_max_f32_e32 v1, 0, v1
	v_max_f32_e32 v2, 0, v2
	v_cvt_pk_bf16_f32 v11, v14, v11
	global_store_dwordx4 v[12:13], v[8:11], off
	v_max_f32_e32 v3, 0, v3
	v_lshl_add_u64 v[16:17], v[154:155], 0, s[12:13]
	v_mul_f32_e32 v8, v0, v0
	v_max_f32_e32 v0, 0, v5
	v_mul_f32_e32 v5, v1, v1
	v_max_f32_e32 v1, 0, v6
	v_mul_f32_e32 v6, v2, v2
	v_max_f32_e32 v2, 0, v7
	v_max_f32_e32 v4, 0, v4
	v_mul_f32_e32 v0, v0, v0
	v_mul_f32_e32 v1, v1, v1
	v_mul_f32_e32 v2, v2, v2
	v_mul_f32_e32 v3, v3, v3
	s_and_b64 vcc, exec, s[42:43]
	s_mov_b64 s[12:13], s[18:19]
	v_mul_f32_e32 v4, v4, v4
	v_cvt_pk_bf16_f32 v0, v4, v0
	v_cvt_pk_bf16_f32 v1, v1, v2
	v_cvt_pk_bf16_f32 v2, v8, v5
	v_cvt_pk_bf16_f32 v3, v6, v3
	global_store_dwordx4 v[16:17], v[0:3], off offset:256
	s_cbranch_vccz .LBB0_796
	s_waitcnt vmcnt(0)
	s_cmpk_gt_u32 s22, 0xff
	v_readlane_b32 s35, v252, 37
	s_cbranch_scc1 .LBB0_807
	s_barrier

.LBB0_889:
	s_add_u32 s4, s12, 0xffe00080
	s_addc_u32 s20, s13, -1
	s_add_i32 s58, 0, 0x10000
	v_add_u32_e32 v124, s58, v161
	ds_read_b128 v[104:107], v124
	ds_read_b128 v[108:111], v124 offset:1024
	ds_read_b128 v[116:119], v124 offset:2048
	ds_read_b128 v[124:127], v124 offset:3072
	s_cmpk_eq_i32 vcc_hi, 0x7c
	s_cselect_b32 s25, s29, s20
	s_cselect_b32 s24, s57, s4
	s_cselect_b32 s21, s19, vcc_lo
	s_cselect_b32 s20, s68, s69
	s_add_i32 m0, s22, 0xc000
	ds_read_b128 v[152:155], v163
	ds_read_b128 v[156:159], v163 offset:1024
	ds_read_b128 v[164:167], v163 offset:2048
	ds_read_b128 v[168:171], v163 offset:3072
	ds_read_b128 v[172:175], v163 offset:4096
	ds_read_b128 v[176:179], v163 offset:5120
	ds_read_b128 v[180:183], v163 offset:6144
	ds_read_b128 v[196:199], v163 offset:7168
	v_add_u32_e32 v212, 0x14000, v161
	ds_read_b128 v[200:203], v212
	ds_read_b128 v[204:207], v212 offset:1024
	ds_read_b128 v[208:211], v212 offset:2048
	ds_read_b128 v[212:215], v212 offset:3072
	global_load_lds_dwordx4 v148, s[12:13]
	s_add_i32 m0, s22, 0xe000
	s_nop 0
	global_load_lds_dwordx4 v150, s[12:13]
	s_waitcnt vmcnt(8)
	s_waitcnt lgkmcnt(0)
	s_barrier
	s_setprio 1
	v_mfma_f32_16x16x32_bf16 v[140:143], v[104:107], v[152:155], v[140:143]
	v_mfma_f32_16x16x32_bf16 v[136:139], v[116:119], v[152:155], v[136:139]
	v_mfma_f32_16x16x32_bf16 v[120:123], v[104:107], v[164:167], v[120:123]
	v_mfma_f32_16x16x32_bf16 v[112:115], v[116:119], v[164:167], v[112:115]
	v_mfma_f32_16x16x32_bf16 v[92:95], v[104:107], v[172:175], v[92:95]
	v_mfma_f32_16x16x32_bf16 v[88:91], v[116:119], v[172:175], v[88:91]
	v_mfma_f32_16x16x32_bf16 v[76:79], v[104:107], v[180:183], v[76:79]
	v_mfma_f32_16x16x32_bf16 v[72:75], v[116:119], v[180:183], v[72:75]
	v_mfma_f32_16x16x32_bf16 v[140:143], v[108:111], v[156:159], v[140:143]
	v_mfma_f32_16x16x32_bf16 v[136:139], v[124:127], v[156:159], v[136:139]
	v_mfma_f32_16x16x32_bf16 v[120:123], v[108:111], v[168:171], v[120:123]
	v_mfma_f32_16x16x32_bf16 v[112:115], v[124:127], v[168:171], v[112:115]
	v_mfma_f32_16x16x32_bf16 v[92:95], v[108:111], v[176:179], v[92:95]
	v_mfma_f32_16x16x32_bf16 v[88:91], v[124:127], v[176:179], v[88:91]
	v_mfma_f32_16x16x32_bf16 v[76:79], v[108:111], v[196:199], v[76:79]
	v_mfma_f32_16x16x32_bf16 v[72:75], v[124:127], v[196:199], v[72:75]
	v_mfma_f32_16x16x32_bf16 v[132:135], v[200:203], v[152:155], v[132:135]
	v_mfma_f32_16x16x32_bf16 v[128:131], v[208:211], v[152:155], v[128:131]
	v_mfma_f32_16x16x32_bf16 v[100:103], v[200:203], v[164:167], v[100:103]
	v_mfma_f32_16x16x32_bf16 v[96:99], v[208:211], v[164:167], v[96:99]
	v_mfma_f32_16x16x32_bf16 v[84:87], v[200:203], v[172:175], v[84:87]
	v_mfma_f32_16x16x32_bf16 v[80:83], v[208:211], v[172:175], v[80:83]
	v_mfma_f32_16x16x32_bf16 v[68:71], v[200:203], v[180:183], v[68:71]
	v_mfma_f32_16x16x32_bf16 v[64:67], v[208:211], v[180:183], v[64:67]
	v_mfma_f32_16x16x32_bf16 v[132:135], v[204:207], v[156:159], v[132:135]
	v_mfma_f32_16x16x32_bf16 v[128:131], v[212:215], v[156:159], v[128:131]
	v_mfma_f32_16x16x32_bf16 v[100:103], v[204:207], v[168:171], v[100:103]
	v_mfma_f32_16x16x32_bf16 v[96:99], v[212:215], v[168:171], v[96:99]
	v_mfma_f32_16x16x32_bf16 v[84:87], v[204:207], v[176:179], v[84:87]
	v_mfma_f32_16x16x32_bf16 v[80:83], v[212:215], v[176:179], v[80:83]
	v_mfma_f32_16x16x32_bf16 v[68:71], v[204:207], v[196:199], v[68:71]
	v_mfma_f32_16x16x32_bf16 v[64:67], v[212:215], v[196:199], v[64:67]
	s_setprio 0
	s_barrier
	s_add_i32 s4, 0, 0x14000
	s_add_i32 s58, s58, s27
	v_lshl_add_u64 v[216:217], s[20:21], 0, v[146:147]
	s_mov_b32 m0, s58
	global_load_lds_dwordx4 v146, s[20:21]
	v_lshl_add_u64 v[218:219], s[20:21], 0, v[144:145]
	s_add_i32 m0, s58, 0x2000
	s_nop 0
	global_load_lds_dwordx4 v144, s[20:21]
	s_mov_b32 m0, s22
	v_lshl_add_u64 v[220:221], s[24:25], 0, v[146:147]
	ds_read_b128 v[152:155], v163 offset:16384
	ds_read_b128 v[156:159], v163 offset:17408
	ds_read_b128 v[164:167], v163 offset:18432
	ds_read_b128 v[168:171], v163 offset:19456
	ds_read_b128 v[172:175], v163 offset:20480
	ds_read_b128 v[176:179], v163 offset:21504
	ds_read_b128 v[180:183], v163 offset:22528
	ds_read_b128 v[196:199], v163 offset:23552
	global_load_lds_dwordx4 v146, s[24:25]
	v_lshl_add_u64 v[222:223], s[24:25], 0, v[144:145]
	s_mov_b32 m0, s23
	s_nop 0
	global_load_lds_dwordx4 v144, s[24:25]
	s_waitcnt vmcnt(6)
	s_waitcnt lgkmcnt(0)
	s_barrier
	s_setprio 1
	v_mfma_f32_16x16x32_bf16 v[60:63], v[104:107], v[152:155], v[60:63]
	v_mfma_f32_16x16x32_bf16 v[56:59], v[116:119], v[152:155], v[56:59]
	v_mfma_f32_16x16x32_bf16 v[44:47], v[104:107], v[164:167], v[44:47]
	v_mfma_f32_16x16x32_bf16 v[40:43], v[116:119], v[164:167], v[40:43]
	v_mfma_f32_16x16x32_bf16 v[28:31], v[104:107], v[172:175], v[28:31]
	v_mfma_f32_16x16x32_bf16 v[24:27], v[116:119], v[172:175], v[24:27]
	v_mfma_f32_16x16x32_bf16 v[12:15], v[104:107], v[180:183], v[12:15]
	v_mfma_f32_16x16x32_bf16 v[8:11], v[116:119], v[180:183], v[8:11]
	v_mfma_f32_16x16x32_bf16 v[60:63], v[108:111], v[156:159], v[60:63]
	v_mfma_f32_16x16x32_bf16 v[56:59], v[124:127], v[156:159], v[56:59]
	v_mfma_f32_16x16x32_bf16 v[44:47], v[108:111], v[168:171], v[44:47]
	v_mfma_f32_16x16x32_bf16 v[40:43], v[124:127], v[168:171], v[40:43]
	v_mfma_f32_16x16x32_bf16 v[28:31], v[108:111], v[176:179], v[28:31]
	v_mfma_f32_16x16x32_bf16 v[24:27], v[124:127], v[176:179], v[24:27]
	v_mfma_f32_16x16x32_bf16 v[12:15], v[108:111], v[196:199], v[12:15]
	v_mfma_f32_16x16x32_bf16 v[8:11], v[124:127], v[196:199], v[8:11]
	v_mfma_f32_16x16x32_bf16 v[52:55], v[200:203], v[152:155], v[52:55]
	v_mfma_f32_16x16x32_bf16 v[48:51], v[208:211], v[152:155], v[48:51]
	v_mfma_f32_16x16x32_bf16 v[36:39], v[200:203], v[164:167], v[36:39]
	v_mfma_f32_16x16x32_bf16 v[32:35], v[208:211], v[164:167], v[32:35]
	v_mfma_f32_16x16x32_bf16 v[20:23], v[200:203], v[172:175], v[20:23]
	v_mfma_f32_16x16x32_bf16 v[16:19], v[208:211], v[172:175], v[16:19]
	v_mfma_f32_16x16x32_bf16 v[4:7], v[200:203], v[180:183], v[4:7]
	v_mfma_f32_16x16x32_bf16 v[0:3], v[208:211], v[180:183], v[0:3]
	v_mfma_f32_16x16x32_bf16 v[52:55], v[204:207], v[156:159], v[52:55]
	v_mfma_f32_16x16x32_bf16 v[48:51], v[212:215], v[156:159], v[48:51]
	v_mfma_f32_16x16x32_bf16 v[36:39], v[204:207], v[168:171], v[36:39]
	v_mfma_f32_16x16x32_bf16 v[32:35], v[212:215], v[168:171], v[32:35]
	v_mfma_f32_16x16x32_bf16 v[20:23], v[204:207], v[176:179], v[20:23]
	v_mfma_f32_16x16x32_bf16 v[16:19], v[212:215], v[176:179], v[16:19]
	v_mfma_f32_16x16x32_bf16 v[4:7], v[204:207], v[196:199], v[4:7]
	v_mfma_f32_16x16x32_bf16 v[0:3], v[212:215], v[196:199], v[0:3]
	s_setprio 0
	s_barrier
	s_add_u32 s58, s20, 0x200000
	s_addc_u32 s59, s21, 0
	s_add_i32 s4, s4, s27
	s_mov_b32 m0, s4
	s_nop 0
	global_load_lds_dwordx4 v146, s[58:59]
	s_add_i32 m0, s4, 0x2000
	s_nop 0
	global_load_lds_dwordx4 v144, s[58:59]
	s_add_i32 s4, 0, 0x18000
	v_add_u32_e32 v124, s4, v161
	ds_read_b128 v[104:107], v124
	ds_read_b128 v[108:111], v124 offset:1024
	ds_read_b128 v[116:119], v124 offset:2048
	ds_read_b128 v[124:127], v124 offset:3072
	s_add_u32 s24, s24, 0x200000
	s_addc_u32 s25, s25, 0
	s_mov_b32 m0, s30
	ds_read_b128 v[152:155], v163 offset:32768
	ds_read_b128 v[156:159], v163 offset:33792
	ds_read_b128 v[164:167], v163 offset:34816
	ds_read_b128 v[168:171], v163 offset:35840
	ds_read_b128 v[172:175], v163 offset:36864
	ds_read_b128 v[176:179], v163 offset:37888
	ds_read_b128 v[180:183], v163 offset:38912
	ds_read_b128 v[196:199], v163 offset:39936
	v_add_u32_e32 v212, 0x1c000, v161
	ds_read_b128 v[200:203], v212
	ds_read_b128 v[204:207], v212 offset:1024
	ds_read_b128 v[208:211], v212 offset:2048
	ds_read_b128 v[212:215], v212 offset:3072
	global_load_lds_dwordx4 v146, s[24:25]
	s_mov_b32 m0, s31
	s_nop 0
	global_load_lds_dwordx4 v144, s[24:25]
	s_waitcnt vmcnt(8)
	s_waitcnt lgkmcnt(0)
	s_barrier
	s_setprio 1
	v_mfma_f32_16x16x32_bf16 v[140:143], v[104:107], v[152:155], v[140:143]
	v_mfma_f32_16x16x32_bf16 v[136:139], v[116:119], v[152:155], v[136:139]
	v_mfma_f32_16x16x32_bf16 v[120:123], v[104:107], v[164:167], v[120:123]
	v_mfma_f32_16x16x32_bf16 v[112:115], v[116:119], v[164:167], v[112:115]
	v_mfma_f32_16x16x32_bf16 v[92:95], v[104:107], v[172:175], v[92:95]
	v_mfma_f32_16x16x32_bf16 v[88:91], v[116:119], v[172:175], v[88:91]
	v_mfma_f32_16x16x32_bf16 v[76:79], v[104:107], v[180:183], v[76:79]
	v_mfma_f32_16x16x32_bf16 v[72:75], v[116:119], v[180:183], v[72:75]
	v_mfma_f32_16x16x32_bf16 v[140:143], v[108:111], v[156:159], v[140:143]
	v_mfma_f32_16x16x32_bf16 v[136:139], v[124:127], v[156:159], v[136:139]
	v_mfma_f32_16x16x32_bf16 v[120:123], v[108:111], v[168:171], v[120:123]
	v_mfma_f32_16x16x32_bf16 v[112:115], v[124:127], v[168:171], v[112:115]
	v_mfma_f32_16x16x32_bf16 v[92:95], v[108:111], v[176:179], v[92:95]
	v_mfma_f32_16x16x32_bf16 v[88:91], v[124:127], v[176:179], v[88:91]
	v_mfma_f32_16x16x32_bf16 v[76:79], v[108:111], v[196:199], v[76:79]
	v_mfma_f32_16x16x32_bf16 v[72:75], v[124:127], v[196:199], v[72:75]
	v_mfma_f32_16x16x32_bf16 v[132:135], v[200:203], v[152:155], v[132:135]
	v_mfma_f32_16x16x32_bf16 v[128:131], v[208:211], v[152:155], v[128:131]
	v_mfma_f32_16x16x32_bf16 v[100:103], v[200:203], v[164:167], v[100:103]
	v_mfma_f32_16x16x32_bf16 v[96:99], v[208:211], v[164:167], v[96:99]
	v_mfma_f32_16x16x32_bf16 v[84:87], v[200:203], v[172:175], v[84:87]
	v_mfma_f32_16x16x32_bf16 v[80:83], v[208:211], v[172:175], v[80:83]
	v_mfma_f32_16x16x32_bf16 v[68:71], v[200:203], v[180:183], v[68:71]
	v_mfma_f32_16x16x32_bf16 v[64:67], v[208:211], v[180:183], v[64:67]
	v_mfma_f32_16x16x32_bf16 v[132:135], v[204:207], v[156:159], v[132:135]
	v_mfma_f32_16x16x32_bf16 v[128:131], v[212:215], v[156:159], v[128:131]
	v_mfma_f32_16x16x32_bf16 v[100:103], v[204:207], v[168:171], v[100:103]
	v_mfma_f32_16x16x32_bf16 v[96:99], v[212:215], v[168:171], v[96:99]
	v_mfma_f32_16x16x32_bf16 v[84:87], v[204:207], v[176:179], v[84:87]
	v_mfma_f32_16x16x32_bf16 v[80:83], v[212:215], v[176:179], v[80:83]
	v_mfma_f32_16x16x32_bf16 v[68:71], v[204:207], v[196:199], v[68:71]
	v_mfma_f32_16x16x32_bf16 v[64:67], v[212:215], v[196:199], v[64:67]
	s_setprio 0
	s_barrier
	s_add_i32 s24, 0, 0x1c000
	s_add_i32 s4, s4, s27
	v_lshl_add_u64 v[216:217], v[216:217], 0, s[0:1]
	s_mov_b32 m0, s4
	global_load_lds_dwordx4 v[216:217], off
	v_lshl_add_u64 v[216:217], v[218:219], 0, s[0:1]
	s_add_i32 m0, s4, 0x2000
	s_nop 0
	global_load_lds_dwordx4 v[216:217], off
	s_mov_b32 m0, s16
	v_lshl_add_u64 v[216:217], v[220:221], 0, s[0:1]
	ds_read_b128 v[152:155], v163 offset:49152
	ds_read_b128 v[156:159], v163 offset:50176
	ds_read_b128 v[164:167], v163 offset:51200
	ds_read_b128 v[168:171], v163 offset:52224
	ds_read_b128 v[172:175], v163 offset:53248
	ds_read_b128 v[176:179], v163 offset:54272
	ds_read_b128 v[180:183], v163 offset:55296
	ds_read_b128 v[196:199], v163 offset:56320
	global_load_lds_dwordx4 v[216:217], off
	v_lshl_add_u64 v[216:217], v[222:223], 0, s[0:1]
	s_mov_b32 m0, s17
	s_nop 0
	global_load_lds_dwordx4 v[216:217], off
	s_add_u32 s20, s20, 0x200080
	s_addc_u32 s21, s21, 0
	s_add_i32 s4, s24, s27
	s_mov_b32 m0, s4
	s_nop 0
	global_load_lds_dwordx4 v146, s[20:21]
	s_add_i32 m0, s4, 0x2000
	s_nop 0
	global_load_lds_dwordx4 v144, s[20:21]
	s_waitcnt vmcnt(8)
	s_waitcnt lgkmcnt(0)
	s_barrier
	s_setprio 1
	v_mfma_f32_16x16x32_bf16 v[60:63], v[104:107], v[152:155], v[60:63]
	v_mfma_f32_16x16x32_bf16 v[56:59], v[116:119], v[152:155], v[56:59]
	v_mfma_f32_16x16x32_bf16 v[44:47], v[104:107], v[164:167], v[44:47]
	v_mfma_f32_16x16x32_bf16 v[40:43], v[116:119], v[164:167], v[40:43]
	v_mfma_f32_16x16x32_bf16 v[28:31], v[104:107], v[172:175], v[28:31]
	v_mfma_f32_16x16x32_bf16 v[24:27], v[116:119], v[172:175], v[24:27]
	v_mfma_f32_16x16x32_bf16 v[12:15], v[104:107], v[180:183], v[12:15]
	v_mfma_f32_16x16x32_bf16 v[8:11], v[116:119], v[180:183], v[8:11]
	v_mfma_f32_16x16x32_bf16 v[60:63], v[108:111], v[156:159], v[60:63]
	v_mfma_f32_16x16x32_bf16 v[56:59], v[124:127], v[156:159], v[56:59]
	v_mfma_f32_16x16x32_bf16 v[44:47], v[108:111], v[168:171], v[44:47]
	v_mfma_f32_16x16x32_bf16 v[40:43], v[124:127], v[168:171], v[40:43]
	v_mfma_f32_16x16x32_bf16 v[28:31], v[108:111], v[176:179], v[28:31]
	v_mfma_f32_16x16x32_bf16 v[24:27], v[124:127], v[176:179], v[24:27]
	v_mfma_f32_16x16x32_bf16 v[12:15], v[108:111], v[196:199], v[12:15]
	v_mfma_f32_16x16x32_bf16 v[8:11], v[124:127], v[196:199], v[8:11]
	v_mfma_f32_16x16x32_bf16 v[52:55], v[200:203], v[152:155], v[52:55]
	v_mfma_f32_16x16x32_bf16 v[48:51], v[208:211], v[152:155], v[48:51]
	v_mfma_f32_16x16x32_bf16 v[36:39], v[200:203], v[164:167], v[36:39]
	v_mfma_f32_16x16x32_bf16 v[32:35], v[208:211], v[164:167], v[32:35]
	v_mfma_f32_16x16x32_bf16 v[20:23], v[200:203], v[172:175], v[20:23]
	v_mfma_f32_16x16x32_bf16 v[16:19], v[208:211], v[172:175], v[16:19]
	v_mfma_f32_16x16x32_bf16 v[4:7], v[200:203], v[180:183], v[4:7]
	v_mfma_f32_16x16x32_bf16 v[0:3], v[208:211], v[180:183], v[0:3]
	v_mfma_f32_16x16x32_bf16 v[52:55], v[204:207], v[156:159], v[52:55]
	v_mfma_f32_16x16x32_bf16 v[48:51], v[212:215], v[156:159], v[48:51]
	v_mfma_f32_16x16x32_bf16 v[36:39], v[204:207], v[168:171], v[36:39]
	v_mfma_f32_16x16x32_bf16 v[32:35], v[212:215], v[168:171], v[32:35]
	v_mfma_f32_16x16x32_bf16 v[20:23], v[204:207], v[176:179], v[20:23]
	v_mfma_f32_16x16x32_bf16 v[16:19], v[212:215], v[176:179], v[16:19]
	v_mfma_f32_16x16x32_bf16 v[4:7], v[204:207], v[196:199], v[4:7]
	v_mfma_f32_16x16x32_bf16 v[0:3], v[212:215], v[196:199], v[0:3]
	s_setprio 0
	s_add_i32 vcc_hi, vcc_hi, 2
	s_add_u32 s12, s12, 0x100
	s_addc_u32 s13, s13, 0
	s_add_u32 s69, s69, 0x100
	s_addc_u32 vcc_lo, vcc_lo, 0
	s_cmpk_gt_u32 vcc_hi, 0x7d
	s_barrier
	s_cbranch_scc0 .LBB0_889
	s_lshl_b32 s4, s56, 8
	s_add_i32 s4, s4, s35
	s_min_i32 s12, s4, 0x4000
	s_ashr_i32 s12, s12, 11
	s_mul_hi_i32 s13, s12, 0xc000
	s_mul_i32 s12, s12, 0xc000
	v_lshl_or_b32 v154, s53, 8, v162
	s_add_u32 s12, s8, s12
	s_addc_u32 s13, s9, s13
	v_ashrrev_i32_e32 v155, 31, v154
	v_lshl_add_u64 v[104:105], v[154:155], 2, s[12:13]
	global_load_dwordx4 v[124:127], v[104:105], off
	global_load_dwordx4 v[116:119], v[104:105], off offset:64
	global_load_dwordx4 v[108:111], v[104:105], off offset:512
	s_nop 0
	global_load_dwordx4 v[104:107], v[104:105], off offset:576
	v_add_u32_e32 v152, s4, v160
	s_movk_i32 s4, 0x3fff
	v_cmp_lt_i32_e32 vcc, s4, v152
	s_and_saveexec_b64 s[12:13], vcc
	s_xor_b64 s[12:13], exec, s[12:13]
	v_add_u32_e32 v186, 0xffffc000, v152
	v_lshlrev_b64 v[156:157], 13, v[186:187]
	v_mov_b32_e32 v153, v187
	v_lshl_add_u64 v[158:159], s[10:11], 0, v[156:157]
	v_lshlrev_b64 v[156:157], 13, v[152:153]
	s_andn2_saveexec_b64 s[12:13], s[12:13]
	v_ashrrev_i32_e32 v153, 31, v152
	v_lshlrev_b64 v[156:157], 13, v[152:153]
	v_lshl_add_u64 v[158:159], s[66:67], 0, v[156:157]
	s_or_b64 exec, exec, s[12:13]
	v_lshlrev_b64 v[154:155], 2, v[154:155]
	v_lshl_add_u64 v[158:159], v[158:159], 0, v[154:155]
	global_load_dwordx4 v[164:167], v[158:159], off
	v_lshl_add_u64 v[156:157], s[66:67], 0, v[156:157]
	v_lshl_add_u64 v[156:157], v[156:157], 0, v[154:155]
	s_movk_i32 s4, 0x3fef
	v_cmp_lt_i32_e32 vcc, s4, v152
	s_waitcnt vmcnt(0)
	v_pk_fma_f32 v[142:143], v[142:143], v[126:127], v[166:167]
	v_pk_fma_f32 v[140:141], v[140:141], v[124:125], v[164:165]
	global_store_dwordx4 v[156:157], v[140:143], off
	global_load_dwordx4 v[140:143], v[158:159], off offset:64
	s_waitcnt vmcnt(0)
	v_pk_fma_f32 v[138:139], v[138:139], v[118:119], v[142:143]
	v_pk_fma_f32 v[136:137], v[136:137], v[116:117], v[140:141]
	global_store_dwordx4 v[156:157], v[136:139], off offset:64
	global_load_dwordx4 v[136:139], v[158:159], off offset:512
	s_waitcnt vmcnt(0)
	v_pk_fma_f32 v[134:135], v[134:135], v[110:111], v[138:139]
	v_pk_fma_f32 v[132:133], v[132:133], v[108:109], v[136:137]
	global_store_dwordx4 v[156:157], v[132:135], off offset:512
	global_load_dwordx4 v[134:137], v[158:159], off offset:576
	s_waitcnt vmcnt(0)
	v_pk_fma_f32 v[130:131], v[130:131], v[106:107], v[136:137]
	v_or_b32_e32 v132, 16, v152
	v_pk_fma_f32 v[128:129], v[128:129], v[104:105], v[134:135]
	global_store_dwordx4 v[156:157], v[128:131], off offset:576
	s_and_saveexec_b64 s[12:13], vcc
	s_xor_b64 s[12:13], exec, s[12:13]
	v_add_u32_e32 v186, 0xffffc010, v152
	v_lshlrev_b64 v[128:129], 13, v[186:187]
	v_mov_b32_e32 v133, v187
	v_lshl_add_u64 v[130:131], s[10:11], 0, v[128:129]
	v_lshlrev_b64 v[128:129], 13, v[132:133]
	s_andn2_saveexec_b64 s[12:13], s[12:13]
	v_ashrrev_i32_e32 v133, 31, v132
	v_lshlrev_b64 v[128:129], 13, v[132:133]
	v_lshl_add_u64 v[130:131], s[66:67], 0, v[128:129]
	s_or_b64 exec, exec, s[12:13]
	v_lshl_add_u64 v[134:135], v[130:131], 0, v[154:155]
	global_load_dwordx4 v[130:133], v[134:135], off
	v_lshl_add_u64 v[128:129], s[66:67], 0, v[128:129]
	v_lshl_add_u64 v[128:129], v[128:129], 0, v[154:155]
	s_movk_i32 s4, 0x3fdf
	v_cmp_lt_i32_e32 vcc, s4, v152
	s_waitcnt vmcnt(0)
	v_pk_fma_f32 v[122:123], v[122:123], v[126:127], v[132:133]
	v_pk_fma_f32 v[120:121], v[120:121], v[124:125], v[130:131]
	global_store_dwordx4 v[128:129], v[120:123], off
	global_load_dwordx4 v[120:123], v[134:135], off offset:64
	s_waitcnt vmcnt(0)
	v_pk_fma_f32 v[114:115], v[114:115], v[118:119], v[122:123]
	v_pk_fma_f32 v[112:113], v[112:113], v[116:117], v[120:121]
	global_store_dwordx4 v[128:129], v[112:115], off offset:64
	global_load_dwordx4 v[112:115], v[134:135], off offset:512
	s_waitcnt vmcnt(0)
	v_pk_fma_f32 v[102:103], v[102:103], v[110:111], v[114:115]
	v_pk_fma_f32 v[100:101], v[100:101], v[108:109], v[112:113]
	global_store_dwordx4 v[128:129], v[100:103], off offset:512
	global_load_dwordx4 v[112:115], v[134:135], off offset:576
	s_waitcnt vmcnt(0)
	v_pk_fma_f32 v[98:99], v[98:99], v[106:107], v[114:115]
	v_or_b32_e32 v100, 32, v152
	v_pk_fma_f32 v[96:97], v[96:97], v[104:105], v[112:113]
	global_store_dwordx4 v[128:129], v[96:99], off offset:576
	s_and_saveexec_b64 s[12:13], vcc
	s_xor_b64 s[12:13], exec, s[12:13]
	v_add_u32_e32 v186, 0xffffc020, v152
	v_lshlrev_b64 v[96:97], 13, v[186:187]
	v_mov_b32_e32 v101, v187
	v_lshl_add_u64 v[98:99], s[10:11], 0, v[96:97]
	v_lshlrev_b64 v[96:97], 13, v[100:101]
	s_andn2_saveexec_b64 s[12:13], s[12:13]
	v_ashrrev_i32_e32 v101, 31, v100
	v_lshlrev_b64 v[96:97], 13, v[100:101]
	v_lshl_add_u64 v[98:99], s[66:67], 0, v[96:97]
	s_or_b64 exec, exec, s[12:13]
	v_lshl_add_u64 v[102:103], v[98:99], 0, v[154:155]
	global_load_dwordx4 v[98:101], v[102:103], off
	v_lshl_add_u64 v[96:97], s[66:67], 0, v[96:97]
	v_lshl_add_u64 v[96:97], v[96:97], 0, v[154:155]
	s_movk_i32 s4, 0x3fcf
	v_cmp_lt_i32_e32 vcc, s4, v152
	s_waitcnt vmcnt(0)
	v_pk_fma_f32 v[94:95], v[94:95], v[126:127], v[100:101]
	v_pk_fma_f32 v[92:93], v[92:93], v[124:125], v[98:99]
	global_store_dwordx4 v[96:97], v[92:95], off
	global_load_dwordx4 v[92:95], v[102:103], off offset:64
	s_waitcnt vmcnt(0)
	v_pk_fma_f32 v[90:91], v[90:91], v[118:119], v[94:95]
	v_pk_fma_f32 v[88:89], v[88:89], v[116:117], v[92:93]
	global_store_dwordx4 v[96:97], v[88:91], off offset:64
	global_load_dwordx4 v[88:91], v[102:103], off offset:512
	s_waitcnt vmcnt(0)
	v_pk_fma_f32 v[86:87], v[86:87], v[110:111], v[90:91]
	v_pk_fma_f32 v[84:85], v[84:85], v[108:109], v[88:89]
	global_store_dwordx4 v[96:97], v[84:87], off offset:512
	global_load_dwordx4 v[86:89], v[102:103], off offset:576
	s_waitcnt vmcnt(0)
	v_pk_fma_f32 v[82:83], v[82:83], v[106:107], v[88:89]
	v_or_b32_e32 v84, 48, v152
	v_pk_fma_f32 v[80:81], v[80:81], v[104:105], v[86:87]
	global_store_dwordx4 v[96:97], v[80:83], off offset:576
	s_and_saveexec_b64 s[12:13], vcc
	s_xor_b64 s[12:13], exec, s[12:13]
	v_add_u32_e32 v186, 0xffffc030, v152
	v_lshlrev_b64 v[80:81], 13, v[186:187]
	v_mov_b32_e32 v85, v187
	v_lshl_add_u64 v[82:83], s[10:11], 0, v[80:81]
	v_lshlrev_b64 v[80:81], 13, v[84:85]
	s_andn2_saveexec_b64 s[12:13], s[12:13]
	v_ashrrev_i32_e32 v85, 31, v84
	v_lshlrev_b64 v[80:81], 13, v[84:85]
	v_lshl_add_u64 v[82:83], s[66:67], 0, v[80:81]
	s_or_b64 exec, exec, s[12:13]
	v_lshl_add_u64 v[86:87], v[82:83], 0, v[154:155]
	global_load_dwordx4 v[82:85], v[86:87], off
	v_lshl_add_u64 v[80:81], s[66:67], 0, v[80:81]
	v_lshl_add_u64 v[80:81], v[80:81], 0, v[154:155]
	s_movk_i32 s4, 0x3f7f
	v_cmp_lt_i32_e32 vcc, s4, v152
	s_waitcnt vmcnt(0)
	v_pk_fma_f32 v[78:79], v[78:79], v[126:127], v[84:85]
	v_pk_fma_f32 v[76:77], v[76:77], v[124:125], v[82:83]
	global_store_dwordx4 v[80:81], v[76:79], off
	global_load_dwordx4 v[76:79], v[86:87], off offset:64
	s_waitcnt vmcnt(0)
	v_pk_fma_f32 v[74:75], v[74:75], v[118:119], v[78:79]
	v_pk_fma_f32 v[72:73], v[72:73], v[116:117], v[76:77]
	global_store_dwordx4 v[80:81], v[72:75], off offset:64
	global_load_dwordx4 v[72:75], v[86:87], off offset:512
	s_waitcnt vmcnt(0)
	v_pk_fma_f32 v[70:71], v[70:71], v[110:111], v[74:75]
	v_pk_fma_f32 v[68:69], v[68:69], v[108:109], v[72:73]
	global_store_dwordx4 v[80:81], v[68:71], off offset:512
	global_load_dwordx4 v[70:73], v[86:87], off offset:576
	s_waitcnt vmcnt(0)
	v_pk_fma_f32 v[66:67], v[66:67], v[106:107], v[72:73]
	v_add_u32_e32 v68, 0x80, v152
	v_pk_fma_f32 v[64:65], v[64:65], v[104:105], v[70:71]
	global_store_dwordx4 v[80:81], v[64:67], off offset:576
	s_and_saveexec_b64 s[12:13], vcc
	s_xor_b64 s[12:13], exec, s[12:13]
	v_add_u32_e32 v186, 0xffffc080, v152
	v_lshlrev_b64 v[64:65], 13, v[186:187]
	v_mov_b32_e32 v69, v187
	v_lshl_add_u64 v[66:67], s[10:11], 0, v[64:65]
	v_lshlrev_b64 v[64:65], 13, v[68:69]
	s_andn2_saveexec_b64 s[12:13], s[12:13]
	v_ashrrev_i32_e32 v69, 31, v68
	v_lshlrev_b64 v[64:65], 13, v[68:69]
	v_lshl_add_u64 v[66:67], s[66:67], 0, v[64:65]
	s_or_b64 exec, exec, s[12:13]
	v_lshl_add_u64 v[70:71], v[66:67], 0, v[154:155]
	global_load_dwordx4 v[66:69], v[70:71], off
	v_lshl_add_u64 v[64:65], s[66:67], 0, v[64:65]
	v_lshl_add_u64 v[64:65], v[64:65], 0, v[154:155]
	s_movk_i32 s4, 0x3f6f
	v_cmp_lt_i32_e32 vcc, s4, v152
	s_waitcnt vmcnt(0)
	v_pk_fma_f32 v[62:63], v[62:63], v[126:127], v[68:69]
	v_pk_fma_f32 v[60:61], v[60:61], v[124:125], v[66:67]
	global_store_dwordx4 v[64:65], v[60:63], off
	global_load_dwordx4 v[60:63], v[70:71], off offset:64
	s_waitcnt vmcnt(0)
	v_pk_fma_f32 v[58:59], v[58:59], v[118:119], v[62:63]
	v_pk_fma_f32 v[56:57], v[56:57], v[116:117], v[60:61]
	global_store_dwordx4 v[64:65], v[56:59], off offset:64
	global_load_dwordx4 v[56:59], v[70:71], off offset:512
	s_waitcnt vmcnt(0)
	v_pk_fma_f32 v[54:55], v[54:55], v[110:111], v[58:59]
	v_pk_fma_f32 v[52:53], v[52:53], v[108:109], v[56:57]
	global_store_dwordx4 v[64:65], v[52:55], off offset:512
	global_load_dwordx4 v[54:57], v[70:71], off offset:576
	s_waitcnt vmcnt(0)
	v_pk_fma_f32 v[50:51], v[50:51], v[106:107], v[56:57]
	v_add_u32_e32 v52, 0x90, v152
	v_pk_fma_f32 v[48:49], v[48:49], v[104:105], v[54:55]
	global_store_dwordx4 v[64:65], v[48:51], off offset:576
	s_and_saveexec_b64 s[12:13], vcc
	s_xor_b64 s[12:13], exec, s[12:13]
	v_add_u32_e32 v186, 0xffffc090, v152
	v_lshlrev_b64 v[48:49], 13, v[186:187]
	v_mov_b32_e32 v53, v187
	v_lshl_add_u64 v[50:51], s[10:11], 0, v[48:49]
	v_lshlrev_b64 v[48:49], 13, v[52:53]
	s_andn2_saveexec_b64 s[12:13], s[12:13]
	v_ashrrev_i32_e32 v53, 31, v52
	v_lshlrev_b64 v[48:49], 13, v[52:53]
	v_lshl_add_u64 v[50:51], s[66:67], 0, v[48:49]
	s_or_b64 exec, exec, s[12:13]
	v_lshl_add_u64 v[54:55], v[50:51], 0, v[154:155]
	global_load_dwordx4 v[50:53], v[54:55], off
	v_lshl_add_u64 v[48:49], s[66:67], 0, v[48:49]
	v_lshl_add_u64 v[48:49], v[48:49], 0, v[154:155]
	s_movk_i32 s4, 0x3f5f
	v_cmp_lt_i32_e32 vcc, s4, v152
	s_waitcnt vmcnt(0)
	v_pk_fma_f32 v[46:47], v[46:47], v[126:127], v[52:53]
	v_pk_fma_f32 v[44:45], v[44:45], v[124:125], v[50:51]
	global_store_dwordx4 v[48:49], v[44:47], off
	global_load_dwordx4 v[44:47], v[54:55], off offset:64
	s_waitcnt vmcnt(0)
	v_pk_fma_f32 v[42:43], v[42:43], v[118:119], v[46:47]
	v_pk_fma_f32 v[40:41], v[40:41], v[116:117], v[44:45]
	global_store_dwordx4 v[48:49], v[40:43], off offset:64
	global_load_dwordx4 v[40:43], v[54:55], off offset:512
	s_waitcnt vmcnt(0)
	v_pk_fma_f32 v[38:39], v[38:39], v[110:111], v[42:43]
	v_pk_fma_f32 v[36:37], v[36:37], v[108:109], v[40:41]
	global_store_dwordx4 v[48:49], v[36:39], off offset:512
	global_load_dwordx4 v[38:41], v[54:55], off offset:576
	s_waitcnt vmcnt(0)
	v_pk_fma_f32 v[34:35], v[34:35], v[106:107], v[40:41]
	v_add_u32_e32 v36, 0xa0, v152
	v_pk_fma_f32 v[32:33], v[32:33], v[104:105], v[38:39]
	global_store_dwordx4 v[48:49], v[32:35], off offset:576
	s_and_saveexec_b64 s[12:13], vcc
	s_xor_b64 s[12:13], exec, s[12:13]
	v_add_u32_e32 v186, 0xffffc0a0, v152
	v_lshlrev_b64 v[32:33], 13, v[186:187]
	v_mov_b32_e32 v37, v187
	v_lshl_add_u64 v[34:35], s[10:11], 0, v[32:33]
	v_lshlrev_b64 v[32:33], 13, v[36:37]
	s_andn2_saveexec_b64 s[12:13], s[12:13]
	v_ashrrev_i32_e32 v37, 31, v36
	v_lshlrev_b64 v[32:33], 13, v[36:37]
	v_lshl_add_u64 v[34:35], s[66:67], 0, v[32:33]
	s_or_b64 exec, exec, s[12:13]
	v_lshl_add_u64 v[38:39], v[34:35], 0, v[154:155]
	global_load_dwordx4 v[34:37], v[38:39], off
	v_lshl_add_u64 v[32:33], s[66:67], 0, v[32:33]
	v_lshl_add_u64 v[32:33], v[32:33], 0, v[154:155]
	s_movk_i32 s4, 0x3f4f
	v_cmp_lt_i32_e32 vcc, s4, v152
	s_waitcnt vmcnt(0)
	v_pk_fma_f32 v[30:31], v[30:31], v[126:127], v[36:37]
	v_pk_fma_f32 v[28:29], v[28:29], v[124:125], v[34:35]
	global_store_dwordx4 v[32:33], v[28:31], off
	global_load_dwordx4 v[28:31], v[38:39], off offset:64
	s_waitcnt vmcnt(0)
	v_pk_fma_f32 v[26:27], v[26:27], v[118:119], v[30:31]
	v_pk_fma_f32 v[24:25], v[24:25], v[116:117], v[28:29]
	global_store_dwordx4 v[32:33], v[24:27], off offset:64
	global_load_dwordx4 v[24:27], v[38:39], off offset:512
	s_waitcnt vmcnt(0)
	v_pk_fma_f32 v[22:23], v[22:23], v[110:111], v[26:27]
	v_pk_fma_f32 v[20:21], v[20:21], v[108:109], v[24:25]
	global_store_dwordx4 v[32:33], v[20:23], off offset:512
	global_load_dwordx4 v[22:25], v[38:39], off offset:576
	s_waitcnt vmcnt(0)
	v_pk_fma_f32 v[18:19], v[18:19], v[106:107], v[24:25]
	v_add_u32_e32 v20, 0xb0, v152
	v_pk_fma_f32 v[16:17], v[16:17], v[104:105], v[22:23]
	global_store_dwordx4 v[32:33], v[16:19], off offset:576
	s_and_saveexec_b64 s[12:13], vcc
	s_xor_b64 s[12:13], exec, s[12:13]
	v_add_u32_e32 v186, 0xffffc0b0, v152
	v_lshlrev_b64 v[16:17], 13, v[186:187]
	v_mov_b32_e32 v21, v187
	v_lshl_add_u64 v[16:17], s[10:11], 0, v[16:17]
	v_lshlrev_b64 v[18:19], 13, v[20:21]
	s_andn2_saveexec_b64 s[12:13], s[12:13]
	s_cbranch_execz .LBB0_881
	v_ashrrev_i32_e32 v21, 31, v20
	v_lshlrev_b64 v[18:19], 13, v[20:21]
	v_lshl_add_u64 v[16:17], s[66:67], 0, v[18:19]
	s_branch .LBB0_881

.LBB0_940:
	s_add_u32 s24, s2, vcc_lo
	s_addc_u32 s25, s3, vcc_hi
	s_add_u32 s24, s24, 0x100
	s_addc_u32 s25, s25, 0
	s_add_u32 s61, s19, vcc_lo
	s_addc_u32 s62, s4, vcc_hi
	s_add_i32 s63, 0, 0x10000
	v_add_u32_e32 v152, s63, v138
	ds_read_b128 v[140:143], v152
	ds_read_b128 v[144:147], v152 offset:1024
	ds_read_b128 v[148:151], v152 offset:2048
	ds_read_b128 v[152:155], v152 offset:3072
	s_cmpk_eq_i32 vcc_lo, 0x3f00
	s_cselect_b32 s27, s39, s25
	s_cselect_b32 s26, s58, s24
	s_cselect_b32 s25, s29, s62
	s_cselect_b32 s24, s59, s61
	v_lshl_add_u64 v[182:183], v[134:135], 0, vcc
	s_add_i32 m0, s23, 0xc000
	ds_read_b128 v[156:159], v139
	ds_read_b128 v[162:165], v139 offset:1024
	ds_read_b128 v[166:169], v139 offset:2048
	ds_read_b128 v[170:173], v139 offset:3072
	ds_read_b128 v[174:177], v139 offset:4096
	ds_read_b128 v[178:181], v139 offset:5120
	ds_read_b128 v[196:199], v139 offset:6144
	ds_read_b128 v[200:203], v139 offset:7168
	global_load_lds_dwordx4 v[182:183], off
	v_lshl_add_u64 v[182:183], v[136:137], 0, vcc
	s_add_i32 m0, s23, 0xe000
	s_nop 0
	global_load_lds_dwordx4 v[182:183], off
	v_add_u32_e32 v216, 0x14000, v138
	ds_read_b128 v[204:207], v216
	ds_read_b128 v[208:211], v216 offset:1024
	ds_read_b128 v[212:215], v216 offset:2048
	ds_read_b128 v[216:219], v216 offset:3072
	s_waitcnt vmcnt(8)
	s_waitcnt lgkmcnt(0)
	s_barrier
	s_setprio 1
	v_mfma_f32_16x16x32_bf16 v[124:127], v[140:143], v[156:159], v[124:127]
	v_mfma_f32_16x16x32_bf16 v[120:123], v[148:151], v[156:159], v[120:123]
	v_mfma_f32_16x16x32_bf16 v[108:111], v[140:143], v[166:169], v[108:111]
	v_mfma_f32_16x16x32_bf16 v[104:107], v[148:151], v[166:169], v[104:107]
	v_mfma_f32_16x16x32_bf16 v[92:95], v[140:143], v[174:177], v[92:95]
	v_mfma_f32_16x16x32_bf16 v[88:91], v[148:151], v[174:177], v[88:91]
	v_mfma_f32_16x16x32_bf16 v[76:79], v[140:143], v[196:199], v[76:79]
	v_mfma_f32_16x16x32_bf16 v[72:75], v[148:151], v[196:199], v[72:75]
	v_mfma_f32_16x16x32_bf16 v[124:127], v[144:147], v[162:165], v[124:127]
	v_mfma_f32_16x16x32_bf16 v[120:123], v[152:155], v[162:165], v[120:123]
	v_mfma_f32_16x16x32_bf16 v[108:111], v[144:147], v[170:173], v[108:111]
	v_mfma_f32_16x16x32_bf16 v[104:107], v[152:155], v[170:173], v[104:107]
	v_mfma_f32_16x16x32_bf16 v[92:95], v[144:147], v[178:181], v[92:95]
	v_mfma_f32_16x16x32_bf16 v[88:91], v[152:155], v[178:181], v[88:91]
	v_mfma_f32_16x16x32_bf16 v[76:79], v[144:147], v[200:203], v[76:79]
	v_mfma_f32_16x16x32_bf16 v[72:75], v[152:155], v[200:203], v[72:75]
	v_mfma_f32_16x16x32_bf16 v[116:119], v[204:207], v[156:159], v[116:119]
	v_mfma_f32_16x16x32_bf16 v[112:115], v[212:215], v[156:159], v[112:115]
	v_mfma_f32_16x16x32_bf16 v[100:103], v[204:207], v[166:169], v[100:103]
	v_mfma_f32_16x16x32_bf16 v[96:99], v[212:215], v[166:169], v[96:99]
	v_mfma_f32_16x16x32_bf16 v[84:87], v[204:207], v[174:177], v[84:87]
	v_mfma_f32_16x16x32_bf16 v[80:83], v[212:215], v[174:177], v[80:83]
	v_mfma_f32_16x16x32_bf16 v[68:71], v[204:207], v[196:199], v[68:71]
	v_mfma_f32_16x16x32_bf16 v[64:67], v[212:215], v[196:199], v[64:67]
	v_mfma_f32_16x16x32_bf16 v[116:119], v[208:211], v[162:165], v[116:119]
	v_mfma_f32_16x16x32_bf16 v[112:115], v[216:219], v[162:165], v[112:115]
	v_mfma_f32_16x16x32_bf16 v[100:103], v[208:211], v[170:173], v[100:103]
	v_mfma_f32_16x16x32_bf16 v[96:99], v[216:219], v[170:173], v[96:99]
	v_mfma_f32_16x16x32_bf16 v[84:87], v[208:211], v[178:181], v[84:87]
	v_mfma_f32_16x16x32_bf16 v[80:83], v[216:219], v[178:181], v[80:83]
	v_mfma_f32_16x16x32_bf16 v[68:71], v[208:211], v[200:203], v[68:71]
	v_mfma_f32_16x16x32_bf16 v[64:67], v[216:219], v[200:203], v[64:67]
	s_setprio 0
	s_barrier
	s_add_i32 s61, 0, 0x14000
	s_add_i32 s62, s63, s17
	v_lshl_add_u64 v[182:183], s[24:25], 0, v[186:187]
	s_mov_b32 m0, s62
	global_load_lds_dwordx4 v186, s[24:25]
	v_lshl_add_u64 v[220:221], s[24:25], 0, v[128:129]
	s_add_i32 m0, s62, 0x2000
	s_nop 0
	global_load_lds_dwordx4 v128, s[24:25]
	s_mov_b32 m0, s23
	v_lshl_add_u64 v[222:223], s[26:27], 0, v[186:187]
	ds_read_b128 v[156:159], v139 offset:16384
	ds_read_b128 v[162:165], v139 offset:17408
	ds_read_b128 v[166:169], v139 offset:18432
	ds_read_b128 v[170:173], v139 offset:19456
	ds_read_b128 v[174:177], v139 offset:20480
	ds_read_b128 v[178:181], v139 offset:21504
	ds_read_b128 v[196:199], v139 offset:22528
	ds_read_b128 v[200:203], v139 offset:23552
	global_load_lds_dwordx4 v186, s[26:27]
	v_lshl_add_u64 v[224:225], s[26:27], 0, v[128:129]
	s_mov_b32 m0, s30
	s_nop 0
	global_load_lds_dwordx4 v128, s[26:27]
	s_waitcnt vmcnt(6)
	s_waitcnt lgkmcnt(0)
	s_barrier
	s_setprio 1
	v_mfma_f32_16x16x32_bf16 v[60:63], v[140:143], v[156:159], v[60:63]
	v_mfma_f32_16x16x32_bf16 v[56:59], v[148:151], v[156:159], v[56:59]
	v_mfma_f32_16x16x32_bf16 v[44:47], v[140:143], v[166:169], v[44:47]
	v_mfma_f32_16x16x32_bf16 v[40:43], v[148:151], v[166:169], v[40:43]
	v_mfma_f32_16x16x32_bf16 v[32:35], v[140:143], v[174:177], v[32:35]
	v_mfma_f32_16x16x32_bf16 v[24:27], v[148:151], v[174:177], v[24:27]
	v_mfma_f32_16x16x32_bf16 v[16:19], v[140:143], v[196:199], v[16:19]
	v_mfma_f32_16x16x32_bf16 v[8:11], v[148:151], v[196:199], v[8:11]
	v_mfma_f32_16x16x32_bf16 v[60:63], v[144:147], v[162:165], v[60:63]
	v_mfma_f32_16x16x32_bf16 v[56:59], v[152:155], v[162:165], v[56:59]
	v_mfma_f32_16x16x32_bf16 v[44:47], v[144:147], v[170:173], v[44:47]
	v_mfma_f32_16x16x32_bf16 v[40:43], v[152:155], v[170:173], v[40:43]
	v_mfma_f32_16x16x32_bf16 v[32:35], v[144:147], v[178:181], v[32:35]
	v_mfma_f32_16x16x32_bf16 v[24:27], v[152:155], v[178:181], v[24:27]
	v_mfma_f32_16x16x32_bf16 v[16:19], v[144:147], v[200:203], v[16:19]
	v_mfma_f32_16x16x32_bf16 v[8:11], v[152:155], v[200:203], v[8:11]
	v_mfma_f32_16x16x32_bf16 v[52:55], v[204:207], v[156:159], v[52:55]
	v_mfma_f32_16x16x32_bf16 v[48:51], v[212:215], v[156:159], v[48:51]
	v_mfma_f32_16x16x32_bf16 v[36:39], v[204:207], v[166:169], v[36:39]
	v_mfma_f32_16x16x32_bf16 v[28:31], v[212:215], v[166:169], v[28:31]
	v_mfma_f32_16x16x32_bf16 v[20:23], v[204:207], v[174:177], v[20:23]
	v_mfma_f32_16x16x32_bf16 v[12:15], v[212:215], v[174:177], v[12:15]
	v_mfma_f32_16x16x32_bf16 v[4:7], v[204:207], v[196:199], v[4:7]
	v_mfma_f32_16x16x32_bf16 v[0:3], v[212:215], v[196:199], v[0:3]
	v_mfma_f32_16x16x32_bf16 v[52:55], v[208:211], v[162:165], v[52:55]
	v_mfma_f32_16x16x32_bf16 v[48:51], v[216:219], v[162:165], v[48:51]
	v_mfma_f32_16x16x32_bf16 v[36:39], v[208:211], v[170:173], v[36:39]
	v_mfma_f32_16x16x32_bf16 v[28:31], v[216:219], v[170:173], v[28:31]
	v_mfma_f32_16x16x32_bf16 v[20:23], v[208:211], v[178:181], v[20:23]
	v_mfma_f32_16x16x32_bf16 v[12:15], v[216:219], v[178:181], v[12:15]
	v_mfma_f32_16x16x32_bf16 v[4:7], v[208:211], v[200:203], v[4:7]
	v_mfma_f32_16x16x32_bf16 v[0:3], v[216:219], v[200:203], v[0:3]
	s_setprio 0
	s_barrier
	s_add_u32 s62, s24, 0x200000
	s_addc_u32 s63, s25, 0
	s_add_i32 s61, s61, s17
	s_mov_b32 m0, s61
	s_nop 0
	global_load_lds_dwordx4 v186, s[62:63]
	s_add_i32 m0, s61, 0x2000
	s_nop 0
	global_load_lds_dwordx4 v128, s[62:63]
	s_add_i32 s61, 0, 0x18000
	v_add_u32_e32 v152, s61, v138
	ds_read_b128 v[140:143], v152
	ds_read_b128 v[144:147], v152 offset:1024
	ds_read_b128 v[148:151], v152 offset:2048
	ds_read_b128 v[152:155], v152 offset:3072
	s_add_u32 s26, s26, 0x200000
	s_addc_u32 s27, s27, 0
	s_mov_b32 m0, s31
	ds_read_b128 v[156:159], v139 offset:32768
	ds_read_b128 v[162:165], v139 offset:33792
	ds_read_b128 v[166:169], v139 offset:34816
	ds_read_b128 v[170:173], v139 offset:35840
	ds_read_b128 v[174:177], v139 offset:36864
	ds_read_b128 v[178:181], v139 offset:37888
	ds_read_b128 v[196:199], v139 offset:38912
	ds_read_b128 v[200:203], v139 offset:39936
	v_add_u32_e32 v216, 0x1c000, v138
	ds_read_b128 v[204:207], v216
	ds_read_b128 v[208:211], v216 offset:1024
	ds_read_b128 v[212:215], v216 offset:2048
	ds_read_b128 v[216:219], v216 offset:3072
	global_load_lds_dwordx4 v186, s[26:27]
	s_mov_b32 m0, s52
	s_nop 0
	global_load_lds_dwordx4 v128, s[26:27]
	s_waitcnt vmcnt(8)
	s_waitcnt lgkmcnt(0)
	s_barrier
	s_setprio 1
	v_mfma_f32_16x16x32_bf16 v[124:127], v[140:143], v[156:159], v[124:127]
	v_mfma_f32_16x16x32_bf16 v[120:123], v[148:151], v[156:159], v[120:123]
	v_mfma_f32_16x16x32_bf16 v[108:111], v[140:143], v[166:169], v[108:111]
	v_mfma_f32_16x16x32_bf16 v[104:107], v[148:151], v[166:169], v[104:107]
	v_mfma_f32_16x16x32_bf16 v[92:95], v[140:143], v[174:177], v[92:95]
	v_mfma_f32_16x16x32_bf16 v[88:91], v[148:151], v[174:177], v[88:91]
	v_mfma_f32_16x16x32_bf16 v[76:79], v[140:143], v[196:199], v[76:79]
	v_mfma_f32_16x16x32_bf16 v[72:75], v[148:151], v[196:199], v[72:75]
	v_mfma_f32_16x16x32_bf16 v[124:127], v[144:147], v[162:165], v[124:127]
	v_mfma_f32_16x16x32_bf16 v[120:123], v[152:155], v[162:165], v[120:123]
	v_mfma_f32_16x16x32_bf16 v[108:111], v[144:147], v[170:173], v[108:111]
	v_mfma_f32_16x16x32_bf16 v[104:107], v[152:155], v[170:173], v[104:107]
	v_mfma_f32_16x16x32_bf16 v[92:95], v[144:147], v[178:181], v[92:95]
	v_mfma_f32_16x16x32_bf16 v[88:91], v[152:155], v[178:181], v[88:91]
	v_mfma_f32_16x16x32_bf16 v[76:79], v[144:147], v[200:203], v[76:79]
	v_mfma_f32_16x16x32_bf16 v[72:75], v[152:155], v[200:203], v[72:75]
	v_mfma_f32_16x16x32_bf16 v[116:119], v[204:207], v[156:159], v[116:119]
	v_mfma_f32_16x16x32_bf16 v[112:115], v[212:215], v[156:159], v[112:115]
	v_mfma_f32_16x16x32_bf16 v[100:103], v[204:207], v[166:169], v[100:103]
	v_mfma_f32_16x16x32_bf16 v[96:99], v[212:215], v[166:169], v[96:99]
	v_mfma_f32_16x16x32_bf16 v[84:87], v[204:207], v[174:177], v[84:87]
	v_mfma_f32_16x16x32_bf16 v[80:83], v[212:215], v[174:177], v[80:83]
	v_mfma_f32_16x16x32_bf16 v[68:71], v[204:207], v[196:199], v[68:71]
	v_mfma_f32_16x16x32_bf16 v[64:67], v[212:215], v[196:199], v[64:67]
	v_mfma_f32_16x16x32_bf16 v[116:119], v[208:211], v[162:165], v[116:119]
	v_mfma_f32_16x16x32_bf16 v[112:115], v[216:219], v[162:165], v[112:115]
	v_mfma_f32_16x16x32_bf16 v[100:103], v[208:211], v[170:173], v[100:103]
	v_mfma_f32_16x16x32_bf16 v[96:99], v[216:219], v[170:173], v[96:99]
	v_mfma_f32_16x16x32_bf16 v[84:87], v[208:211], v[178:181], v[84:87]
	v_mfma_f32_16x16x32_bf16 v[80:83], v[216:219], v[178:181], v[80:83]
	v_mfma_f32_16x16x32_bf16 v[68:71], v[208:211], v[200:203], v[68:71]
	v_mfma_f32_16x16x32_bf16 v[64:67], v[216:219], v[200:203], v[64:67]
	s_setprio 0
	s_barrier
	s_add_i32 s26, 0, 0x1c000
	s_add_i32 s27, s61, s17
	v_lshl_add_u64 v[182:183], v[182:183], 0, s[0:1]
	s_mov_b32 m0, s27
	global_load_lds_dwordx4 v[182:183], off
	v_lshl_add_u64 v[182:183], v[220:221], 0, s[0:1]
	s_add_i32 m0, s27, 0x2000
	s_nop 0
	global_load_lds_dwordx4 v[182:183], off
	s_mov_b32 m0, s53
	v_lshl_add_u64 v[182:183], v[222:223], 0, s[0:1]
	ds_read_b128 v[156:159], v139 offset:49152
	ds_read_b128 v[162:165], v139 offset:50176
	ds_read_b128 v[166:169], v139 offset:51200
	ds_read_b128 v[170:173], v139 offset:52224
	ds_read_b128 v[174:177], v139 offset:53248
	ds_read_b128 v[178:181], v139 offset:54272
	ds_read_b128 v[196:199], v139 offset:55296
	ds_read_b128 v[200:203], v139 offset:56320
	global_load_lds_dwordx4 v[182:183], off
	v_lshl_add_u64 v[182:183], v[224:225], 0, s[0:1]
	s_mov_b32 m0, s68
	s_nop 0
	global_load_lds_dwordx4 v[182:183], off
	s_add_u32 s24, s24, 0x200080
	s_addc_u32 s25, s25, 0
	s_add_i32 s26, s26, s17
	s_mov_b32 m0, s26
	s_nop 0
	global_load_lds_dwordx4 v186, s[24:25]
	s_add_i32 m0, s26, 0x2000
	s_nop 0
	global_load_lds_dwordx4 v128, s[24:25]
	s_waitcnt vmcnt(8)
	s_waitcnt lgkmcnt(0)
	s_barrier
	s_setprio 1
	v_mfma_f32_16x16x32_bf16 v[60:63], v[140:143], v[156:159], v[60:63]
	v_mfma_f32_16x16x32_bf16 v[56:59], v[148:151], v[156:159], v[56:59]
	v_mfma_f32_16x16x32_bf16 v[44:47], v[140:143], v[166:169], v[44:47]
	v_mfma_f32_16x16x32_bf16 v[40:43], v[148:151], v[166:169], v[40:43]
	v_mfma_f32_16x16x32_bf16 v[32:35], v[140:143], v[174:177], v[32:35]
	v_mfma_f32_16x16x32_bf16 v[24:27], v[148:151], v[174:177], v[24:27]
	v_mfma_f32_16x16x32_bf16 v[16:19], v[140:143], v[196:199], v[16:19]
	v_mfma_f32_16x16x32_bf16 v[8:11], v[148:151], v[196:199], v[8:11]
	v_mfma_f32_16x16x32_bf16 v[60:63], v[144:147], v[162:165], v[60:63]
	v_mfma_f32_16x16x32_bf16 v[56:59], v[152:155], v[162:165], v[56:59]
	v_mfma_f32_16x16x32_bf16 v[44:47], v[144:147], v[170:173], v[44:47]
	v_mfma_f32_16x16x32_bf16 v[40:43], v[152:155], v[170:173], v[40:43]
	v_mfma_f32_16x16x32_bf16 v[32:35], v[144:147], v[178:181], v[32:35]
	v_mfma_f32_16x16x32_bf16 v[24:27], v[152:155], v[178:181], v[24:27]
	v_mfma_f32_16x16x32_bf16 v[16:19], v[144:147], v[200:203], v[16:19]
	v_mfma_f32_16x16x32_bf16 v[8:11], v[152:155], v[200:203], v[8:11]
	v_mfma_f32_16x16x32_bf16 v[52:55], v[204:207], v[156:159], v[52:55]
	v_mfma_f32_16x16x32_bf16 v[48:51], v[212:215], v[156:159], v[48:51]
	v_mfma_f32_16x16x32_bf16 v[36:39], v[204:207], v[166:169], v[36:39]
	v_mfma_f32_16x16x32_bf16 v[28:31], v[212:215], v[166:169], v[28:31]
	v_mfma_f32_16x16x32_bf16 v[20:23], v[204:207], v[174:177], v[20:23]
	v_mfma_f32_16x16x32_bf16 v[12:15], v[212:215], v[174:177], v[12:15]
	v_mfma_f32_16x16x32_bf16 v[4:7], v[204:207], v[196:199], v[4:7]
	v_mfma_f32_16x16x32_bf16 v[0:3], v[212:215], v[196:199], v[0:3]
	v_mfma_f32_16x16x32_bf16 v[52:55], v[208:211], v[162:165], v[52:55]
	v_mfma_f32_16x16x32_bf16 v[48:51], v[216:219], v[162:165], v[48:51]
	v_mfma_f32_16x16x32_bf16 v[36:39], v[208:211], v[170:173], v[36:39]
	v_mfma_f32_16x16x32_bf16 v[28:31], v[216:219], v[170:173], v[28:31]
	v_mfma_f32_16x16x32_bf16 v[20:23], v[208:211], v[178:181], v[20:23]
	v_mfma_f32_16x16x32_bf16 v[12:15], v[216:219], v[178:181], v[12:15]
	v_mfma_f32_16x16x32_bf16 v[4:7], v[208:211], v[200:203], v[4:7]
	v_mfma_f32_16x16x32_bf16 v[0:3], v[216:219], v[200:203], v[0:3]
	s_setprio 0
	s_add_i32 s60, s60, 2
	s_add_u32 vcc_lo, vcc_lo, 0x100
	s_addc_u32 vcc_hi, vcc_hi, 0
	s_cmpk_gt_u32 s60, 0x7d
	s_barrier
	s_cbranch_scc0 .LBB0_940
	s_add_u32 s24, s19, 0xffffff00
	s_addc_u32 s25, s4, -1
	s_andn2_b64 vcc, exec, s[44:45]
	s_cbranch_vccnz .LBB0_931
	v_mov_b32_e32 v0, 0
	s_mov_b32 s18, s28
	s_mov_b32 s56, s38
	s_mov_b64 s[2:3], s[20:21]
	s_mov_b32 s69, s57
	v_mov_b32_e32 v1, v0
	v_mov_b32_e32 v2, v0
	v_mov_b32_e32 v3, v0
	v_mov_b32_e32 v4, v0
	v_mov_b32_e32 v5, v0
	v_mov_b32_e32 v6, v0
	v_mov_b32_e32 v7, v0
	v_mov_b32_e32 v12, v0
	v_mov_b32_e32 v13, v0
	v_mov_b32_e32 v14, v0
	v_mov_b32_e32 v15, v0
	v_mov_b32_e32 v20, v0
	v_mov_b32_e32 v21, v0
	v_mov_b32_e32 v22, v0
	v_mov_b32_e32 v23, v0
	v_mov_b32_e32 v28, v0
	v_mov_b32_e32 v29, v0
	v_mov_b32_e32 v30, v0
	v_mov_b32_e32 v31, v0
	v_mov_b32_e32 v36, v0
	v_mov_b32_e32 v37, v0
	v_mov_b32_e32 v38, v0
	v_mov_b32_e32 v39, v0
	v_mov_b32_e32 v48, v0
	v_mov_b32_e32 v49, v0
	v_mov_b32_e32 v50, v0
	v_mov_b32_e32 v51, v0
	v_mov_b32_e32 v52, v0
	v_mov_b32_e32 v53, v0
	v_mov_b32_e32 v54, v0
	v_mov_b32_e32 v55, v0
	v_mov_b32_e32 v8, v0
	v_mov_b32_e32 v9, v0
	v_mov_b32_e32 v10, v0
	v_mov_b32_e32 v11, v0
	v_mov_b32_e32 v16, v0
	v_mov_b32_e32 v17, v0
	v_mov_b32_e32 v18, v0
	v_mov_b32_e32 v19, v0
	v_mov_b32_e32 v24, v0
	v_mov_b32_e32 v25, v0
	v_mov_b32_e32 v26, v0
	v_mov_b32_e32 v27, v0
	v_mov_b32_e32 v32, v0
	v_mov_b32_e32 v33, v0
	v_mov_b32_e32 v34, v0
	v_mov_b32_e32 v35, v0
	v_mov_b32_e32 v40, v0
	v_mov_b32_e32 v41, v0
	v_mov_b32_e32 v42, v0
	v_mov_b32_e32 v43, v0
	v_mov_b32_e32 v44, v0
	v_mov_b32_e32 v45, v0
	v_mov_b32_e32 v46, v0
	v_mov_b32_e32 v47, v0
	v_mov_b32_e32 v56, v0
	v_mov_b32_e32 v57, v0
	v_mov_b32_e32 v58, v0
	v_mov_b32_e32 v59, v0
	v_mov_b32_e32 v60, v0
	v_mov_b32_e32 v61, v0
	v_mov_b32_e32 v62, v0
	v_mov_b32_e32 v63, v0
	v_mov_b32_e32 v64, v0
	v_mov_b32_e32 v65, v0
	v_mov_b32_e32 v66, v0
	v_mov_b32_e32 v67, v0
	v_mov_b32_e32 v68, v0
	v_mov_b32_e32 v69, v0
	v_mov_b32_e32 v70, v0
	v_mov_b32_e32 v71, v0
	v_mov_b32_e32 v80, v0
	v_mov_b32_e32 v81, v0
	v_mov_b32_e32 v82, v0
	v_mov_b32_e32 v83, v0
	v_mov_b32_e32 v84, v0
	v_mov_b32_e32 v85, v0
	v_mov_b32_e32 v86, v0
	v_mov_b32_e32 v87, v0
	v_mov_b32_e32 v96, v0
	v_mov_b32_e32 v97, v0
	v_mov_b32_e32 v98, v0
	v_mov_b32_e32 v99, v0
	v_mov_b32_e32 v100, v0
	v_mov_b32_e32 v101, v0
	v_mov_b32_e32 v102, v0
	v_mov_b32_e32 v103, v0
	v_mov_b32_e32 v112, v0
	v_mov_b32_e32 v113, v0
	v_mov_b32_e32 v114, v0
	v_mov_b32_e32 v115, v0
	v_mov_b32_e32 v116, v0
	v_mov_b32_e32 v117, v0
	v_mov_b32_e32 v118, v0
	v_mov_b32_e32 v119, v0
	v_mov_b32_e32 v72, v0
	v_mov_b32_e32 v73, v0
	v_mov_b32_e32 v74, v0
	v_mov_b32_e32 v75, v0
	v_mov_b32_e32 v76, v0
	v_mov_b32_e32 v77, v0
	v_mov_b32_e32 v78, v0
	v_mov_b32_e32 v79, v0
	v_mov_b32_e32 v88, v0
	v_mov_b32_e32 v89, v0
	v_mov_b32_e32 v90, v0
	v_mov_b32_e32 v91, v0
	v_mov_b32_e32 v92, v0
	v_mov_b32_e32 v93, v0
	v_mov_b32_e32 v94, v0
	v_mov_b32_e32 v95, v0
	v_mov_b32_e32 v104, v0
	v_mov_b32_e32 v105, v0
	v_mov_b32_e32 v106, v0
	v_mov_b32_e32 v107, v0
	v_mov_b32_e32 v108, v0
	v_mov_b32_e32 v109, v0
	v_mov_b32_e32 v110, v0
	v_mov_b32_e32 v111, v0
	v_mov_b32_e32 v120, v0
	v_mov_b32_e32 v121, v0
	v_mov_b32_e32 v122, v0
	v_mov_b32_e32 v123, v0
	v_mov_b32_e32 v124, v0
	v_mov_b32_e32 v125, v0
	v_mov_b32_e32 v126, v0
	v_mov_b32_e32 v127, v0
	s_andn2_b64 vcc, exec, s[42:43]
	s_cbranch_vccnz .LBB0_932
